# v46 + GEMM loops: m0 write/address calc swapped to fill the m0->LDS-DMA wait state (no s_nop), redundant lgkmcnt(8) before phase 1/5 opening barrier dropped
# speedup vs baseline: 1.0087x; 1.0034x over previous
.LBB0_127:
	s_add_u32 s22, s20, 0xfff80080
	s_addc_u32 s23, s21, -1
	s_add_i32 s50, 0, 0x10000
	s_cmp_eq_u32 s49, 4
	s_cselect_b32 s23, s81, s23
	s_cselect_b32 s22, s80, s22
	s_cselect_b32 s39, s19, s48
	s_cselect_b32 s38, s31, s47
	v_lshl_add_u64 v[178:179], s[20:21], 0, v[138:139]
	s_add_i32 m0, s27, 0xc000
	ds_read_b128 v[162:165], v144
	ds_read_b128 v[166:169], v144 offset:1024
	ds_read_b128 v[170:173], v144 offset:2048
	ds_read_b128 v[174:177], v144 offset:3072
	ds_read_b128 v[192:195], v144 offset:4096
	ds_read_b128 v[196:199], v144 offset:5120
	ds_read_b128 v[200:203], v144 offset:6144
	ds_read_b128 v[204:207], v144 offset:7168
	global_load_lds_dwordx4 v[178:179], off
	s_add_i32 m0, s27, 0xe000
	v_lshl_add_u64 v[178:179], s[20:21], 0, v[140:141]
	global_load_lds_dwordx4 v[178:179], off
	s_barrier
	s_waitcnt lgkmcnt(0)
	v_mfma_f32_16x16x32_bf16 v[126:129], v[146:149], v[162:165], v[126:129]
	v_mfma_f32_16x16x32_bf16 v[122:125], v[154:157], v[162:165], v[122:125]
	v_mfma_f32_16x16x32_bf16 v[118:121], v[146:149], v[170:173], v[118:121]
	v_mfma_f32_16x16x32_bf16 v[114:117], v[154:157], v[170:173], v[114:117]
	v_mfma_f32_16x16x32_bf16 v[102:105], v[146:149], v[192:195], v[102:105]
	v_mfma_f32_16x16x32_bf16 v[98:101], v[154:157], v[192:195], v[98:101]
	v_mfma_f32_16x16x32_bf16 v[86:89], v[146:149], v[200:203], v[86:89]
	v_mfma_f32_16x16x32_bf16 v[82:85], v[154:157], v[200:203], v[82:85]
	v_mfma_f32_16x16x32_bf16 v[126:129], v[150:153], v[166:169], v[126:129]
	v_mfma_f32_16x16x32_bf16 v[122:125], v[158:161], v[166:169], v[122:125]
	v_mfma_f32_16x16x32_bf16 v[118:121], v[150:153], v[174:177], v[118:121]
	v_mfma_f32_16x16x32_bf16 v[114:117], v[158:161], v[174:177], v[114:117]
	v_mfma_f32_16x16x32_bf16 v[102:105], v[150:153], v[196:199], v[102:105]
	v_mfma_f32_16x16x32_bf16 v[98:101], v[158:161], v[196:199], v[98:101]
	v_mfma_f32_16x16x32_bf16 v[86:89], v[150:153], v[204:207], v[86:89]
	v_mfma_f32_16x16x32_bf16 v[82:85], v[158:161], v[204:207], v[82:85]
	s_barrier
	s_add_i32 s52, 0, 0x14000
	s_add_i32 s50, s50, s26
	v_add_u32_e32 v145, s52, v142
	v_lshl_add_u64 v[178:179], s[38:39], 0, v[134:135]
	s_mov_b32 m0, s50
	ds_read_b128 v[208:211], v145
	ds_read_b128 v[224:227], v145 offset:1024
	ds_read_b128 v[228:231], v145 offset:2048
	ds_read_b128 v[232:235], v145 offset:3072
	global_load_lds_dwordx4 v[178:179], off
	s_add_i32 m0, s50, 0x2000
	v_lshl_add_u64 v[212:213], s[38:39], 0, v[130:131]
	global_load_lds_dwordx4 v[212:213], off
	s_mov_b32 m0, s27
	v_lshl_add_u64 v[236:237], s[22:23], 0, v[136:137]
	s_waitcnt lgkmcnt(0)
	s_barrier
	v_mfma_f32_16x16x32_bf16 v[110:113], v[208:211], v[162:165], v[110:113]
	v_mfma_f32_16x16x32_bf16 v[106:109], v[228:231], v[162:165], v[106:109]
	v_mfma_f32_16x16x32_bf16 v[94:97], v[208:211], v[170:173], v[94:97]
	v_mfma_f32_16x16x32_bf16 v[90:93], v[228:231], v[170:173], v[90:93]
	v_mfma_f32_16x16x32_bf16 v[78:81], v[208:211], v[192:195], v[78:81]
	v_mfma_f32_16x16x32_bf16 v[74:77], v[228:231], v[192:195], v[74:77]
	v_mfma_f32_16x16x32_bf16 v[70:73], v[208:211], v[200:203], v[70:73]
	v_mfma_f32_16x16x32_bf16 v[66:69], v[228:231], v[200:203], v[66:69]
	v_mfma_f32_16x16x32_bf16 v[110:113], v[224:227], v[166:169], v[110:113]
	v_mfma_f32_16x16x32_bf16 v[106:109], v[232:235], v[166:169], v[106:109]
	v_mfma_f32_16x16x32_bf16 v[94:97], v[224:227], v[174:177], v[94:97]
	v_mfma_f32_16x16x32_bf16 v[90:93], v[232:235], v[174:177], v[90:93]
	v_mfma_f32_16x16x32_bf16 v[78:81], v[224:227], v[196:199], v[78:81]
	v_mfma_f32_16x16x32_bf16 v[74:77], v[232:235], v[196:199], v[74:77]
	v_mfma_f32_16x16x32_bf16 v[70:73], v[224:227], v[204:207], v[70:73]
	v_mfma_f32_16x16x32_bf16 v[66:69], v[232:235], v[204:207], v[66:69]
	s_barrier
	ds_read_b128 v[162:165], v144 offset:16384
	ds_read_b128 v[166:169], v144 offset:17408
	ds_read_b128 v[170:173], v144 offset:18432
	ds_read_b128 v[174:177], v144 offset:19456
	ds_read_b128 v[192:195], v144 offset:20480
	ds_read_b128 v[196:199], v144 offset:21504
	ds_read_b128 v[200:203], v144 offset:22528
	ds_read_b128 v[204:207], v144 offset:23552
	global_load_lds_dwordx4 v[236:237], off
	s_mov_b32 m0, s28
	v_lshl_add_u64 v[238:239], s[22:23], 0, v[132:133]
	global_load_lds_dwordx4 v[238:239], off
	s_waitcnt vmcnt(10)
	s_barrier
	s_waitcnt lgkmcnt(0)
	v_mfma_f32_16x16x32_bf16 v[62:65], v[146:149], v[162:165], v[62:65]
	v_mfma_f32_16x16x32_bf16 v[58:61], v[154:157], v[162:165], v[58:61]
	v_mfma_f32_16x16x32_bf16 v[54:57], v[146:149], v[170:173], v[54:57]
	v_mfma_f32_16x16x32_bf16 v[50:53], v[154:157], v[170:173], v[50:53]
	v_mfma_f32_16x16x32_bf16 v[38:41], v[146:149], v[192:195], v[38:41]
	v_mfma_f32_16x16x32_bf16 v[34:37], v[154:157], v[192:195], v[34:37]
	v_mfma_f32_16x16x32_bf16 v[22:25], v[146:149], v[200:203], v[22:25]
	v_mfma_f32_16x16x32_bf16 v[18:21], v[154:157], v[200:203], v[18:21]
	v_mfma_f32_16x16x32_bf16 v[62:65], v[150:153], v[166:169], v[62:65]
	v_mfma_f32_16x16x32_bf16 v[58:61], v[158:161], v[166:169], v[58:61]
	v_mfma_f32_16x16x32_bf16 v[54:57], v[150:153], v[174:177], v[54:57]
	v_mfma_f32_16x16x32_bf16 v[50:53], v[158:161], v[174:177], v[50:53]
	v_mfma_f32_16x16x32_bf16 v[38:41], v[150:153], v[196:199], v[38:41]
	v_mfma_f32_16x16x32_bf16 v[34:37], v[158:161], v[196:199], v[34:37]
	v_mfma_f32_16x16x32_bf16 v[22:25], v[150:153], v[204:207], v[22:25]
	v_mfma_f32_16x16x32_bf16 v[18:21], v[158:161], v[204:207], v[18:21]
	s_barrier
	s_add_u32 s50, s38, 0x20000
	s_addc_u32 s51, s39, 0
	s_add_i32 s52, s52, s26
	s_mov_b32 m0, s52
	v_lshl_add_u64 v[146:147], s[50:51], 0, v[134:135]
	global_load_lds_dwordx4 v[146:147], off
	s_add_i32 m0, s52, 0x2000
	v_lshl_add_u64 v[146:147], s[50:51], 0, v[130:131]
	global_load_lds_dwordx4 v[146:147], off
	v_add_u32_e32 v145, 0x18000, v142
	ds_read_b128 v[146:149], v145
	ds_read_b128 v[150:153], v145 offset:1024
	ds_read_b128 v[154:157], v145 offset:2048
	ds_read_b128 v[158:161], v145 offset:3072
	s_add_i32 s50, 0, 0x18000
	s_waitcnt vmcnt(6)
	s_barrier
	v_mfma_f32_16x16x32_bf16 v[46:49], v[208:211], v[162:165], v[46:49]
	v_mfma_f32_16x16x32_bf16 v[42:45], v[228:231], v[162:165], v[42:45]
	v_mfma_f32_16x16x32_bf16 v[30:33], v[208:211], v[170:173], v[30:33]
	v_mfma_f32_16x16x32_bf16 v[26:29], v[228:231], v[170:173], v[26:29]
	v_mfma_f32_16x16x32_bf16 v[14:17], v[208:211], v[192:195], v[14:17]
	v_mfma_f32_16x16x32_bf16 v[10:13], v[228:231], v[192:195], v[10:13]
	v_mfma_f32_16x16x32_bf16 v[6:9], v[208:211], v[200:203], v[6:9]
	v_mfma_f32_16x16x32_bf16 v[2:5], v[228:231], v[200:203], v[2:5]
	v_mfma_f32_16x16x32_bf16 v[46:49], v[224:227], v[166:169], v[46:49]
	v_mfma_f32_16x16x32_bf16 v[42:45], v[232:235], v[166:169], v[42:45]
	v_mfma_f32_16x16x32_bf16 v[30:33], v[224:227], v[174:177], v[30:33]
	v_mfma_f32_16x16x32_bf16 v[26:29], v[232:235], v[174:177], v[26:29]
	v_mfma_f32_16x16x32_bf16 v[14:17], v[224:227], v[196:199], v[14:17]
	v_mfma_f32_16x16x32_bf16 v[10:13], v[232:235], v[196:199], v[10:13]
	v_mfma_f32_16x16x32_bf16 v[6:9], v[224:227], v[204:207], v[6:9]
	v_mfma_f32_16x16x32_bf16 v[2:5], v[232:235], v[204:207], v[2:5]
	s_barrier
	s_add_u32 s22, s22, 0x80000
	s_addc_u32 s23, s23, 0
	s_mov_b32 m0, s29
	v_lshl_add_u64 v[208:209], s[22:23], 0, v[136:137]
	ds_read_b128 v[162:165], v144 offset:32768
	ds_read_b128 v[166:169], v144 offset:33792
	ds_read_b128 v[170:173], v144 offset:34816
	ds_read_b128 v[174:177], v144 offset:35840
	ds_read_b128 v[192:195], v144 offset:36864
	ds_read_b128 v[196:199], v144 offset:37888
	ds_read_b128 v[200:203], v144 offset:38912
	ds_read_b128 v[204:207], v144 offset:39936
	global_load_lds_dwordx4 v[208:209], off
	s_mov_b32 m0, s36
	v_lshl_add_u64 v[208:209], s[22:23], 0, v[132:133]
	global_load_lds_dwordx4 v[208:209], off
	s_barrier
	s_waitcnt lgkmcnt(0)
	v_mfma_f32_16x16x32_bf16 v[126:129], v[146:149], v[162:165], v[126:129]
	v_mfma_f32_16x16x32_bf16 v[122:125], v[154:157], v[162:165], v[122:125]
	v_mfma_f32_16x16x32_bf16 v[118:121], v[146:149], v[170:173], v[118:121]
	v_mfma_f32_16x16x32_bf16 v[114:117], v[154:157], v[170:173], v[114:117]
	v_mfma_f32_16x16x32_bf16 v[102:105], v[146:149], v[192:195], v[102:105]
	v_mfma_f32_16x16x32_bf16 v[98:101], v[154:157], v[192:195], v[98:101]
	v_mfma_f32_16x16x32_bf16 v[86:89], v[146:149], v[200:203], v[86:89]
	v_mfma_f32_16x16x32_bf16 v[82:85], v[154:157], v[200:203], v[82:85]
	v_mfma_f32_16x16x32_bf16 v[126:129], v[150:153], v[166:169], v[126:129]
	v_mfma_f32_16x16x32_bf16 v[122:125], v[158:161], v[166:169], v[122:125]
	v_mfma_f32_16x16x32_bf16 v[118:121], v[150:153], v[174:177], v[118:121]
	v_mfma_f32_16x16x32_bf16 v[114:117], v[158:161], v[174:177], v[114:117]
	v_mfma_f32_16x16x32_bf16 v[102:105], v[150:153], v[196:199], v[102:105]
	v_mfma_f32_16x16x32_bf16 v[98:101], v[158:161], v[196:199], v[98:101]
	v_mfma_f32_16x16x32_bf16 v[86:89], v[150:153], v[204:207], v[86:89]
	v_mfma_f32_16x16x32_bf16 v[82:85], v[158:161], v[204:207], v[82:85]
	s_barrier
	s_add_i32 s51, 0, 0x1c000
	s_add_i32 s22, s50, s26
	v_add_u32_e32 v145, s51, v142
	v_lshl_add_u64 v[178:179], v[178:179], 0, s[78:79]
	s_mov_b32 m0, s22
	ds_read_b128 v[208:211], v145
	ds_read_b128 v[224:227], v145 offset:1024
	ds_read_b128 v[228:231], v145 offset:2048
	ds_read_b128 v[232:235], v145 offset:3072
	global_load_lds_dwordx4 v[178:179], off
	s_add_i32 m0, s22, 0x2000
	v_lshl_add_u64 v[178:179], v[212:213], 0, s[78:79]
	global_load_lds_dwordx4 v[178:179], off
	s_mov_b32 m0, s42
	v_lshl_add_u64 v[178:179], v[236:237], 0, s[78:79]
	s_waitcnt lgkmcnt(0)
	s_barrier
	v_mfma_f32_16x16x32_bf16 v[110:113], v[208:211], v[162:165], v[110:113]
	v_mfma_f32_16x16x32_bf16 v[106:109], v[228:231], v[162:165], v[106:109]
	v_mfma_f32_16x16x32_bf16 v[94:97], v[208:211], v[170:173], v[94:97]
	v_mfma_f32_16x16x32_bf16 v[90:93], v[228:231], v[170:173], v[90:93]
	v_mfma_f32_16x16x32_bf16 v[78:81], v[208:211], v[192:195], v[78:81]
	v_mfma_f32_16x16x32_bf16 v[74:77], v[228:231], v[192:195], v[74:77]
	v_mfma_f32_16x16x32_bf16 v[70:73], v[208:211], v[200:203], v[70:73]
	v_mfma_f32_16x16x32_bf16 v[66:69], v[228:231], v[200:203], v[66:69]
	v_mfma_f32_16x16x32_bf16 v[110:113], v[224:227], v[166:169], v[110:113]
	v_mfma_f32_16x16x32_bf16 v[106:109], v[232:235], v[166:169], v[106:109]
	v_mfma_f32_16x16x32_bf16 v[94:97], v[224:227], v[174:177], v[94:97]
	v_mfma_f32_16x16x32_bf16 v[90:93], v[232:235], v[174:177], v[90:93]
	v_mfma_f32_16x16x32_bf16 v[78:81], v[224:227], v[196:199], v[78:81]
	v_mfma_f32_16x16x32_bf16 v[74:77], v[232:235], v[196:199], v[74:77]
	v_mfma_f32_16x16x32_bf16 v[70:73], v[224:227], v[204:207], v[70:73]
	v_mfma_f32_16x16x32_bf16 v[66:69], v[232:235], v[204:207], v[66:69]
	s_barrier
	ds_read_b128 v[162:165], v144 offset:49152
	ds_read_b128 v[166:169], v144 offset:50176
	ds_read_b128 v[170:173], v144 offset:51200
	ds_read_b128 v[174:177], v144 offset:52224
	ds_read_b128 v[192:195], v144 offset:53248
	ds_read_b128 v[196:199], v144 offset:54272
	ds_read_b128 v[200:203], v144 offset:55296
	ds_read_b128 v[204:207], v144 offset:56320
	global_load_lds_dwordx4 v[178:179], off
	s_mov_b32 m0, s43
	v_lshl_add_u64 v[178:179], v[238:239], 0, s[78:79]
	global_load_lds_dwordx4 v[178:179], off
	s_waitcnt vmcnt(10)
	s_barrier
	s_waitcnt lgkmcnt(0)
	v_mfma_f32_16x16x32_bf16 v[62:65], v[146:149], v[162:165], v[62:65]
	v_mfma_f32_16x16x32_bf16 v[58:61], v[154:157], v[162:165], v[58:61]
	v_mfma_f32_16x16x32_bf16 v[54:57], v[146:149], v[170:173], v[54:57]
	v_mfma_f32_16x16x32_bf16 v[50:53], v[154:157], v[170:173], v[50:53]
	v_mfma_f32_16x16x32_bf16 v[38:41], v[146:149], v[192:195], v[38:41]
	v_mfma_f32_16x16x32_bf16 v[34:37], v[154:157], v[192:195], v[34:37]
	v_mfma_f32_16x16x32_bf16 v[22:25], v[146:149], v[200:203], v[22:25]
	v_mfma_f32_16x16x32_bf16 v[18:21], v[154:157], v[200:203], v[18:21]
	v_mfma_f32_16x16x32_bf16 v[62:65], v[150:153], v[166:169], v[62:65]
	v_mfma_f32_16x16x32_bf16 v[58:61], v[158:161], v[166:169], v[58:61]
	v_mfma_f32_16x16x32_bf16 v[54:57], v[150:153], v[174:177], v[54:57]
	v_mfma_f32_16x16x32_bf16 v[50:53], v[158:161], v[174:177], v[50:53]
	v_mfma_f32_16x16x32_bf16 v[38:41], v[150:153], v[196:199], v[38:41]
	v_mfma_f32_16x16x32_bf16 v[34:37], v[158:161], v[196:199], v[34:37]
	v_mfma_f32_16x16x32_bf16 v[22:25], v[150:153], v[204:207], v[22:25]
	v_mfma_f32_16x16x32_bf16 v[18:21], v[158:161], v[204:207], v[18:21]
	s_barrier
	s_add_u32 s22, s38, 0x20080
	s_addc_u32 s23, s39, 0
	s_add_i32 s38, s51, s26
	s_mov_b32 m0, s38
	v_lshl_add_u64 v[146:147], s[22:23], 0, v[134:135]
	global_load_lds_dwordx4 v[146:147], off
	s_add_i32 m0, s38, 0x2000
	v_lshl_add_u64 v[146:147], s[22:23], 0, v[130:131]
	global_load_lds_dwordx4 v[146:147], off
	v_add_u32_e32 v145, 0x10000, v142
	ds_read_b128 v[146:149], v145
	ds_read_b128 v[150:153], v145 offset:1024
	ds_read_b128 v[154:157], v145 offset:2048
	ds_read_b128 v[158:161], v145 offset:3072
	s_add_i32 s49, s49, 2
	s_add_u32 s20, s20, 0x100
	s_addc_u32 s21, s21, 0
	s_add_u32 s47, s47, 0x100
	s_addc_u32 s48, s48, 0
	s_cmp_gt_u32 s49, 5
	s_waitcnt vmcnt(6)
	s_barrier
	v_mfma_f32_16x16x32_bf16 v[46:49], v[208:211], v[162:165], v[46:49]
	v_mfma_f32_16x16x32_bf16 v[42:45], v[228:231], v[162:165], v[42:45]
	v_mfma_f32_16x16x32_bf16 v[30:33], v[208:211], v[170:173], v[30:33]
	v_mfma_f32_16x16x32_bf16 v[26:29], v[228:231], v[170:173], v[26:29]
	v_mfma_f32_16x16x32_bf16 v[14:17], v[208:211], v[192:195], v[14:17]
	v_mfma_f32_16x16x32_bf16 v[10:13], v[228:231], v[192:195], v[10:13]
	v_mfma_f32_16x16x32_bf16 v[6:9], v[208:211], v[200:203], v[6:9]
	v_mfma_f32_16x16x32_bf16 v[2:5], v[228:231], v[200:203], v[2:5]
	v_mfma_f32_16x16x32_bf16 v[46:49], v[224:227], v[166:169], v[46:49]
	v_mfma_f32_16x16x32_bf16 v[42:45], v[232:235], v[166:169], v[42:45]
	v_mfma_f32_16x16x32_bf16 v[30:33], v[224:227], v[174:177], v[30:33]
	v_mfma_f32_16x16x32_bf16 v[26:29], v[232:235], v[174:177], v[26:29]
	v_mfma_f32_16x16x32_bf16 v[14:17], v[224:227], v[196:199], v[14:17]
	v_mfma_f32_16x16x32_bf16 v[10:13], v[232:235], v[196:199], v[10:13]
	v_mfma_f32_16x16x32_bf16 v[6:9], v[224:227], v[204:207], v[6:9]
	v_mfma_f32_16x16x32_bf16 v[2:5], v[232:235], v[204:207], v[2:5]
	s_barrier
	s_cbranch_scc0 .LBB0_127
	s_waitcnt lgkmcnt(0)
	v_lshl_add_u32 v146, s46, 8, v1
	v_lshl_or_b32 v148, s45, 8, v143
	v_ashrrev_i32_e32 v147, 31, v146
	v_readlane_b32 s48, v254, 40
	v_ashrrev_i32_e32 v149, 31, v148
	v_lshlrev_b64 v[150:151], 12, v[146:147]
	v_readlane_b32 s52, v254, 44
	v_readlane_b32 s53, v254, 45
	v_lshlrev_b64 v[148:149], 1, v[148:149]
	s_mov_b32 s19, 0x80000
	v_lshl_add_u64 v[150:151], s[52:53], 0, v[150:151]
	v_lshl_add_u64 v[150:151], v[150:151], 0, v[148:149]
	s_mov_b64 s[20:21], 0x80000
	v_cvt_pk_bf16_f32 v62, v62, v63
	v_cvt_pk_bf16_f32 v63, v64, v65
	v_cvt_pk_bf16_f32 v64, v58, v59
	v_add_co_u32_e32 v58, vcc, s19, v150
	v_cvt_pk_bf16_f32 v70, v70, v71
	v_cvt_pk_bf16_f32 v71, v72, v73
	v_cvt_pk_bf16_f32 v72, v66, v67
	v_lshl_add_u64 v[66:67], v[150:151], 0, s[20:21]
	v_addc_co_u32_e32 v59, vcc, 0, v151, vcc
	v_cvt_pk_bf16_f32 v46, v46, v47
	v_cvt_pk_bf16_f32 v47, v48, v49
	v_cvt_pk_bf16_f32 v48, v42, v43
	v_cvt_pk_bf16_f32 v49, v44, v45
	s_mov_b32 s19, 0x90000
	v_cvt_pk_bf16_f32 v110, v110, v111
	v_cvt_pk_bf16_f32 v111, v112, v113
	v_cvt_pk_bf16_f32 v112, v106, v107
	v_or_b32_e32 v106, 16, v146
	global_store_dwordx4 v[66:67], v[46:49], off offset:256
	s_mov_b64 s[20:21], 0x90000
	v_ashrrev_i32_e32 v107, 31, v106
	v_add_co_u32_e32 v48, vcc, s19, v150
	v_cvt_pk_bf16_f32 v94, v94, v95
	v_cvt_pk_bf16_f32 v95, v96, v97
	v_cvt_pk_bf16_f32 v96, v90, v91
	v_or_b32_e32 v90, 32, v146
	v_lshl_add_u64 v[46:47], v[150:151], 0, s[20:21]
	v_addc_co_u32_e32 v49, vcc, 0, v151, vcc
	v_cvt_pk_bf16_f32 v30, v30, v31
	v_cvt_pk_bf16_f32 v31, v32, v33
	v_cvt_pk_bf16_f32 v32, v26, v27
	v_cvt_pk_bf16_f32 v33, v28, v29
	s_mov_b32 s19, 0xa0000
	v_lshlrev_b64 v[106:107], 12, v[106:107]
	v_ashrrev_i32_e32 v91, 31, v90
	v_cvt_pk_bf16_f32 v78, v78, v79
	v_cvt_pk_bf16_f32 v79, v80, v81
	v_cvt_pk_bf16_f32 v80, v74, v75
	v_or_b32_e32 v74, 48, v146
	global_store_dwordx4 v[46:47], v[30:33], off offset:256
	s_mov_b64 s[20:21], 0xa0000
	v_cvt_pk_bf16_f32 v113, v108, v109
	v_add_co_u32_e32 v32, vcc, s19, v150
	v_lshl_add_u64 v[106:107], s[52:53], 0, v[106:107]
	v_lshlrev_b64 v[90:91], 12, v[90:91]
	v_ashrrev_i32_e32 v75, 31, v74
	v_lshl_add_u64 v[30:31], v[150:151], 0, s[20:21]
	v_addc_co_u32_e32 v33, vcc, 0, v151, vcc
	v_cvt_pk_bf16_f32 v14, v14, v15
	v_cvt_pk_bf16_f32 v15, v16, v17
	v_cvt_pk_bf16_f32 v16, v10, v11
	v_cvt_pk_bf16_f32 v17, v12, v13
	s_mov_b32 s19, 0xb0000
	global_store_dwordx4 v[150:151], v[110:113], off offset:256
	v_cvt_pk_bf16_f32 v97, v92, v93
	v_lshl_add_u64 v[90:91], s[52:53], 0, v[90:91]
	v_lshl_add_u64 v[110:111], v[106:107], 0, v[148:149]
	v_lshlrev_b64 v[74:75], 12, v[74:75]
	global_store_dwordx4 v[30:31], v[14:17], off offset:256
	global_store_dwordx4 v[110:111], v[94:97], off offset:256
	v_cvt_pk_bf16_f32 v81, v76, v77
	v_add_co_u32_e32 v16, vcc, s19, v150
	v_lshl_add_u64 v[94:95], v[90:91], 0, v[148:149]
	v_lshl_add_u64 v[74:75], s[52:53], 0, v[74:75]
	s_mov_b64 s[20:21], 0xb0000
	v_addc_co_u32_e32 v17, vcc, 0, v151, vcc
	v_cvt_pk_bf16_f32 v126, v126, v127
	v_cvt_pk_bf16_f32 v127, v128, v129
	v_cvt_pk_bf16_f32 v128, v122, v123
	v_cvt_pk_bf16_f32 v129, v124, v125
	v_cvt_pk_bf16_f32 v106, v118, v119
	v_cvt_pk_bf16_f32 v107, v120, v121
	v_cvt_pk_bf16_f32 v108, v114, v115
	v_cvt_pk_bf16_f32 v109, v116, v117
	v_cvt_pk_bf16_f32 v90, v102, v103
	v_cvt_pk_bf16_f32 v91, v104, v105
	v_cvt_pk_bf16_f32 v92, v98, v99
	v_cvt_pk_bf16_f32 v93, v100, v101
	global_store_dwordx4 v[94:95], v[78:81], off offset:256
	v_cvt_pk_bf16_f32 v76, v82, v83
	v_cvt_pk_bf16_f32 v77, v84, v85
	v_lshl_add_u64 v[78:79], v[74:75], 0, v[148:149]
	v_cvt_pk_bf16_f32 v74, v86, v87
	v_cvt_pk_bf16_f32 v75, v88, v89
	v_cvt_pk_bf16_f32 v73, v68, v69
	v_cvt_pk_bf16_f32 v65, v60, v61
	v_cvt_pk_bf16_f32 v42, v54, v55
	v_cvt_pk_bf16_f32 v43, v56, v57
	v_cvt_pk_bf16_f32 v44, v50, v51
	v_cvt_pk_bf16_f32 v45, v52, v53
	v_cvt_pk_bf16_f32 v26, v38, v39
	v_cvt_pk_bf16_f32 v27, v40, v41
	v_cvt_pk_bf16_f32 v28, v34, v35
	v_cvt_pk_bf16_f32 v29, v36, v37
	v_lshl_add_u64 v[14:15], v[150:151], 0, s[20:21]
	v_cvt_pk_bf16_f32 v10, v22, v23
	v_cvt_pk_bf16_f32 v11, v24, v25
	v_cvt_pk_bf16_f32 v12, v18, v19
	v_cvt_pk_bf16_f32 v13, v20, v21
	v_cvt_pk_bf16_f32 v6, v6, v7
	v_cvt_pk_bf16_f32 v7, v8, v9
	v_cvt_pk_bf16_f32 v8, v2, v3
	v_cvt_pk_bf16_f32 v9, v4, v5
	s_and_b64 vcc, exec, s[0:1]
	s_mov_b32 s45, s18
	s_mov_b32 s46, s30
	s_mov_b64 s[22:23], s[82:83]
	s_mov_b64 s[20:21], s[80:81]
	s_mov_b32 s64, 0x800000
	s_movk_i32 s65, 0x1fff
	v_readlane_b32 s49, v254, 41
	v_readlane_b32 s50, v254, 42
	v_readlane_b32 s51, v254, 43
	v_readlane_b32 s54, v254, 46
	v_readlane_b32 s55, v254, 47
	v_readlane_b32 s56, v254, 48
	v_readlane_b32 s57, v254, 49
	v_readlane_b32 s58, v254, 50
	v_readlane_b32 s59, v254, 51
	v_readlane_b32 s60, v254, 52
	v_readlane_b32 s61, v254, 53
	v_readlane_b32 s62, v254, 54
	v_readlane_b32 s63, v254, 55
	global_store_dwordx4 v[150:151], v[126:129], off
	global_store_dwordx4 v[110:111], v[106:109], off
	global_store_dwordx4 v[94:95], v[90:93], off
	global_store_dwordx4 v[78:79], v[74:77], off
	global_store_dwordx4 v[78:79], v[70:73], off offset:256
	global_store_dwordx4 v[58:59], v[62:65], off
	global_store_dwordx4 v[48:49], v[42:45], off
	global_store_dwordx4 v[32:33], v[26:29], off
	global_store_dwordx4 v[16:17], v[10:13], off
	global_store_dwordx4 v[14:15], v[6:9], off offset:256
	s_cbranch_vccz .LBB0_118
	s_waitcnt vmcnt(0)
	v_readlane_b32 s44, v255, 30
	s_mov_b32 s66, s90
	s_cmpk_gt_u32 s25, 0xff
	v_readlane_b32 s45, v255, 31
	v_readlane_b32 s42, v255, 32
	s_cbranch_scc1 .LBB0_131
	s_barrier

.LBB0_240:
	s_add_u32 s22, s80, 0xfff80080
	s_addc_u32 s23, s81, -1
	s_add_i32 s52, 0, 0x10000
	s_cmp_eq_u32 s51, 28
	s_cselect_b32 s23, s21, s23
	s_cselect_b32 s22, s47, s22
	s_cselect_b32 s83, s19, s50
	s_cselect_b32 s82, s48, s49
	v_lshl_add_u64 v[178:179], s[80:81], 0, v[134:135]
	s_add_i32 m0, s27, 0xc000
	ds_read_b128 v[158:161], v140
	ds_read_b128 v[162:165], v140 offset:1024
	ds_read_b128 v[166:169], v140 offset:2048
	ds_read_b128 v[170:173], v140 offset:3072
	ds_read_b128 v[174:177], v140 offset:4096
	ds_read_b128 v[192:195], v140 offset:5120
	ds_read_b128 v[196:199], v140 offset:6144
	ds_read_b128 v[200:203], v140 offset:7168
	global_load_lds_dwordx4 v[178:179], off
	s_add_i32 m0, s27, 0xe000
	v_lshl_add_u64 v[178:179], s[80:81], 0, v[136:137]
	global_load_lds_dwordx4 v[178:179], off
	s_barrier
	s_waitcnt lgkmcnt(0)
	v_mfma_f32_16x16x32_bf16 v[126:129], v[142:145], v[158:161], v[126:129]
	v_mfma_f32_16x16x32_bf16 v[122:125], v[150:153], v[158:161], v[122:125]
	v_mfma_f32_16x16x32_bf16 v[118:121], v[142:145], v[166:169], v[118:121]
	v_mfma_f32_16x16x32_bf16 v[114:117], v[150:153], v[166:169], v[114:117]
	v_mfma_f32_16x16x32_bf16 v[110:113], v[142:145], v[174:177], v[110:113]
	v_mfma_f32_16x16x32_bf16 v[102:105], v[150:153], v[174:177], v[102:105]
	v_mfma_f32_16x16x32_bf16 v[94:97], v[142:145], v[196:199], v[94:97]
	v_mfma_f32_16x16x32_bf16 v[86:89], v[150:153], v[196:199], v[86:89]
	v_mfma_f32_16x16x32_bf16 v[126:129], v[146:149], v[162:165], v[126:129]
	v_mfma_f32_16x16x32_bf16 v[122:125], v[154:157], v[162:165], v[122:125]
	v_mfma_f32_16x16x32_bf16 v[118:121], v[146:149], v[170:173], v[118:121]
	v_mfma_f32_16x16x32_bf16 v[114:117], v[154:157], v[170:173], v[114:117]
	v_mfma_f32_16x16x32_bf16 v[110:113], v[146:149], v[192:195], v[110:113]
	v_mfma_f32_16x16x32_bf16 v[102:105], v[154:157], v[192:195], v[102:105]
	v_mfma_f32_16x16x32_bf16 v[94:97], v[146:149], v[200:203], v[94:97]
	v_mfma_f32_16x16x32_bf16 v[86:89], v[154:157], v[200:203], v[86:89]
	s_barrier
	s_add_i32 s54, 0, 0x14000
	s_add_i32 s52, s52, s26
	v_add_u32_e32 v141, s54, v138
	v_lshl_add_u64 v[178:179], s[82:83], 0, v[132:133]
	s_mov_b32 m0, s52
	ds_read_b128 v[204:207], v141
	ds_read_b128 v[208:211], v141 offset:1024
	ds_read_b128 v[224:227], v141 offset:2048
	ds_read_b128 v[228:231], v141 offset:3072
	global_load_lds_dwordx4 v[178:179], off
	s_add_i32 m0, s52, 0x2000
	v_lshl_add_u64 v[212:213], s[82:83], 0, v[130:131]
	global_load_lds_dwordx4 v[212:213], off
	s_mov_b32 m0, s27
	v_lshl_add_u64 v[232:233], s[22:23], 0, v[132:133]
	s_waitcnt lgkmcnt(0)
	s_barrier
	v_mfma_f32_16x16x32_bf16 v[106:109], v[204:207], v[158:161], v[106:109]
	v_mfma_f32_16x16x32_bf16 v[98:101], v[224:227], v[158:161], v[98:101]
	v_mfma_f32_16x16x32_bf16 v[90:93], v[204:207], v[166:169], v[90:93]
	v_mfma_f32_16x16x32_bf16 v[82:85], v[224:227], v[166:169], v[82:85]
	v_mfma_f32_16x16x32_bf16 v[78:81], v[204:207], v[174:177], v[78:81]
	v_mfma_f32_16x16x32_bf16 v[74:77], v[224:227], v[174:177], v[74:77]
	v_mfma_f32_16x16x32_bf16 v[70:73], v[204:207], v[196:199], v[70:73]
	v_mfma_f32_16x16x32_bf16 v[66:69], v[224:227], v[196:199], v[66:69]
	v_mfma_f32_16x16x32_bf16 v[106:109], v[208:211], v[162:165], v[106:109]
	v_mfma_f32_16x16x32_bf16 v[98:101], v[228:231], v[162:165], v[98:101]
	v_mfma_f32_16x16x32_bf16 v[90:93], v[208:211], v[170:173], v[90:93]
	v_mfma_f32_16x16x32_bf16 v[82:85], v[228:231], v[170:173], v[82:85]
	v_mfma_f32_16x16x32_bf16 v[78:81], v[208:211], v[192:195], v[78:81]
	v_mfma_f32_16x16x32_bf16 v[74:77], v[228:231], v[192:195], v[74:77]
	v_mfma_f32_16x16x32_bf16 v[70:73], v[208:211], v[200:203], v[70:73]
	v_mfma_f32_16x16x32_bf16 v[66:69], v[228:231], v[200:203], v[66:69]
	s_barrier
	ds_read_b128 v[158:161], v140 offset:16384
	ds_read_b128 v[162:165], v140 offset:17408
	ds_read_b128 v[166:169], v140 offset:18432
	ds_read_b128 v[170:173], v140 offset:19456
	ds_read_b128 v[174:177], v140 offset:20480
	ds_read_b128 v[192:195], v140 offset:21504
	ds_read_b128 v[196:199], v140 offset:22528
	ds_read_b128 v[200:203], v140 offset:23552
	global_load_lds_dwordx4 v[232:233], off
	s_mov_b32 m0, s28
	v_lshl_add_u64 v[234:235], s[22:23], 0, v[130:131]
	global_load_lds_dwordx4 v[234:235], off
	s_waitcnt vmcnt(10)
	s_barrier
	s_waitcnt lgkmcnt(0)
	v_mfma_f32_16x16x32_bf16 v[62:65], v[142:145], v[158:161], v[62:65]
	v_mfma_f32_16x16x32_bf16 v[58:61], v[150:153], v[158:161], v[58:61]
	v_mfma_f32_16x16x32_bf16 v[54:57], v[142:145], v[166:169], v[54:57]
	v_mfma_f32_16x16x32_bf16 v[50:53], v[150:153], v[166:169], v[50:53]
	v_mfma_f32_16x16x32_bf16 v[46:49], v[142:145], v[174:177], v[46:49]
	v_mfma_f32_16x16x32_bf16 v[38:41], v[150:153], v[174:177], v[38:41]
	v_mfma_f32_16x16x32_bf16 v[30:33], v[142:145], v[196:199], v[30:33]
	v_mfma_f32_16x16x32_bf16 v[22:25], v[150:153], v[196:199], v[22:25]
	v_mfma_f32_16x16x32_bf16 v[62:65], v[146:149], v[162:165], v[62:65]
	v_mfma_f32_16x16x32_bf16 v[58:61], v[154:157], v[162:165], v[58:61]
	v_mfma_f32_16x16x32_bf16 v[54:57], v[146:149], v[170:173], v[54:57]
	v_mfma_f32_16x16x32_bf16 v[50:53], v[154:157], v[170:173], v[50:53]
	v_mfma_f32_16x16x32_bf16 v[46:49], v[146:149], v[192:195], v[46:49]
	v_mfma_f32_16x16x32_bf16 v[38:41], v[154:157], v[192:195], v[38:41]
	v_mfma_f32_16x16x32_bf16 v[30:33], v[146:149], v[200:203], v[30:33]
	v_mfma_f32_16x16x32_bf16 v[22:25], v[154:157], v[200:203], v[22:25]
	s_barrier
	s_add_u32 s52, s82, 0x80000
	s_addc_u32 s53, s83, 0
	s_add_i32 s54, s54, s26
	s_mov_b32 m0, s54
	v_lshl_add_u64 v[142:143], s[52:53], 0, v[132:133]
	global_load_lds_dwordx4 v[142:143], off
	s_add_i32 m0, s54, 0x2000
	v_lshl_add_u64 v[142:143], s[52:53], 0, v[130:131]
	global_load_lds_dwordx4 v[142:143], off
	v_add_u32_e32 v141, 0x18000, v138
	ds_read_b128 v[142:145], v141
	ds_read_b128 v[146:149], v141 offset:1024
	ds_read_b128 v[150:153], v141 offset:2048
	ds_read_b128 v[154:157], v141 offset:3072
	s_add_i32 s52, 0, 0x18000
	s_waitcnt vmcnt(6)
	s_barrier
	v_mfma_f32_16x16x32_bf16 v[42:45], v[204:207], v[158:161], v[42:45]
	v_mfma_f32_16x16x32_bf16 v[34:37], v[224:227], v[158:161], v[34:37]
	v_mfma_f32_16x16x32_bf16 v[26:29], v[204:207], v[166:169], v[26:29]
	v_mfma_f32_16x16x32_bf16 v[18:21], v[224:227], v[166:169], v[18:21]
	v_mfma_f32_16x16x32_bf16 v[14:17], v[204:207], v[174:177], v[14:17]
	v_mfma_f32_16x16x32_bf16 v[10:13], v[224:227], v[174:177], v[10:13]
	v_mfma_f32_16x16x32_bf16 v[6:9], v[204:207], v[196:199], v[6:9]
	v_mfma_f32_16x16x32_bf16 v[2:5], v[224:227], v[196:199], v[2:5]
	v_mfma_f32_16x16x32_bf16 v[42:45], v[208:211], v[162:165], v[42:45]
	v_mfma_f32_16x16x32_bf16 v[34:37], v[228:231], v[162:165], v[34:37]
	v_mfma_f32_16x16x32_bf16 v[26:29], v[208:211], v[170:173], v[26:29]
	v_mfma_f32_16x16x32_bf16 v[18:21], v[228:231], v[170:173], v[18:21]
	v_mfma_f32_16x16x32_bf16 v[14:17], v[208:211], v[192:195], v[14:17]
	v_mfma_f32_16x16x32_bf16 v[10:13], v[228:231], v[192:195], v[10:13]
	v_mfma_f32_16x16x32_bf16 v[6:9], v[208:211], v[200:203], v[6:9]
	v_mfma_f32_16x16x32_bf16 v[2:5], v[228:231], v[200:203], v[2:5]
	s_barrier
	s_add_u32 s22, s22, 0x80000
	s_addc_u32 s23, s23, 0
	s_mov_b32 m0, s29
	v_lshl_add_u64 v[204:205], s[22:23], 0, v[132:133]
	ds_read_b128 v[158:161], v140 offset:32768
	ds_read_b128 v[162:165], v140 offset:33792
	ds_read_b128 v[166:169], v140 offset:34816
	ds_read_b128 v[170:173], v140 offset:35840
	ds_read_b128 v[174:177], v140 offset:36864
	ds_read_b128 v[192:195], v140 offset:37888
	ds_read_b128 v[196:199], v140 offset:38912
	ds_read_b128 v[200:203], v140 offset:39936
	global_load_lds_dwordx4 v[204:205], off
	s_mov_b32 m0, s36
	v_lshl_add_u64 v[204:205], s[22:23], 0, v[130:131]
	global_load_lds_dwordx4 v[204:205], off
	s_barrier
	s_waitcnt lgkmcnt(0)
	v_mfma_f32_16x16x32_bf16 v[126:129], v[142:145], v[158:161], v[126:129]
	v_mfma_f32_16x16x32_bf16 v[122:125], v[150:153], v[158:161], v[122:125]
	v_mfma_f32_16x16x32_bf16 v[118:121], v[142:145], v[166:169], v[118:121]
	v_mfma_f32_16x16x32_bf16 v[114:117], v[150:153], v[166:169], v[114:117]
	v_mfma_f32_16x16x32_bf16 v[110:113], v[142:145], v[174:177], v[110:113]
	v_mfma_f32_16x16x32_bf16 v[102:105], v[150:153], v[174:177], v[102:105]
	v_mfma_f32_16x16x32_bf16 v[94:97], v[142:145], v[196:199], v[94:97]
	v_mfma_f32_16x16x32_bf16 v[86:89], v[150:153], v[196:199], v[86:89]
	v_mfma_f32_16x16x32_bf16 v[126:129], v[146:149], v[162:165], v[126:129]
	v_mfma_f32_16x16x32_bf16 v[122:125], v[154:157], v[162:165], v[122:125]
	v_mfma_f32_16x16x32_bf16 v[118:121], v[146:149], v[170:173], v[118:121]
	v_mfma_f32_16x16x32_bf16 v[114:117], v[154:157], v[170:173], v[114:117]
	v_mfma_f32_16x16x32_bf16 v[110:113], v[146:149], v[192:195], v[110:113]
	v_mfma_f32_16x16x32_bf16 v[102:105], v[154:157], v[192:195], v[102:105]
	v_mfma_f32_16x16x32_bf16 v[94:97], v[146:149], v[200:203], v[94:97]
	v_mfma_f32_16x16x32_bf16 v[86:89], v[154:157], v[200:203], v[86:89]
	s_barrier
	s_add_i32 s53, 0, 0x1c000
	s_add_i32 s22, s52, s26
	v_add_u32_e32 v141, s53, v138
	v_lshl_add_u64 v[178:179], v[178:179], 0, s[78:79]
	s_mov_b32 m0, s22
	ds_read_b128 v[204:207], v141
	ds_read_b128 v[208:211], v141 offset:1024
	ds_read_b128 v[224:227], v141 offset:2048
	ds_read_b128 v[228:231], v141 offset:3072
	global_load_lds_dwordx4 v[178:179], off
	s_add_i32 m0, s22, 0x2000
	v_lshl_add_u64 v[178:179], v[212:213], 0, s[78:79]
	global_load_lds_dwordx4 v[178:179], off
	s_mov_b32 m0, s42
	v_lshl_add_u64 v[178:179], v[232:233], 0, s[78:79]
	s_waitcnt lgkmcnt(0)
	s_barrier
	v_mfma_f32_16x16x32_bf16 v[106:109], v[204:207], v[158:161], v[106:109]
	v_mfma_f32_16x16x32_bf16 v[98:101], v[224:227], v[158:161], v[98:101]
	v_mfma_f32_16x16x32_bf16 v[90:93], v[204:207], v[166:169], v[90:93]
	v_mfma_f32_16x16x32_bf16 v[82:85], v[224:227], v[166:169], v[82:85]
	v_mfma_f32_16x16x32_bf16 v[78:81], v[204:207], v[174:177], v[78:81]
	v_mfma_f32_16x16x32_bf16 v[74:77], v[224:227], v[174:177], v[74:77]
	v_mfma_f32_16x16x32_bf16 v[70:73], v[204:207], v[196:199], v[70:73]
	v_mfma_f32_16x16x32_bf16 v[66:69], v[224:227], v[196:199], v[66:69]
	v_mfma_f32_16x16x32_bf16 v[106:109], v[208:211], v[162:165], v[106:109]
	v_mfma_f32_16x16x32_bf16 v[98:101], v[228:231], v[162:165], v[98:101]
	v_mfma_f32_16x16x32_bf16 v[90:93], v[208:211], v[170:173], v[90:93]
	v_mfma_f32_16x16x32_bf16 v[82:85], v[228:231], v[170:173], v[82:85]
	v_mfma_f32_16x16x32_bf16 v[78:81], v[208:211], v[192:195], v[78:81]
	v_mfma_f32_16x16x32_bf16 v[74:77], v[228:231], v[192:195], v[74:77]
	v_mfma_f32_16x16x32_bf16 v[70:73], v[208:211], v[200:203], v[70:73]
	v_mfma_f32_16x16x32_bf16 v[66:69], v[228:231], v[200:203], v[66:69]
	s_barrier
	ds_read_b128 v[158:161], v140 offset:49152
	ds_read_b128 v[162:165], v140 offset:50176
	ds_read_b128 v[166:169], v140 offset:51200
	ds_read_b128 v[170:173], v140 offset:52224
	ds_read_b128 v[174:177], v140 offset:53248
	ds_read_b128 v[192:195], v140 offset:54272
	ds_read_b128 v[196:199], v140 offset:55296
	ds_read_b128 v[200:203], v140 offset:56320
	global_load_lds_dwordx4 v[178:179], off
	s_mov_b32 m0, s43
	v_lshl_add_u64 v[178:179], v[234:235], 0, s[78:79]
	global_load_lds_dwordx4 v[178:179], off
	s_waitcnt vmcnt(10)
	s_barrier
	s_waitcnt lgkmcnt(0)
	v_mfma_f32_16x16x32_bf16 v[62:65], v[142:145], v[158:161], v[62:65]
	v_mfma_f32_16x16x32_bf16 v[58:61], v[150:153], v[158:161], v[58:61]
	v_mfma_f32_16x16x32_bf16 v[54:57], v[142:145], v[166:169], v[54:57]
	v_mfma_f32_16x16x32_bf16 v[50:53], v[150:153], v[166:169], v[50:53]
	v_mfma_f32_16x16x32_bf16 v[46:49], v[142:145], v[174:177], v[46:49]
	v_mfma_f32_16x16x32_bf16 v[38:41], v[150:153], v[174:177], v[38:41]
	v_mfma_f32_16x16x32_bf16 v[30:33], v[142:145], v[196:199], v[30:33]
	v_mfma_f32_16x16x32_bf16 v[22:25], v[150:153], v[196:199], v[22:25]
	v_mfma_f32_16x16x32_bf16 v[62:65], v[146:149], v[162:165], v[62:65]
	v_mfma_f32_16x16x32_bf16 v[58:61], v[154:157], v[162:165], v[58:61]
	v_mfma_f32_16x16x32_bf16 v[54:57], v[146:149], v[170:173], v[54:57]
	v_mfma_f32_16x16x32_bf16 v[50:53], v[154:157], v[170:173], v[50:53]
	v_mfma_f32_16x16x32_bf16 v[46:49], v[146:149], v[192:195], v[46:49]
	v_mfma_f32_16x16x32_bf16 v[38:41], v[154:157], v[192:195], v[38:41]
	v_mfma_f32_16x16x32_bf16 v[30:33], v[146:149], v[200:203], v[30:33]
	v_mfma_f32_16x16x32_bf16 v[22:25], v[154:157], v[200:203], v[22:25]
	s_barrier
	s_add_u32 s22, s82, 0x80080
	s_addc_u32 s23, s83, 0
	s_add_i32 s52, s53, s26
	s_mov_b32 m0, s52
	v_lshl_add_u64 v[142:143], s[22:23], 0, v[132:133]
	global_load_lds_dwordx4 v[142:143], off
	s_add_i32 m0, s52, 0x2000
	v_lshl_add_u64 v[142:143], s[22:23], 0, v[130:131]
	global_load_lds_dwordx4 v[142:143], off
	v_add_u32_e32 v141, 0x10000, v138
	ds_read_b128 v[142:145], v141
	ds_read_b128 v[146:149], v141 offset:1024
	ds_read_b128 v[150:153], v141 offset:2048
	ds_read_b128 v[154:157], v141 offset:3072
	s_add_i32 s51, s51, 2
	s_add_u32 s80, s80, 0x100
	s_addc_u32 s81, s81, 0
	s_add_u32 s49, s49, 0x100
	s_addc_u32 s50, s50, 0
	s_cmp_gt_u32 s51, 29
	s_waitcnt vmcnt(6)
	s_barrier
	v_mfma_f32_16x16x32_bf16 v[42:45], v[204:207], v[158:161], v[42:45]
	v_mfma_f32_16x16x32_bf16 v[34:37], v[224:227], v[158:161], v[34:37]
	v_mfma_f32_16x16x32_bf16 v[26:29], v[204:207], v[166:169], v[26:29]
	v_mfma_f32_16x16x32_bf16 v[18:21], v[224:227], v[166:169], v[18:21]
	v_mfma_f32_16x16x32_bf16 v[14:17], v[204:207], v[174:177], v[14:17]
	v_mfma_f32_16x16x32_bf16 v[10:13], v[224:227], v[174:177], v[10:13]
	v_mfma_f32_16x16x32_bf16 v[6:9], v[204:207], v[196:199], v[6:9]
	v_mfma_f32_16x16x32_bf16 v[2:5], v[224:227], v[196:199], v[2:5]
	v_mfma_f32_16x16x32_bf16 v[42:45], v[208:211], v[162:165], v[42:45]
	v_mfma_f32_16x16x32_bf16 v[34:37], v[228:231], v[162:165], v[34:37]
	v_mfma_f32_16x16x32_bf16 v[26:29], v[208:211], v[170:173], v[26:29]
	v_mfma_f32_16x16x32_bf16 v[18:21], v[228:231], v[170:173], v[18:21]
	v_mfma_f32_16x16x32_bf16 v[14:17], v[208:211], v[192:195], v[14:17]
	v_mfma_f32_16x16x32_bf16 v[10:13], v[228:231], v[192:195], v[10:13]
	v_mfma_f32_16x16x32_bf16 v[6:9], v[208:211], v[200:203], v[6:9]
	v_mfma_f32_16x16x32_bf16 v[2:5], v[228:231], v[200:203], v[2:5]
	s_barrier
	s_cbranch_scc0 .LBB0_240
	s_waitcnt lgkmcnt(0)
	v_readlane_b32 s48, v254, 40
	v_lshl_or_b32 v142, s45, 8, v139
	v_readlane_b32 s52, v254, 44
	v_readlane_b32 s53, v254, 45
	v_lshl_add_u32 v141, s46, 8, v1
	v_ashrrev_i32_e32 v143, 31, v142
	v_mov_b64_e32 v[144:145], s[52:53]
	s_movk_i32 s19, 0x1400
	v_mad_i64_i32 v[146:147], s[22:23], v141, s19, v[144:145]
	v_lshlrev_b64 v[142:143], 2, v[142:143]
	v_lshl_add_u64 v[146:147], v[146:147], 0, v[142:143]
	global_store_dwordx4 v[146:147], v[126:129], off
	global_store_dwordx4 v[146:147], v[122:125], off offset:64
	global_store_dwordx4 v[146:147], v[106:109], off offset:512
	global_store_dwordx4 v[146:147], v[98:101], off offset:576
	s_movk_i32 s94, 0x1400
	s_and_b64 vcc, exec, s[0:1]
	v_or_b32_e32 v98, 16, v141
	v_mad_i64_i32 v[98:99], s[22:23], v98, s19, v[144:145]
	v_lshl_add_u64 v[98:99], v[98:99], 0, v[142:143]
	global_store_dwordx4 v[98:99], v[118:121], off
	global_store_dwordx4 v[98:99], v[114:117], off offset:64
	global_store_dwordx4 v[98:99], v[90:93], off offset:512
	global_store_dwordx4 v[98:99], v[82:85], off offset:576
	s_mov_b32 s45, s18
	s_mov_b32 s46, s20
	v_or_b32_e32 v82, 32, v141
	v_mad_i64_i32 v[82:83], s[22:23], v82, s19, v[144:145]
	v_lshl_add_u64 v[82:83], v[82:83], 0, v[142:143]
	global_store_dwordx4 v[82:83], v[110:113], off
	global_store_dwordx4 v[82:83], v[102:105], off offset:64
	global_store_dwordx4 v[82:83], v[78:81], off offset:512
	global_store_dwordx4 v[82:83], v[74:77], off offset:576
	s_mov_b64 s[80:81], s[30:31]
	v_readlane_b32 s49, v254, 41
	v_or_b32_e32 v74, 48, v141
	v_mad_i64_i32 v[74:75], s[22:23], v74, s19, v[144:145]
	v_lshl_add_u64 v[74:75], v[74:75], 0, v[142:143]
	global_store_dwordx4 v[74:75], v[94:97], off
	global_store_dwordx4 v[74:75], v[86:89], off offset:64
	global_store_dwordx4 v[74:75], v[70:73], off offset:512
	global_store_dwordx4 v[74:75], v[66:69], off offset:576
	v_readlane_b32 s50, v254, 42
	v_readlane_b32 s51, v254, 43
	v_add_u32_e32 v66, 0x80, v141
	v_mad_i64_i32 v[66:67], s[22:23], v66, s19, v[144:145]
	v_lshl_add_u64 v[66:67], v[66:67], 0, v[142:143]
	global_store_dwordx4 v[66:67], v[62:65], off
	global_store_dwordx4 v[66:67], v[58:61], off offset:64
	global_store_dwordx4 v[66:67], v[42:45], off offset:512
	global_store_dwordx4 v[66:67], v[34:37], off offset:576
	v_readlane_b32 s54, v254, 46
	v_readlane_b32 s55, v254, 47
	v_add_u32_e32 v34, 0x90, v141
	v_mad_i64_i32 v[34:35], s[22:23], v34, s19, v[144:145]
	v_lshl_add_u64 v[34:35], v[34:35], 0, v[142:143]
	global_store_dwordx4 v[34:35], v[54:57], off
	global_store_dwordx4 v[34:35], v[50:53], off offset:64
	global_store_dwordx4 v[34:35], v[26:29], off offset:512
	global_store_dwordx4 v[34:35], v[18:21], off offset:576
	v_readlane_b32 s56, v254, 48
	v_readlane_b32 s57, v254, 49
	v_add_u32_e32 v18, 0xa0, v141
	v_mad_i64_i32 v[18:19], s[22:23], v18, s19, v[144:145]
	v_lshl_add_u64 v[18:19], v[18:19], 0, v[142:143]
	global_store_dwordx4 v[18:19], v[46:49], off
	global_store_dwordx4 v[18:19], v[38:41], off offset:64
	global_store_dwordx4 v[18:19], v[14:17], off offset:512
	global_store_dwordx4 v[18:19], v[10:13], off offset:576
	v_readlane_b32 s58, v254, 50
	v_readlane_b32 s59, v254, 51
	v_add_u32_e32 v10, 0xb0, v141
	v_mad_i64_i32 v[10:11], s[22:23], v10, s19, v[144:145]
	v_lshl_add_u64 v[10:11], v[10:11], 0, v[142:143]
	s_mov_b64 s[22:23], s[38:39]
	v_readlane_b32 s60, v254, 52
	v_readlane_b32 s61, v254, 53
	v_readlane_b32 s62, v254, 54
	v_readlane_b32 s63, v254, 55
	global_store_dwordx4 v[10:11], v[30:33], off
	global_store_dwordx4 v[10:11], v[22:25], off offset:64
	global_store_dwordx4 v[10:11], v[6:9], off offset:512
	global_store_dwordx4 v[10:11], v[2:5], off offset:576
	s_cbranch_vccz .LBB0_237
	s_waitcnt vmcnt(0)
	v_readlane_b32 s44, v255, 30
	s_cmpk_gt_u32 s25, 0xff
	v_readlane_b32 s45, v255, 31
	v_readlane_b32 s42, v255, 32
	s_cbranch_scc1 .LBB0_244
	s_barrier

.LBB0_357:
	s_add_u32 s22, s20, 0xfffe0080
	s_addc_u32 s23, s21, -1
	s_add_i32 s52, 0, 0x10000
	s_cmp_eq_u32 s51, 4
	s_cselect_b32 s23, s31, s23
	s_cselect_b32 s22, s47, s22
	s_cselect_b32 s85, s19, s50
	s_cselect_b32 s84, s48, s49
	v_lshl_add_u64 v[178:179], s[20:21], 0, v[138:139]
	s_add_i32 m0, s27, 0xc000
	ds_read_b128 v[162:165], v144
	ds_read_b128 v[166:169], v144 offset:1024
	ds_read_b128 v[170:173], v144 offset:2048
	ds_read_b128 v[174:177], v144 offset:3072
	ds_read_b128 v[192:195], v144 offset:4096
	ds_read_b128 v[196:199], v144 offset:5120
	ds_read_b128 v[200:203], v144 offset:6144
	ds_read_b128 v[204:207], v144 offset:7168
	global_load_lds_dwordx4 v[178:179], off
	s_add_i32 m0, s27, 0xe000
	v_lshl_add_u64 v[178:179], s[20:21], 0, v[140:141]
	global_load_lds_dwordx4 v[178:179], off
	s_barrier
	s_waitcnt lgkmcnt(0)
	v_mfma_f32_16x16x32_bf16 v[126:129], v[146:149], v[162:165], v[126:129]
	v_mfma_f32_16x16x32_bf16 v[122:125], v[154:157], v[162:165], v[122:125]
	v_mfma_f32_16x16x32_bf16 v[118:121], v[146:149], v[170:173], v[118:121]
	v_mfma_f32_16x16x32_bf16 v[114:117], v[154:157], v[170:173], v[114:117]
	v_mfma_f32_16x16x32_bf16 v[102:105], v[146:149], v[192:195], v[102:105]
	v_mfma_f32_16x16x32_bf16 v[98:101], v[154:157], v[192:195], v[98:101]
	v_mfma_f32_16x16x32_bf16 v[86:89], v[146:149], v[200:203], v[86:89]
	v_mfma_f32_16x16x32_bf16 v[82:85], v[154:157], v[200:203], v[82:85]
	v_mfma_f32_16x16x32_bf16 v[126:129], v[150:153], v[166:169], v[126:129]
	v_mfma_f32_16x16x32_bf16 v[122:125], v[158:161], v[166:169], v[122:125]
	v_mfma_f32_16x16x32_bf16 v[118:121], v[150:153], v[174:177], v[118:121]
	v_mfma_f32_16x16x32_bf16 v[114:117], v[158:161], v[174:177], v[114:117]
	v_mfma_f32_16x16x32_bf16 v[102:105], v[150:153], v[196:199], v[102:105]
	v_mfma_f32_16x16x32_bf16 v[98:101], v[158:161], v[196:199], v[98:101]
	v_mfma_f32_16x16x32_bf16 v[86:89], v[150:153], v[204:207], v[86:89]
	v_mfma_f32_16x16x32_bf16 v[82:85], v[158:161], v[204:207], v[82:85]
	s_barrier
	s_add_i32 s54, 0, 0x14000
	s_add_i32 s52, s52, s26
	v_add_u32_e32 v145, s54, v142
	v_lshl_add_u64 v[178:179], s[84:85], 0, v[134:135]
	s_mov_b32 m0, s52
	ds_read_b128 v[208:211], v145
	ds_read_b128 v[224:227], v145 offset:1024
	ds_read_b128 v[228:231], v145 offset:2048
	ds_read_b128 v[232:235], v145 offset:3072
	global_load_lds_dwordx4 v[178:179], off
	s_add_i32 m0, s52, 0x2000
	v_lshl_add_u64 v[212:213], s[84:85], 0, v[130:131]
	global_load_lds_dwordx4 v[212:213], off
	s_mov_b32 m0, s27
	v_lshl_add_u64 v[236:237], s[22:23], 0, v[136:137]
	s_waitcnt lgkmcnt(0)
	s_barrier
	v_mfma_f32_16x16x32_bf16 v[110:113], v[208:211], v[162:165], v[110:113]
	v_mfma_f32_16x16x32_bf16 v[106:109], v[228:231], v[162:165], v[106:109]
	v_mfma_f32_16x16x32_bf16 v[94:97], v[208:211], v[170:173], v[94:97]
	v_mfma_f32_16x16x32_bf16 v[90:93], v[228:231], v[170:173], v[90:93]
	v_mfma_f32_16x16x32_bf16 v[78:81], v[208:211], v[192:195], v[78:81]
	v_mfma_f32_16x16x32_bf16 v[74:77], v[228:231], v[192:195], v[74:77]
	v_mfma_f32_16x16x32_bf16 v[70:73], v[208:211], v[200:203], v[70:73]
	v_mfma_f32_16x16x32_bf16 v[66:69], v[228:231], v[200:203], v[66:69]
	v_mfma_f32_16x16x32_bf16 v[110:113], v[224:227], v[166:169], v[110:113]
	v_mfma_f32_16x16x32_bf16 v[106:109], v[232:235], v[166:169], v[106:109]
	v_mfma_f32_16x16x32_bf16 v[94:97], v[224:227], v[174:177], v[94:97]
	v_mfma_f32_16x16x32_bf16 v[90:93], v[232:235], v[174:177], v[90:93]
	v_mfma_f32_16x16x32_bf16 v[78:81], v[224:227], v[196:199], v[78:81]
	v_mfma_f32_16x16x32_bf16 v[74:77], v[232:235], v[196:199], v[74:77]
	v_mfma_f32_16x16x32_bf16 v[70:73], v[224:227], v[204:207], v[70:73]
	v_mfma_f32_16x16x32_bf16 v[66:69], v[232:235], v[204:207], v[66:69]
	s_barrier
	ds_read_b128 v[162:165], v144 offset:16384
	ds_read_b128 v[166:169], v144 offset:17408
	ds_read_b128 v[170:173], v144 offset:18432
	ds_read_b128 v[174:177], v144 offset:19456
	ds_read_b128 v[192:195], v144 offset:20480
	ds_read_b128 v[196:199], v144 offset:21504
	ds_read_b128 v[200:203], v144 offset:22528
	ds_read_b128 v[204:207], v144 offset:23552
	global_load_lds_dwordx4 v[236:237], off
	s_mov_b32 m0, s28
	v_lshl_add_u64 v[238:239], s[22:23], 0, v[132:133]
	global_load_lds_dwordx4 v[238:239], off
	s_waitcnt vmcnt(10)
	s_barrier
	s_waitcnt lgkmcnt(0)
	v_mfma_f32_16x16x32_bf16 v[62:65], v[146:149], v[162:165], v[62:65]
	v_mfma_f32_16x16x32_bf16 v[58:61], v[154:157], v[162:165], v[58:61]
	v_mfma_f32_16x16x32_bf16 v[54:57], v[146:149], v[170:173], v[54:57]
	v_mfma_f32_16x16x32_bf16 v[50:53], v[154:157], v[170:173], v[50:53]
	v_mfma_f32_16x16x32_bf16 v[38:41], v[146:149], v[192:195], v[38:41]
	v_mfma_f32_16x16x32_bf16 v[34:37], v[154:157], v[192:195], v[34:37]
	v_mfma_f32_16x16x32_bf16 v[22:25], v[146:149], v[200:203], v[22:25]
	v_mfma_f32_16x16x32_bf16 v[18:21], v[154:157], v[200:203], v[18:21]
	v_mfma_f32_16x16x32_bf16 v[62:65], v[150:153], v[166:169], v[62:65]
	v_mfma_f32_16x16x32_bf16 v[58:61], v[158:161], v[166:169], v[58:61]
	v_mfma_f32_16x16x32_bf16 v[54:57], v[150:153], v[174:177], v[54:57]
	v_mfma_f32_16x16x32_bf16 v[50:53], v[158:161], v[174:177], v[50:53]
	v_mfma_f32_16x16x32_bf16 v[38:41], v[150:153], v[196:199], v[38:41]
	v_mfma_f32_16x16x32_bf16 v[34:37], v[158:161], v[196:199], v[34:37]
	v_mfma_f32_16x16x32_bf16 v[22:25], v[150:153], v[204:207], v[22:25]
	v_mfma_f32_16x16x32_bf16 v[18:21], v[158:161], v[204:207], v[18:21]
	s_barrier
	s_add_u32 s52, s84, 0x20000
	s_addc_u32 s53, s85, 0
	s_add_i32 s54, s54, s26
	s_mov_b32 m0, s54
	v_lshl_add_u64 v[146:147], s[52:53], 0, v[134:135]
	global_load_lds_dwordx4 v[146:147], off
	s_add_i32 m0, s54, 0x2000
	v_lshl_add_u64 v[146:147], s[52:53], 0, v[130:131]
	global_load_lds_dwordx4 v[146:147], off
	v_add_u32_e32 v145, 0x18000, v142
	ds_read_b128 v[146:149], v145
	ds_read_b128 v[150:153], v145 offset:1024
	ds_read_b128 v[154:157], v145 offset:2048
	ds_read_b128 v[158:161], v145 offset:3072
	s_add_i32 s52, 0, 0x18000
	s_waitcnt vmcnt(6)
	s_barrier
	v_mfma_f32_16x16x32_bf16 v[46:49], v[208:211], v[162:165], v[46:49]
	v_mfma_f32_16x16x32_bf16 v[42:45], v[228:231], v[162:165], v[42:45]
	v_mfma_f32_16x16x32_bf16 v[30:33], v[208:211], v[170:173], v[30:33]
	v_mfma_f32_16x16x32_bf16 v[26:29], v[228:231], v[170:173], v[26:29]
	v_mfma_f32_16x16x32_bf16 v[14:17], v[208:211], v[192:195], v[14:17]
	v_mfma_f32_16x16x32_bf16 v[10:13], v[228:231], v[192:195], v[10:13]
	v_mfma_f32_16x16x32_bf16 v[6:9], v[208:211], v[200:203], v[6:9]
	v_mfma_f32_16x16x32_bf16 v[2:5], v[228:231], v[200:203], v[2:5]
	v_mfma_f32_16x16x32_bf16 v[46:49], v[224:227], v[166:169], v[46:49]
	v_mfma_f32_16x16x32_bf16 v[42:45], v[232:235], v[166:169], v[42:45]
	v_mfma_f32_16x16x32_bf16 v[30:33], v[224:227], v[174:177], v[30:33]
	v_mfma_f32_16x16x32_bf16 v[26:29], v[232:235], v[174:177], v[26:29]
	v_mfma_f32_16x16x32_bf16 v[14:17], v[224:227], v[196:199], v[14:17]
	v_mfma_f32_16x16x32_bf16 v[10:13], v[232:235], v[196:199], v[10:13]
	v_mfma_f32_16x16x32_bf16 v[6:9], v[224:227], v[204:207], v[6:9]
	v_mfma_f32_16x16x32_bf16 v[2:5], v[232:235], v[204:207], v[2:5]
	s_barrier
	s_add_u32 s22, s22, 0x20000
	s_addc_u32 s23, s23, 0
	s_mov_b32 m0, s29
	v_lshl_add_u64 v[208:209], s[22:23], 0, v[136:137]
	ds_read_b128 v[162:165], v144 offset:32768
	ds_read_b128 v[166:169], v144 offset:33792
	ds_read_b128 v[170:173], v144 offset:34816
	ds_read_b128 v[174:177], v144 offset:35840
	ds_read_b128 v[192:195], v144 offset:36864
	ds_read_b128 v[196:199], v144 offset:37888
	ds_read_b128 v[200:203], v144 offset:38912
	ds_read_b128 v[204:207], v144 offset:39936
	global_load_lds_dwordx4 v[208:209], off
	s_mov_b32 m0, s36
	v_lshl_add_u64 v[208:209], s[22:23], 0, v[132:133]
	global_load_lds_dwordx4 v[208:209], off
	s_barrier
	s_waitcnt lgkmcnt(0)
	v_mfma_f32_16x16x32_bf16 v[126:129], v[146:149], v[162:165], v[126:129]
	v_mfma_f32_16x16x32_bf16 v[122:125], v[154:157], v[162:165], v[122:125]
	v_mfma_f32_16x16x32_bf16 v[118:121], v[146:149], v[170:173], v[118:121]
	v_mfma_f32_16x16x32_bf16 v[114:117], v[154:157], v[170:173], v[114:117]
	v_mfma_f32_16x16x32_bf16 v[102:105], v[146:149], v[192:195], v[102:105]
	v_mfma_f32_16x16x32_bf16 v[98:101], v[154:157], v[192:195], v[98:101]
	v_mfma_f32_16x16x32_bf16 v[86:89], v[146:149], v[200:203], v[86:89]
	v_mfma_f32_16x16x32_bf16 v[82:85], v[154:157], v[200:203], v[82:85]
	v_mfma_f32_16x16x32_bf16 v[126:129], v[150:153], v[166:169], v[126:129]
	v_mfma_f32_16x16x32_bf16 v[122:125], v[158:161], v[166:169], v[122:125]
	v_mfma_f32_16x16x32_bf16 v[118:121], v[150:153], v[174:177], v[118:121]
	v_mfma_f32_16x16x32_bf16 v[114:117], v[158:161], v[174:177], v[114:117]
	v_mfma_f32_16x16x32_bf16 v[102:105], v[150:153], v[196:199], v[102:105]
	v_mfma_f32_16x16x32_bf16 v[98:101], v[158:161], v[196:199], v[98:101]
	v_mfma_f32_16x16x32_bf16 v[86:89], v[150:153], v[204:207], v[86:89]
	v_mfma_f32_16x16x32_bf16 v[82:85], v[158:161], v[204:207], v[82:85]
	s_barrier
	s_add_i32 s53, 0, 0x1c000
	s_add_i32 s22, s52, s26
	v_add_u32_e32 v145, s53, v142
	v_lshl_add_u64 v[178:179], v[178:179], 0, s[78:79]
	s_mov_b32 m0, s22
	ds_read_b128 v[208:211], v145
	ds_read_b128 v[224:227], v145 offset:1024
	ds_read_b128 v[228:231], v145 offset:2048
	ds_read_b128 v[232:235], v145 offset:3072
	global_load_lds_dwordx4 v[178:179], off
	s_add_i32 m0, s22, 0x2000
	v_lshl_add_u64 v[178:179], v[212:213], 0, s[78:79]
	global_load_lds_dwordx4 v[178:179], off
	s_mov_b32 m0, s42
	v_lshl_add_u64 v[178:179], v[236:237], 0, s[78:79]
	s_waitcnt lgkmcnt(0)
	s_barrier
	v_mfma_f32_16x16x32_bf16 v[110:113], v[208:211], v[162:165], v[110:113]
	v_mfma_f32_16x16x32_bf16 v[106:109], v[228:231], v[162:165], v[106:109]
	v_mfma_f32_16x16x32_bf16 v[94:97], v[208:211], v[170:173], v[94:97]
	v_mfma_f32_16x16x32_bf16 v[90:93], v[228:231], v[170:173], v[90:93]
	v_mfma_f32_16x16x32_bf16 v[78:81], v[208:211], v[192:195], v[78:81]
	v_mfma_f32_16x16x32_bf16 v[74:77], v[228:231], v[192:195], v[74:77]
	v_mfma_f32_16x16x32_bf16 v[70:73], v[208:211], v[200:203], v[70:73]
	v_mfma_f32_16x16x32_bf16 v[66:69], v[228:231], v[200:203], v[66:69]
	v_mfma_f32_16x16x32_bf16 v[110:113], v[224:227], v[166:169], v[110:113]
	v_mfma_f32_16x16x32_bf16 v[106:109], v[232:235], v[166:169], v[106:109]
	v_mfma_f32_16x16x32_bf16 v[94:97], v[224:227], v[174:177], v[94:97]
	v_mfma_f32_16x16x32_bf16 v[90:93], v[232:235], v[174:177], v[90:93]
	v_mfma_f32_16x16x32_bf16 v[78:81], v[224:227], v[196:199], v[78:81]
	v_mfma_f32_16x16x32_bf16 v[74:77], v[232:235], v[196:199], v[74:77]
	v_mfma_f32_16x16x32_bf16 v[70:73], v[224:227], v[204:207], v[70:73]
	v_mfma_f32_16x16x32_bf16 v[66:69], v[232:235], v[204:207], v[66:69]
	s_barrier
	ds_read_b128 v[162:165], v144 offset:49152
	ds_read_b128 v[166:169], v144 offset:50176
	ds_read_b128 v[170:173], v144 offset:51200
	ds_read_b128 v[174:177], v144 offset:52224
	ds_read_b128 v[192:195], v144 offset:53248
	ds_read_b128 v[196:199], v144 offset:54272
	ds_read_b128 v[200:203], v144 offset:55296
	ds_read_b128 v[204:207], v144 offset:56320
	global_load_lds_dwordx4 v[178:179], off
	s_mov_b32 m0, s43
	v_lshl_add_u64 v[178:179], v[238:239], 0, s[78:79]
	global_load_lds_dwordx4 v[178:179], off
	s_waitcnt vmcnt(10)
	s_barrier
	s_waitcnt lgkmcnt(0)
	v_mfma_f32_16x16x32_bf16 v[62:65], v[146:149], v[162:165], v[62:65]
	v_mfma_f32_16x16x32_bf16 v[58:61], v[154:157], v[162:165], v[58:61]
	v_mfma_f32_16x16x32_bf16 v[54:57], v[146:149], v[170:173], v[54:57]
	v_mfma_f32_16x16x32_bf16 v[50:53], v[154:157], v[170:173], v[50:53]
	v_mfma_f32_16x16x32_bf16 v[38:41], v[146:149], v[192:195], v[38:41]
	v_mfma_f32_16x16x32_bf16 v[34:37], v[154:157], v[192:195], v[34:37]
	v_mfma_f32_16x16x32_bf16 v[22:25], v[146:149], v[200:203], v[22:25]
	v_mfma_f32_16x16x32_bf16 v[18:21], v[154:157], v[200:203], v[18:21]
	v_mfma_f32_16x16x32_bf16 v[62:65], v[150:153], v[166:169], v[62:65]
	v_mfma_f32_16x16x32_bf16 v[58:61], v[158:161], v[166:169], v[58:61]
	v_mfma_f32_16x16x32_bf16 v[54:57], v[150:153], v[174:177], v[54:57]
	v_mfma_f32_16x16x32_bf16 v[50:53], v[158:161], v[174:177], v[50:53]
	v_mfma_f32_16x16x32_bf16 v[38:41], v[150:153], v[196:199], v[38:41]
	v_mfma_f32_16x16x32_bf16 v[34:37], v[158:161], v[196:199], v[34:37]
	v_mfma_f32_16x16x32_bf16 v[22:25], v[150:153], v[204:207], v[22:25]
	v_mfma_f32_16x16x32_bf16 v[18:21], v[158:161], v[204:207], v[18:21]
	s_barrier
	s_add_u32 s22, s84, 0x20080
	s_addc_u32 s23, s85, 0
	s_add_i32 s52, s53, s26
	s_mov_b32 m0, s52
	v_lshl_add_u64 v[146:147], s[22:23], 0, v[134:135]
	global_load_lds_dwordx4 v[146:147], off
	s_add_i32 m0, s52, 0x2000
	v_lshl_add_u64 v[146:147], s[22:23], 0, v[130:131]
	global_load_lds_dwordx4 v[146:147], off
	v_add_u32_e32 v145, 0x10000, v142
	ds_read_b128 v[146:149], v145
	ds_read_b128 v[150:153], v145 offset:1024
	ds_read_b128 v[154:157], v145 offset:2048
	ds_read_b128 v[158:161], v145 offset:3072
	s_add_i32 s51, s51, 2
	s_add_u32 s20, s20, 0x100
	s_addc_u32 s21, s21, 0
	s_add_u32 s49, s49, 0x100
	s_addc_u32 s50, s50, 0
	s_cmp_gt_u32 s51, 5
	s_waitcnt vmcnt(6)
	s_barrier
	v_mfma_f32_16x16x32_bf16 v[46:49], v[208:211], v[162:165], v[46:49]
	v_mfma_f32_16x16x32_bf16 v[42:45], v[228:231], v[162:165], v[42:45]
	v_mfma_f32_16x16x32_bf16 v[30:33], v[208:211], v[170:173], v[30:33]
	v_mfma_f32_16x16x32_bf16 v[26:29], v[228:231], v[170:173], v[26:29]
	v_mfma_f32_16x16x32_bf16 v[14:17], v[208:211], v[192:195], v[14:17]
	v_mfma_f32_16x16x32_bf16 v[10:13], v[228:231], v[192:195], v[10:13]
	v_mfma_f32_16x16x32_bf16 v[6:9], v[208:211], v[200:203], v[6:9]
	v_mfma_f32_16x16x32_bf16 v[2:5], v[228:231], v[200:203], v[2:5]
	v_mfma_f32_16x16x32_bf16 v[46:49], v[224:227], v[166:169], v[46:49]
	v_mfma_f32_16x16x32_bf16 v[42:45], v[232:235], v[166:169], v[42:45]
	v_mfma_f32_16x16x32_bf16 v[30:33], v[224:227], v[174:177], v[30:33]
	v_mfma_f32_16x16x32_bf16 v[26:29], v[232:235], v[174:177], v[26:29]
	v_mfma_f32_16x16x32_bf16 v[14:17], v[224:227], v[196:199], v[14:17]
	v_mfma_f32_16x16x32_bf16 v[10:13], v[232:235], v[196:199], v[10:13]
	v_mfma_f32_16x16x32_bf16 v[6:9], v[224:227], v[204:207], v[6:9]
	v_mfma_f32_16x16x32_bf16 v[2:5], v[232:235], v[204:207], v[2:5]
	s_barrier
	s_cbranch_scc0 .LBB0_357
	s_waitcnt lgkmcnt(0)
	v_lshl_add_u32 v146, s46, 8, v1
	v_lshl_or_b32 v148, s45, 8, v143
	v_ashrrev_i32_e32 v147, 31, v146
	v_readlane_b32 s48, v254, 40
	v_ashrrev_i32_e32 v149, 31, v148
	v_lshlrev_b64 v[150:151], 12, v[146:147]
	v_readlane_b32 s60, v254, 52
	v_readlane_b32 s61, v254, 53
	v_lshlrev_b64 v[148:149], 1, v[148:149]
	s_mov_b32 s19, 0x80000
	v_lshl_add_u64 v[150:151], s[60:61], 0, v[150:151]
	v_lshl_add_u64 v[150:151], v[150:151], 0, v[148:149]
	s_mov_b64 s[20:21], 0x80000
	v_cvt_pk_bf16_f32 v62, v62, v63
	v_cvt_pk_bf16_f32 v63, v64, v65
	v_cvt_pk_bf16_f32 v64, v58, v59
	v_add_co_u32_e32 v58, vcc, s19, v150
	v_cvt_pk_bf16_f32 v70, v70, v71
	v_cvt_pk_bf16_f32 v71, v72, v73
	v_cvt_pk_bf16_f32 v72, v66, v67
	v_lshl_add_u64 v[66:67], v[150:151], 0, s[20:21]
	v_addc_co_u32_e32 v59, vcc, 0, v151, vcc
	v_cvt_pk_bf16_f32 v46, v46, v47
	v_cvt_pk_bf16_f32 v47, v48, v49
	v_cvt_pk_bf16_f32 v48, v42, v43
	v_cvt_pk_bf16_f32 v49, v44, v45
	s_mov_b32 s19, 0x90000
	v_cvt_pk_bf16_f32 v110, v110, v111
	v_cvt_pk_bf16_f32 v111, v112, v113
	v_cvt_pk_bf16_f32 v112, v106, v107
	v_or_b32_e32 v106, 16, v146
	global_store_dwordx4 v[66:67], v[46:49], off offset:256
	s_mov_b64 s[20:21], 0x90000
	v_ashrrev_i32_e32 v107, 31, v106
	v_add_co_u32_e32 v48, vcc, s19, v150
	v_cvt_pk_bf16_f32 v94, v94, v95
	v_cvt_pk_bf16_f32 v95, v96, v97
	v_cvt_pk_bf16_f32 v96, v90, v91
	v_or_b32_e32 v90, 32, v146
	v_lshl_add_u64 v[46:47], v[150:151], 0, s[20:21]
	v_addc_co_u32_e32 v49, vcc, 0, v151, vcc
	v_cvt_pk_bf16_f32 v30, v30, v31
	v_cvt_pk_bf16_f32 v31, v32, v33
	v_cvt_pk_bf16_f32 v32, v26, v27
	v_cvt_pk_bf16_f32 v33, v28, v29
	s_mov_b32 s19, 0xa0000
	v_lshlrev_b64 v[106:107], 12, v[106:107]
	v_ashrrev_i32_e32 v91, 31, v90
	v_cvt_pk_bf16_f32 v78, v78, v79
	v_cvt_pk_bf16_f32 v79, v80, v81
	v_cvt_pk_bf16_f32 v80, v74, v75
	v_or_b32_e32 v74, 48, v146
	global_store_dwordx4 v[46:47], v[30:33], off offset:256
	s_mov_b64 s[20:21], 0xa0000
	v_cvt_pk_bf16_f32 v113, v108, v109
	v_add_co_u32_e32 v32, vcc, s19, v150
	v_lshl_add_u64 v[106:107], s[60:61], 0, v[106:107]
	v_lshlrev_b64 v[90:91], 12, v[90:91]
	v_ashrrev_i32_e32 v75, 31, v74
	v_lshl_add_u64 v[30:31], v[150:151], 0, s[20:21]
	v_addc_co_u32_e32 v33, vcc, 0, v151, vcc
	v_cvt_pk_bf16_f32 v14, v14, v15
	v_cvt_pk_bf16_f32 v15, v16, v17
	v_cvt_pk_bf16_f32 v16, v10, v11
	v_cvt_pk_bf16_f32 v17, v12, v13
	s_mov_b32 s19, 0xb0000
	global_store_dwordx4 v[150:151], v[110:113], off offset:256
	v_cvt_pk_bf16_f32 v97, v92, v93
	v_lshl_add_u64 v[90:91], s[60:61], 0, v[90:91]
	v_lshl_add_u64 v[110:111], v[106:107], 0, v[148:149]
	v_lshlrev_b64 v[74:75], 12, v[74:75]
	global_store_dwordx4 v[30:31], v[14:17], off offset:256
	global_store_dwordx4 v[110:111], v[94:97], off offset:256
	v_cvt_pk_bf16_f32 v81, v76, v77
	v_add_co_u32_e32 v16, vcc, s19, v150
	v_lshl_add_u64 v[94:95], v[90:91], 0, v[148:149]
	v_lshl_add_u64 v[74:75], s[60:61], 0, v[74:75]
	s_mov_b64 s[20:21], 0xb0000
	v_addc_co_u32_e32 v17, vcc, 0, v151, vcc
	v_cvt_pk_bf16_f32 v126, v126, v127
	v_cvt_pk_bf16_f32 v127, v128, v129
	v_cvt_pk_bf16_f32 v128, v122, v123
	v_cvt_pk_bf16_f32 v129, v124, v125
	v_cvt_pk_bf16_f32 v106, v118, v119
	v_cvt_pk_bf16_f32 v107, v120, v121
	v_cvt_pk_bf16_f32 v108, v114, v115
	v_cvt_pk_bf16_f32 v109, v116, v117
	v_cvt_pk_bf16_f32 v90, v102, v103
	v_cvt_pk_bf16_f32 v91, v104, v105
	v_cvt_pk_bf16_f32 v92, v98, v99
	v_cvt_pk_bf16_f32 v93, v100, v101
	global_store_dwordx4 v[94:95], v[78:81], off offset:256
	v_cvt_pk_bf16_f32 v76, v82, v83
	v_cvt_pk_bf16_f32 v77, v84, v85
	v_lshl_add_u64 v[78:79], v[74:75], 0, v[148:149]
	v_cvt_pk_bf16_f32 v74, v86, v87
	v_cvt_pk_bf16_f32 v75, v88, v89
	v_cvt_pk_bf16_f32 v73, v68, v69
	v_cvt_pk_bf16_f32 v65, v60, v61
	v_cvt_pk_bf16_f32 v42, v54, v55
	v_cvt_pk_bf16_f32 v43, v56, v57
	v_cvt_pk_bf16_f32 v44, v50, v51
	v_cvt_pk_bf16_f32 v45, v52, v53
	v_cvt_pk_bf16_f32 v26, v38, v39
	v_cvt_pk_bf16_f32 v27, v40, v41
	v_cvt_pk_bf16_f32 v28, v34, v35
	v_cvt_pk_bf16_f32 v29, v36, v37
	v_lshl_add_u64 v[14:15], v[150:151], 0, s[20:21]
	v_cvt_pk_bf16_f32 v10, v22, v23
	v_cvt_pk_bf16_f32 v11, v24, v25
	v_cvt_pk_bf16_f32 v12, v18, v19
	v_cvt_pk_bf16_f32 v13, v20, v21
	v_cvt_pk_bf16_f32 v6, v6, v7
	v_cvt_pk_bf16_f32 v7, v8, v9
	v_cvt_pk_bf16_f32 v8, v2, v3
	v_cvt_pk_bf16_f32 v9, v4, v5
	s_and_b64 vcc, exec, s[38:39]
	s_mov_b32 s45, s18
	s_mov_b32 s46, s30
	s_mov_b64 s[22:23], s[82:83]
	s_mov_b64 s[20:21], s[80:81]
	s_mov_b32 s64, 0x800000
	s_movk_i32 s65, 0x1fff
	v_readlane_b32 s49, v254, 41
	v_readlane_b32 s50, v254, 42
	v_readlane_b32 s51, v254, 43
	v_readlane_b32 s52, v254, 44
	v_readlane_b32 s53, v254, 45
	v_readlane_b32 s54, v254, 46
	v_readlane_b32 s55, v254, 47
	v_readlane_b32 s56, v254, 48
	v_readlane_b32 s57, v254, 49
	v_readlane_b32 s58, v254, 50
	v_readlane_b32 s59, v254, 51
	v_readlane_b32 s62, v254, 54
	v_readlane_b32 s63, v254, 55
	global_store_dwordx4 v[150:151], v[126:129], off
	global_store_dwordx4 v[110:111], v[106:109], off
	global_store_dwordx4 v[94:95], v[90:93], off
	global_store_dwordx4 v[78:79], v[74:77], off
	global_store_dwordx4 v[78:79], v[70:73], off offset:256
	global_store_dwordx4 v[58:59], v[62:65], off
	global_store_dwordx4 v[48:49], v[42:45], off
	global_store_dwordx4 v[32:33], v[26:29], off
	global_store_dwordx4 v[16:17], v[10:13], off
	global_store_dwordx4 v[14:15], v[6:9], off offset:256
	s_cbranch_vccz .LBB0_350
	s_waitcnt vmcnt(0)
	v_readlane_b32 s44, v255, 30
	s_mov_b32 s66, s90
	s_cmpk_gt_u32 s25, 0xff
	v_readlane_b32 s45, v255, 31
	v_readlane_b32 s42, v255, 32
	s_cbranch_scc1 .LBB0_361
	s_barrier

.LBB0_373:
	s_add_u32 s22, s20, 0xfffe0080
	s_addc_u32 s23, s21, -1
	s_add_i32 s52, 0, 0x10000
	s_cmp_eq_u32 s51, 4
	s_cselect_b32 s23, s31, s23
	s_cselect_b32 s22, s47, s22
	s_cselect_b32 s83, s19, s50
	s_cselect_b32 s82, s48, s49
	v_lshl_add_u64 v[178:179], s[20:21], 0, v[138:139]
	s_add_i32 m0, s27, 0xc000
	ds_read_b128 v[162:165], v144
	ds_read_b128 v[166:169], v144 offset:1024
	ds_read_b128 v[170:173], v144 offset:2048
	ds_read_b128 v[174:177], v144 offset:3072
	ds_read_b128 v[192:195], v144 offset:4096
	ds_read_b128 v[196:199], v144 offset:5120
	ds_read_b128 v[200:203], v144 offset:6144
	ds_read_b128 v[204:207], v144 offset:7168
	global_load_lds_dwordx4 v[178:179], off
	s_add_i32 m0, s27, 0xe000
	v_lshl_add_u64 v[178:179], s[20:21], 0, v[140:141]
	global_load_lds_dwordx4 v[178:179], off
	s_barrier
	s_waitcnt lgkmcnt(0)
	v_mfma_f32_16x16x32_bf16 v[126:129], v[146:149], v[162:165], v[126:129]
	v_mfma_f32_16x16x32_bf16 v[122:125], v[154:157], v[162:165], v[122:125]
	v_mfma_f32_16x16x32_bf16 v[118:121], v[146:149], v[170:173], v[118:121]
	v_mfma_f32_16x16x32_bf16 v[114:117], v[154:157], v[170:173], v[114:117]
	v_mfma_f32_16x16x32_bf16 v[102:105], v[146:149], v[192:195], v[102:105]
	v_mfma_f32_16x16x32_bf16 v[98:101], v[154:157], v[192:195], v[98:101]
	v_mfma_f32_16x16x32_bf16 v[86:89], v[146:149], v[200:203], v[86:89]
	v_mfma_f32_16x16x32_bf16 v[82:85], v[154:157], v[200:203], v[82:85]
	v_mfma_f32_16x16x32_bf16 v[126:129], v[150:153], v[166:169], v[126:129]
	v_mfma_f32_16x16x32_bf16 v[122:125], v[158:161], v[166:169], v[122:125]
	v_mfma_f32_16x16x32_bf16 v[118:121], v[150:153], v[174:177], v[118:121]
	v_mfma_f32_16x16x32_bf16 v[114:117], v[158:161], v[174:177], v[114:117]
	v_mfma_f32_16x16x32_bf16 v[102:105], v[150:153], v[196:199], v[102:105]
	v_mfma_f32_16x16x32_bf16 v[98:101], v[158:161], v[196:199], v[98:101]
	v_mfma_f32_16x16x32_bf16 v[86:89], v[150:153], v[204:207], v[86:89]
	v_mfma_f32_16x16x32_bf16 v[82:85], v[158:161], v[204:207], v[82:85]
	s_barrier
	s_add_i32 s54, 0, 0x14000
	s_add_i32 s52, s52, s26
	v_add_u32_e32 v145, s54, v142
	v_lshl_add_u64 v[178:179], s[82:83], 0, v[134:135]
	s_mov_b32 m0, s52
	ds_read_b128 v[208:211], v145
	ds_read_b128 v[224:227], v145 offset:1024
	ds_read_b128 v[228:231], v145 offset:2048
	ds_read_b128 v[232:235], v145 offset:3072
	global_load_lds_dwordx4 v[178:179], off
	s_add_i32 m0, s52, 0x2000
	v_lshl_add_u64 v[212:213], s[82:83], 0, v[130:131]
	global_load_lds_dwordx4 v[212:213], off
	s_mov_b32 m0, s27
	v_lshl_add_u64 v[236:237], s[22:23], 0, v[136:137]
	s_waitcnt lgkmcnt(0)
	s_barrier
	v_mfma_f32_16x16x32_bf16 v[110:113], v[208:211], v[162:165], v[110:113]
	v_mfma_f32_16x16x32_bf16 v[106:109], v[228:231], v[162:165], v[106:109]
	v_mfma_f32_16x16x32_bf16 v[94:97], v[208:211], v[170:173], v[94:97]
	v_mfma_f32_16x16x32_bf16 v[90:93], v[228:231], v[170:173], v[90:93]
	v_mfma_f32_16x16x32_bf16 v[78:81], v[208:211], v[192:195], v[78:81]
	v_mfma_f32_16x16x32_bf16 v[74:77], v[228:231], v[192:195], v[74:77]
	v_mfma_f32_16x16x32_bf16 v[70:73], v[208:211], v[200:203], v[70:73]
	v_mfma_f32_16x16x32_bf16 v[66:69], v[228:231], v[200:203], v[66:69]
	v_mfma_f32_16x16x32_bf16 v[110:113], v[224:227], v[166:169], v[110:113]
	v_mfma_f32_16x16x32_bf16 v[106:109], v[232:235], v[166:169], v[106:109]
	v_mfma_f32_16x16x32_bf16 v[94:97], v[224:227], v[174:177], v[94:97]
	v_mfma_f32_16x16x32_bf16 v[90:93], v[232:235], v[174:177], v[90:93]
	v_mfma_f32_16x16x32_bf16 v[78:81], v[224:227], v[196:199], v[78:81]
	v_mfma_f32_16x16x32_bf16 v[74:77], v[232:235], v[196:199], v[74:77]
	v_mfma_f32_16x16x32_bf16 v[70:73], v[224:227], v[204:207], v[70:73]
	v_mfma_f32_16x16x32_bf16 v[66:69], v[232:235], v[204:207], v[66:69]
	s_barrier
	ds_read_b128 v[162:165], v144 offset:16384
	ds_read_b128 v[166:169], v144 offset:17408
	ds_read_b128 v[170:173], v144 offset:18432
	ds_read_b128 v[174:177], v144 offset:19456
	ds_read_b128 v[192:195], v144 offset:20480
	ds_read_b128 v[196:199], v144 offset:21504
	ds_read_b128 v[200:203], v144 offset:22528
	ds_read_b128 v[204:207], v144 offset:23552
	global_load_lds_dwordx4 v[236:237], off
	s_mov_b32 m0, s28
	v_lshl_add_u64 v[238:239], s[22:23], 0, v[132:133]
	global_load_lds_dwordx4 v[238:239], off
	s_waitcnt vmcnt(10)
	s_barrier
	s_waitcnt lgkmcnt(0)
	v_mfma_f32_16x16x32_bf16 v[62:65], v[146:149], v[162:165], v[62:65]
	v_mfma_f32_16x16x32_bf16 v[58:61], v[154:157], v[162:165], v[58:61]
	v_mfma_f32_16x16x32_bf16 v[54:57], v[146:149], v[170:173], v[54:57]
	v_mfma_f32_16x16x32_bf16 v[50:53], v[154:157], v[170:173], v[50:53]
	v_mfma_f32_16x16x32_bf16 v[38:41], v[146:149], v[192:195], v[38:41]
	v_mfma_f32_16x16x32_bf16 v[34:37], v[154:157], v[192:195], v[34:37]
	v_mfma_f32_16x16x32_bf16 v[22:25], v[146:149], v[200:203], v[22:25]
	v_mfma_f32_16x16x32_bf16 v[18:21], v[154:157], v[200:203], v[18:21]
	v_mfma_f32_16x16x32_bf16 v[62:65], v[150:153], v[166:169], v[62:65]
	v_mfma_f32_16x16x32_bf16 v[58:61], v[158:161], v[166:169], v[58:61]
	v_mfma_f32_16x16x32_bf16 v[54:57], v[150:153], v[174:177], v[54:57]
	v_mfma_f32_16x16x32_bf16 v[50:53], v[158:161], v[174:177], v[50:53]
	v_mfma_f32_16x16x32_bf16 v[38:41], v[150:153], v[196:199], v[38:41]
	v_mfma_f32_16x16x32_bf16 v[34:37], v[158:161], v[196:199], v[34:37]
	v_mfma_f32_16x16x32_bf16 v[22:25], v[150:153], v[204:207], v[22:25]
	v_mfma_f32_16x16x32_bf16 v[18:21], v[158:161], v[204:207], v[18:21]
	s_barrier
	s_add_u32 s52, s82, 0x20000
	s_addc_u32 s53, s83, 0
	s_add_i32 s54, s54, s26
	s_mov_b32 m0, s54
	v_lshl_add_u64 v[146:147], s[52:53], 0, v[134:135]
	global_load_lds_dwordx4 v[146:147], off
	s_add_i32 m0, s54, 0x2000
	v_lshl_add_u64 v[146:147], s[52:53], 0, v[130:131]
	global_load_lds_dwordx4 v[146:147], off
	v_add_u32_e32 v145, 0x18000, v142
	ds_read_b128 v[146:149], v145
	ds_read_b128 v[150:153], v145 offset:1024
	ds_read_b128 v[154:157], v145 offset:2048
	ds_read_b128 v[158:161], v145 offset:3072
	s_add_i32 s52, 0, 0x18000
	s_waitcnt vmcnt(6)
	s_barrier
	v_mfma_f32_16x16x32_bf16 v[46:49], v[208:211], v[162:165], v[46:49]
	v_mfma_f32_16x16x32_bf16 v[42:45], v[228:231], v[162:165], v[42:45]
	v_mfma_f32_16x16x32_bf16 v[30:33], v[208:211], v[170:173], v[30:33]
	v_mfma_f32_16x16x32_bf16 v[26:29], v[228:231], v[170:173], v[26:29]
	v_mfma_f32_16x16x32_bf16 v[14:17], v[208:211], v[192:195], v[14:17]
	v_mfma_f32_16x16x32_bf16 v[10:13], v[228:231], v[192:195], v[10:13]
	v_mfma_f32_16x16x32_bf16 v[6:9], v[208:211], v[200:203], v[6:9]
	v_mfma_f32_16x16x32_bf16 v[2:5], v[228:231], v[200:203], v[2:5]
	v_mfma_f32_16x16x32_bf16 v[46:49], v[224:227], v[166:169], v[46:49]
	v_mfma_f32_16x16x32_bf16 v[42:45], v[232:235], v[166:169], v[42:45]
	v_mfma_f32_16x16x32_bf16 v[30:33], v[224:227], v[174:177], v[30:33]
	v_mfma_f32_16x16x32_bf16 v[26:29], v[232:235], v[174:177], v[26:29]
	v_mfma_f32_16x16x32_bf16 v[14:17], v[224:227], v[196:199], v[14:17]
	v_mfma_f32_16x16x32_bf16 v[10:13], v[232:235], v[196:199], v[10:13]
	v_mfma_f32_16x16x32_bf16 v[6:9], v[224:227], v[204:207], v[6:9]
	v_mfma_f32_16x16x32_bf16 v[2:5], v[232:235], v[204:207], v[2:5]
	s_barrier
	s_add_u32 s22, s22, 0x20000
	s_addc_u32 s23, s23, 0
	s_mov_b32 m0, s29
	v_lshl_add_u64 v[208:209], s[22:23], 0, v[136:137]
	ds_read_b128 v[162:165], v144 offset:32768
	ds_read_b128 v[166:169], v144 offset:33792
	ds_read_b128 v[170:173], v144 offset:34816
	ds_read_b128 v[174:177], v144 offset:35840
	ds_read_b128 v[192:195], v144 offset:36864
	ds_read_b128 v[196:199], v144 offset:37888
	ds_read_b128 v[200:203], v144 offset:38912
	ds_read_b128 v[204:207], v144 offset:39936
	global_load_lds_dwordx4 v[208:209], off
	s_mov_b32 m0, s36
	v_lshl_add_u64 v[208:209], s[22:23], 0, v[132:133]
	global_load_lds_dwordx4 v[208:209], off
	s_barrier
	s_waitcnt lgkmcnt(0)
	v_mfma_f32_16x16x32_bf16 v[126:129], v[146:149], v[162:165], v[126:129]
	v_mfma_f32_16x16x32_bf16 v[122:125], v[154:157], v[162:165], v[122:125]
	v_mfma_f32_16x16x32_bf16 v[118:121], v[146:149], v[170:173], v[118:121]
	v_mfma_f32_16x16x32_bf16 v[114:117], v[154:157], v[170:173], v[114:117]
	v_mfma_f32_16x16x32_bf16 v[102:105], v[146:149], v[192:195], v[102:105]
	v_mfma_f32_16x16x32_bf16 v[98:101], v[154:157], v[192:195], v[98:101]
	v_mfma_f32_16x16x32_bf16 v[86:89], v[146:149], v[200:203], v[86:89]
	v_mfma_f32_16x16x32_bf16 v[82:85], v[154:157], v[200:203], v[82:85]
	v_mfma_f32_16x16x32_bf16 v[126:129], v[150:153], v[166:169], v[126:129]
	v_mfma_f32_16x16x32_bf16 v[122:125], v[158:161], v[166:169], v[122:125]
	v_mfma_f32_16x16x32_bf16 v[118:121], v[150:153], v[174:177], v[118:121]
	v_mfma_f32_16x16x32_bf16 v[114:117], v[158:161], v[174:177], v[114:117]
	v_mfma_f32_16x16x32_bf16 v[102:105], v[150:153], v[196:199], v[102:105]
	v_mfma_f32_16x16x32_bf16 v[98:101], v[158:161], v[196:199], v[98:101]
	v_mfma_f32_16x16x32_bf16 v[86:89], v[150:153], v[204:207], v[86:89]
	v_mfma_f32_16x16x32_bf16 v[82:85], v[158:161], v[204:207], v[82:85]
	s_barrier
	s_add_i32 s53, 0, 0x1c000
	s_add_i32 s22, s52, s26
	v_add_u32_e32 v145, s53, v142
	v_lshl_add_u64 v[178:179], v[178:179], 0, s[78:79]
	s_mov_b32 m0, s22
	ds_read_b128 v[208:211], v145
	ds_read_b128 v[224:227], v145 offset:1024
	ds_read_b128 v[228:231], v145 offset:2048
	ds_read_b128 v[232:235], v145 offset:3072
	global_load_lds_dwordx4 v[178:179], off
	s_add_i32 m0, s22, 0x2000
	v_lshl_add_u64 v[178:179], v[212:213], 0, s[78:79]
	global_load_lds_dwordx4 v[178:179], off
	s_mov_b32 m0, s42
	v_lshl_add_u64 v[178:179], v[236:237], 0, s[78:79]
	s_waitcnt lgkmcnt(0)
	s_barrier
	v_mfma_f32_16x16x32_bf16 v[110:113], v[208:211], v[162:165], v[110:113]
	v_mfma_f32_16x16x32_bf16 v[106:109], v[228:231], v[162:165], v[106:109]
	v_mfma_f32_16x16x32_bf16 v[94:97], v[208:211], v[170:173], v[94:97]
	v_mfma_f32_16x16x32_bf16 v[90:93], v[228:231], v[170:173], v[90:93]
	v_mfma_f32_16x16x32_bf16 v[78:81], v[208:211], v[192:195], v[78:81]
	v_mfma_f32_16x16x32_bf16 v[74:77], v[228:231], v[192:195], v[74:77]
	v_mfma_f32_16x16x32_bf16 v[70:73], v[208:211], v[200:203], v[70:73]
	v_mfma_f32_16x16x32_bf16 v[66:69], v[228:231], v[200:203], v[66:69]
	v_mfma_f32_16x16x32_bf16 v[110:113], v[224:227], v[166:169], v[110:113]
	v_mfma_f32_16x16x32_bf16 v[106:109], v[232:235], v[166:169], v[106:109]
	v_mfma_f32_16x16x32_bf16 v[94:97], v[224:227], v[174:177], v[94:97]
	v_mfma_f32_16x16x32_bf16 v[90:93], v[232:235], v[174:177], v[90:93]
	v_mfma_f32_16x16x32_bf16 v[78:81], v[224:227], v[196:199], v[78:81]
	v_mfma_f32_16x16x32_bf16 v[74:77], v[232:235], v[196:199], v[74:77]
	v_mfma_f32_16x16x32_bf16 v[70:73], v[224:227], v[204:207], v[70:73]
	v_mfma_f32_16x16x32_bf16 v[66:69], v[232:235], v[204:207], v[66:69]
	s_barrier
	ds_read_b128 v[162:165], v144 offset:49152
	ds_read_b128 v[166:169], v144 offset:50176
	ds_read_b128 v[170:173], v144 offset:51200
	ds_read_b128 v[174:177], v144 offset:52224
	ds_read_b128 v[192:195], v144 offset:53248
	ds_read_b128 v[196:199], v144 offset:54272
	ds_read_b128 v[200:203], v144 offset:55296
	ds_read_b128 v[204:207], v144 offset:56320
	global_load_lds_dwordx4 v[178:179], off
	s_mov_b32 m0, s43
	v_lshl_add_u64 v[178:179], v[238:239], 0, s[78:79]
	global_load_lds_dwordx4 v[178:179], off
	s_waitcnt vmcnt(10)
	s_barrier
	s_waitcnt lgkmcnt(0)
	v_mfma_f32_16x16x32_bf16 v[62:65], v[146:149], v[162:165], v[62:65]
	v_mfma_f32_16x16x32_bf16 v[58:61], v[154:157], v[162:165], v[58:61]
	v_mfma_f32_16x16x32_bf16 v[54:57], v[146:149], v[170:173], v[54:57]
	v_mfma_f32_16x16x32_bf16 v[50:53], v[154:157], v[170:173], v[50:53]
	v_mfma_f32_16x16x32_bf16 v[38:41], v[146:149], v[192:195], v[38:41]
	v_mfma_f32_16x16x32_bf16 v[34:37], v[154:157], v[192:195], v[34:37]
	v_mfma_f32_16x16x32_bf16 v[22:25], v[146:149], v[200:203], v[22:25]
	v_mfma_f32_16x16x32_bf16 v[18:21], v[154:157], v[200:203], v[18:21]
	v_mfma_f32_16x16x32_bf16 v[62:65], v[150:153], v[166:169], v[62:65]
	v_mfma_f32_16x16x32_bf16 v[58:61], v[158:161], v[166:169], v[58:61]
	v_mfma_f32_16x16x32_bf16 v[54:57], v[150:153], v[174:177], v[54:57]
	v_mfma_f32_16x16x32_bf16 v[50:53], v[158:161], v[174:177], v[50:53]
	v_mfma_f32_16x16x32_bf16 v[38:41], v[150:153], v[196:199], v[38:41]
	v_mfma_f32_16x16x32_bf16 v[34:37], v[158:161], v[196:199], v[34:37]
	v_mfma_f32_16x16x32_bf16 v[22:25], v[150:153], v[204:207], v[22:25]
	v_mfma_f32_16x16x32_bf16 v[18:21], v[158:161], v[204:207], v[18:21]
	s_barrier
	s_add_u32 s22, s82, 0x20080
	s_addc_u32 s23, s83, 0
	s_add_i32 s52, s53, s26
	s_mov_b32 m0, s52
	v_lshl_add_u64 v[146:147], s[22:23], 0, v[134:135]
	global_load_lds_dwordx4 v[146:147], off
	s_add_i32 m0, s52, 0x2000
	v_lshl_add_u64 v[146:147], s[22:23], 0, v[130:131]
	global_load_lds_dwordx4 v[146:147], off
	v_add_u32_e32 v145, 0x10000, v142
	ds_read_b128 v[146:149], v145
	ds_read_b128 v[150:153], v145 offset:1024
	ds_read_b128 v[154:157], v145 offset:2048
	ds_read_b128 v[158:161], v145 offset:3072
	s_add_i32 s51, s51, 2
	s_add_u32 s20, s20, 0x100
	s_addc_u32 s21, s21, 0
	s_add_u32 s49, s49, 0x100
	s_addc_u32 s50, s50, 0
	s_cmp_gt_u32 s51, 5
	s_waitcnt vmcnt(6)
	s_barrier
	v_mfma_f32_16x16x32_bf16 v[46:49], v[208:211], v[162:165], v[46:49]
	v_mfma_f32_16x16x32_bf16 v[42:45], v[228:231], v[162:165], v[42:45]
	v_mfma_f32_16x16x32_bf16 v[30:33], v[208:211], v[170:173], v[30:33]
	v_mfma_f32_16x16x32_bf16 v[26:29], v[228:231], v[170:173], v[26:29]
	v_mfma_f32_16x16x32_bf16 v[14:17], v[208:211], v[192:195], v[14:17]
	v_mfma_f32_16x16x32_bf16 v[10:13], v[228:231], v[192:195], v[10:13]
	v_mfma_f32_16x16x32_bf16 v[6:9], v[208:211], v[200:203], v[6:9]
	v_mfma_f32_16x16x32_bf16 v[2:5], v[228:231], v[200:203], v[2:5]
	v_mfma_f32_16x16x32_bf16 v[46:49], v[224:227], v[166:169], v[46:49]
	v_mfma_f32_16x16x32_bf16 v[42:45], v[232:235], v[166:169], v[42:45]
	v_mfma_f32_16x16x32_bf16 v[30:33], v[224:227], v[174:177], v[30:33]
	v_mfma_f32_16x16x32_bf16 v[26:29], v[232:235], v[174:177], v[26:29]
	v_mfma_f32_16x16x32_bf16 v[14:17], v[224:227], v[196:199], v[14:17]
	v_mfma_f32_16x16x32_bf16 v[10:13], v[232:235], v[196:199], v[10:13]
	v_mfma_f32_16x16x32_bf16 v[6:9], v[224:227], v[204:207], v[6:9]
	v_mfma_f32_16x16x32_bf16 v[2:5], v[232:235], v[204:207], v[2:5]
	s_barrier
	s_cbranch_scc0 .LBB0_373
	s_waitcnt lgkmcnt(0)
	v_lshl_add_u32 v146, s46, 8, v1
	v_lshl_or_b32 v148, s45, 8, v143
	v_ashrrev_i32_e32 v147, 31, v146
	v_readlane_b32 s48, v254, 40
	v_ashrrev_i32_e32 v149, 31, v148
	v_lshlrev_b64 v[150:151], 14, v[146:147]
	v_readlane_b32 s62, v254, 54
	v_readlane_b32 s63, v254, 55
	v_lshlrev_b64 v[148:149], 1, v[148:149]
	s_mov_b32 s19, 0x200000
	v_lshl_add_u64 v[150:151], s[62:63], 0, v[150:151]
	v_lshl_add_u64 v[150:151], v[150:151], 0, v[148:149]
	s_mov_b64 s[20:21], 0x200000
	v_cvt_pk_bf16_f32 v62, v62, v63
	v_cvt_pk_bf16_f32 v63, v64, v65
	v_cvt_pk_bf16_f32 v64, v58, v59
	v_add_co_u32_e32 v58, vcc, s19, v150
	v_cvt_pk_bf16_f32 v70, v70, v71
	v_cvt_pk_bf16_f32 v71, v72, v73
	v_cvt_pk_bf16_f32 v72, v66, v67
	v_lshl_add_u64 v[66:67], v[150:151], 0, s[20:21]
	v_addc_co_u32_e32 v59, vcc, 0, v151, vcc
	v_cvt_pk_bf16_f32 v46, v46, v47
	v_cvt_pk_bf16_f32 v47, v48, v49
	v_cvt_pk_bf16_f32 v48, v42, v43
	v_cvt_pk_bf16_f32 v49, v44, v45
	s_mov_b32 s19, 0x240000
	v_cvt_pk_bf16_f32 v110, v110, v111
	v_cvt_pk_bf16_f32 v111, v112, v113
	v_cvt_pk_bf16_f32 v112, v106, v107
	v_or_b32_e32 v106, 16, v146
	global_store_dwordx4 v[66:67], v[46:49], off offset:256
	s_mov_b64 s[20:21], 0x240000
	v_ashrrev_i32_e32 v107, 31, v106
	v_add_co_u32_e32 v48, vcc, s19, v150
	v_cvt_pk_bf16_f32 v94, v94, v95
	v_cvt_pk_bf16_f32 v95, v96, v97
	v_cvt_pk_bf16_f32 v96, v90, v91
	v_or_b32_e32 v90, 32, v146
	v_lshl_add_u64 v[46:47], v[150:151], 0, s[20:21]
	v_addc_co_u32_e32 v49, vcc, 0, v151, vcc
	v_cvt_pk_bf16_f32 v30, v30, v31
	v_cvt_pk_bf16_f32 v31, v32, v33
	v_cvt_pk_bf16_f32 v32, v26, v27
	v_cvt_pk_bf16_f32 v33, v28, v29
	s_mov_b32 s19, 0x280000
	v_lshlrev_b64 v[106:107], 14, v[106:107]
	v_ashrrev_i32_e32 v91, 31, v90
	v_cvt_pk_bf16_f32 v78, v78, v79
	v_cvt_pk_bf16_f32 v79, v80, v81
	v_cvt_pk_bf16_f32 v80, v74, v75
	v_or_b32_e32 v74, 48, v146
	global_store_dwordx4 v[46:47], v[30:33], off offset:256
	s_mov_b64 s[20:21], 0x280000
	v_cvt_pk_bf16_f32 v113, v108, v109
	v_add_co_u32_e32 v32, vcc, s19, v150
	v_lshl_add_u64 v[106:107], s[62:63], 0, v[106:107]
	v_lshlrev_b64 v[90:91], 14, v[90:91]
	v_ashrrev_i32_e32 v75, 31, v74
	v_lshl_add_u64 v[30:31], v[150:151], 0, s[20:21]
	v_addc_co_u32_e32 v33, vcc, 0, v151, vcc
	v_cvt_pk_bf16_f32 v14, v14, v15
	v_cvt_pk_bf16_f32 v15, v16, v17
	v_cvt_pk_bf16_f32 v16, v10, v11
	v_cvt_pk_bf16_f32 v17, v12, v13
	s_mov_b32 s19, 0x2c0000
	global_store_dwordx4 v[150:151], v[110:113], off offset:256
	v_cvt_pk_bf16_f32 v97, v92, v93
	v_lshl_add_u64 v[90:91], s[62:63], 0, v[90:91]
	v_lshl_add_u64 v[110:111], v[106:107], 0, v[148:149]
	v_lshlrev_b64 v[74:75], 14, v[74:75]
	global_store_dwordx4 v[30:31], v[14:17], off offset:256
	global_store_dwordx4 v[110:111], v[94:97], off offset:256
	v_cvt_pk_bf16_f32 v81, v76, v77
	v_add_co_u32_e32 v16, vcc, s19, v150
	v_lshl_add_u64 v[94:95], v[90:91], 0, v[148:149]
	v_lshl_add_u64 v[74:75], s[62:63], 0, v[74:75]
	s_mov_b64 s[20:21], 0x2c0000
	v_addc_co_u32_e32 v17, vcc, 0, v151, vcc
	v_cvt_pk_bf16_f32 v126, v126, v127
	v_cvt_pk_bf16_f32 v127, v128, v129
	v_cvt_pk_bf16_f32 v128, v122, v123
	v_cvt_pk_bf16_f32 v129, v124, v125
	v_cvt_pk_bf16_f32 v106, v118, v119
	v_cvt_pk_bf16_f32 v107, v120, v121
	v_cvt_pk_bf16_f32 v108, v114, v115
	v_cvt_pk_bf16_f32 v109, v116, v117
	v_cvt_pk_bf16_f32 v90, v102, v103
	v_cvt_pk_bf16_f32 v91, v104, v105
	v_cvt_pk_bf16_f32 v92, v98, v99
	v_cvt_pk_bf16_f32 v93, v100, v101
	global_store_dwordx4 v[94:95], v[78:81], off offset:256
	v_cvt_pk_bf16_f32 v76, v82, v83
	v_cvt_pk_bf16_f32 v77, v84, v85
	v_lshl_add_u64 v[78:79], v[74:75], 0, v[148:149]
	v_cvt_pk_bf16_f32 v74, v86, v87
	v_cvt_pk_bf16_f32 v75, v88, v89
	v_cvt_pk_bf16_f32 v73, v68, v69
	v_cvt_pk_bf16_f32 v65, v60, v61
	v_cvt_pk_bf16_f32 v42, v54, v55
	v_cvt_pk_bf16_f32 v43, v56, v57
	v_cvt_pk_bf16_f32 v44, v50, v51
	v_cvt_pk_bf16_f32 v45, v52, v53
	v_cvt_pk_bf16_f32 v26, v38, v39
	v_cvt_pk_bf16_f32 v27, v40, v41
	v_cvt_pk_bf16_f32 v28, v34, v35
	v_cvt_pk_bf16_f32 v29, v36, v37
	v_lshl_add_u64 v[14:15], v[150:151], 0, s[20:21]
	v_cvt_pk_bf16_f32 v10, v22, v23
	v_cvt_pk_bf16_f32 v11, v24, v25
	v_cvt_pk_bf16_f32 v12, v18, v19
	v_cvt_pk_bf16_f32 v13, v20, v21
	v_cvt_pk_bf16_f32 v6, v6, v7
	v_cvt_pk_bf16_f32 v7, v8, v9
	v_cvt_pk_bf16_f32 v8, v2, v3
	v_cvt_pk_bf16_f32 v9, v4, v5
	s_and_b64 vcc, exec, s[0:1]
	s_mov_b32 s45, s18
	s_mov_b32 s46, s30
	s_mov_b64 s[22:23], s[80:81]
	s_mov_b64 s[20:21], s[38:39]
	s_mov_b32 s64, 0x800000
	s_movk_i32 s65, 0x1fff
	v_readlane_b32 s49, v254, 41
	v_readlane_b32 s50, v254, 42
	v_readlane_b32 s51, v254, 43
	v_readlane_b32 s52, v254, 44
	v_readlane_b32 s53, v254, 45
	v_readlane_b32 s54, v254, 46
	v_readlane_b32 s55, v254, 47
	v_readlane_b32 s56, v254, 48
	v_readlane_b32 s57, v254, 49
	v_readlane_b32 s58, v254, 50
	v_readlane_b32 s59, v254, 51
	v_readlane_b32 s60, v254, 52
	v_readlane_b32 s61, v254, 53
	global_store_dwordx4 v[150:151], v[126:129], off
	global_store_dwordx4 v[110:111], v[106:109], off
	global_store_dwordx4 v[94:95], v[90:93], off
	global_store_dwordx4 v[78:79], v[74:77], off
	global_store_dwordx4 v[78:79], v[70:73], off offset:256
	global_store_dwordx4 v[58:59], v[62:65], off
	global_store_dwordx4 v[48:49], v[42:45], off
	global_store_dwordx4 v[32:33], v[26:29], off
	global_store_dwordx4 v[16:17], v[10:13], off
	global_store_dwordx4 v[14:15], v[6:9], off offset:256
	s_cbranch_vccz .LBB0_366
	s_waitcnt vmcnt(0)
	v_readlane_b32 s44, v255, 30
	s_mov_b32 s66, s90
	s_cmpk_gt_u32 s25, 0xff
	v_readlane_b32 s45, v255, 31
	v_readlane_b32 s42, v255, 32
	s_cbranch_scc1 .LBB0_377
	s_barrier

.LBB0_386:
	s_add_u32 s20, s18, 0xfffe0080
	s_addc_u32 s21, s19, -1
	s_add_i32 s50, 0, 0x10000
	s_cmp_eq_u32 s49, 4
	s_cselect_b32 s23, s44, s21
	s_cselect_b32 s22, s45, s20
	s_cselect_b32 s21, s39, s48
	s_cselect_b32 s20, s46, s47
	v_lshl_add_u64 v[178:179], s[18:19], 0, v[146:147]
	s_add_i32 m0, s90, 0xc000
	ds_read_b128 v[162:165], v156
	ds_read_b128 v[166:169], v156 offset:1024
	ds_read_b128 v[170:173], v156 offset:2048
	ds_read_b128 v[174:177], v156 offset:3072
	ds_read_b128 v[192:195], v156 offset:4096
	ds_read_b128 v[196:199], v156 offset:5120
	ds_read_b128 v[200:203], v156 offset:6144
	ds_read_b128 v[204:207], v156 offset:7168
	global_load_lds_dwordx4 v[178:179], off
	s_add_i32 m0, s90, 0xe000
	v_lshl_add_u64 v[178:179], s[18:19], 0, v[148:149]
	global_load_lds_dwordx4 v[178:179], off
	s_barrier
	s_waitcnt lgkmcnt(0)
	v_mfma_f32_16x16x32_bf16 v[126:129], v[130:133], v[162:165], v[126:129]
	v_mfma_f32_16x16x32_bf16 v[122:125], v[150:153], v[162:165], v[122:125]
	v_mfma_f32_16x16x32_bf16 v[118:121], v[130:133], v[170:173], v[118:121]
	v_mfma_f32_16x16x32_bf16 v[110:113], v[150:153], v[170:173], v[110:113]
	v_mfma_f32_16x16x32_bf16 v[102:105], v[130:133], v[192:195], v[102:105]
	v_mfma_f32_16x16x32_bf16 v[94:97], v[150:153], v[192:195], v[94:97]
	v_mfma_f32_16x16x32_bf16 v[86:89], v[130:133], v[200:203], v[86:89]
	v_mfma_f32_16x16x32_bf16 v[78:81], v[150:153], v[200:203], v[78:81]
	v_mfma_f32_16x16x32_bf16 v[126:129], v[134:137], v[166:169], v[126:129]
	v_mfma_f32_16x16x32_bf16 v[122:125], v[158:161], v[166:169], v[122:125]
	v_mfma_f32_16x16x32_bf16 v[118:121], v[134:137], v[174:177], v[118:121]
	v_mfma_f32_16x16x32_bf16 v[110:113], v[158:161], v[174:177], v[110:113]
	v_mfma_f32_16x16x32_bf16 v[102:105], v[134:137], v[196:199], v[102:105]
	v_mfma_f32_16x16x32_bf16 v[94:97], v[158:161], v[196:199], v[94:97]
	v_mfma_f32_16x16x32_bf16 v[86:89], v[134:137], v[204:207], v[86:89]
	v_mfma_f32_16x16x32_bf16 v[78:81], v[158:161], v[204:207], v[78:81]
	s_barrier
	s_add_i32 s52, 0, 0x14000
	s_add_i32 s50, s50, s36
	v_add_u32_e32 v157, s52, v154
	v_lshl_add_u64 v[178:179], s[20:21], 0, v[142:143]
	s_mov_b32 m0, s50
	ds_read_b128 v[208:211], v157
	ds_read_b128 v[224:227], v157 offset:1024
	ds_read_b128 v[228:231], v157 offset:2048
	ds_read_b128 v[232:235], v157 offset:3072
	global_load_lds_dwordx4 v[178:179], off
	s_add_i32 m0, s50, 0x2000
	v_lshl_add_u64 v[212:213], s[20:21], 0, v[138:139]
	global_load_lds_dwordx4 v[212:213], off
	s_mov_b32 m0, s90
	v_lshl_add_u64 v[236:237], s[22:23], 0, v[144:145]
	s_waitcnt lgkmcnt(0)
	s_barrier
	v_mfma_f32_16x16x32_bf16 v[114:117], v[208:211], v[162:165], v[114:117]
	v_mfma_f32_16x16x32_bf16 v[106:109], v[228:231], v[162:165], v[106:109]
	v_mfma_f32_16x16x32_bf16 v[98:101], v[208:211], v[170:173], v[98:101]
	v_mfma_f32_16x16x32_bf16 v[90:93], v[228:231], v[170:173], v[90:93]
	v_mfma_f32_16x16x32_bf16 v[82:85], v[208:211], v[192:195], v[82:85]
	v_mfma_f32_16x16x32_bf16 v[74:77], v[228:231], v[192:195], v[74:77]
	v_mfma_f32_16x16x32_bf16 v[70:73], v[208:211], v[200:203], v[70:73]
	v_mfma_f32_16x16x32_bf16 v[66:69], v[228:231], v[200:203], v[66:69]
	v_mfma_f32_16x16x32_bf16 v[114:117], v[224:227], v[166:169], v[114:117]
	v_mfma_f32_16x16x32_bf16 v[106:109], v[232:235], v[166:169], v[106:109]
	v_mfma_f32_16x16x32_bf16 v[98:101], v[224:227], v[174:177], v[98:101]
	v_mfma_f32_16x16x32_bf16 v[90:93], v[232:235], v[174:177], v[90:93]
	v_mfma_f32_16x16x32_bf16 v[82:85], v[224:227], v[196:199], v[82:85]
	v_mfma_f32_16x16x32_bf16 v[74:77], v[232:235], v[196:199], v[74:77]
	v_mfma_f32_16x16x32_bf16 v[70:73], v[224:227], v[204:207], v[70:73]
	v_mfma_f32_16x16x32_bf16 v[66:69], v[232:235], v[204:207], v[66:69]
	s_barrier
	ds_read_b128 v[162:165], v156 offset:16384
	ds_read_b128 v[166:169], v156 offset:17408
	ds_read_b128 v[170:173], v156 offset:18432
	ds_read_b128 v[174:177], v156 offset:19456
	ds_read_b128 v[192:195], v156 offset:20480
	ds_read_b128 v[196:199], v156 offset:21504
	ds_read_b128 v[200:203], v156 offset:22528
	ds_read_b128 v[204:207], v156 offset:23552
	global_load_lds_dwordx4 v[236:237], off
	s_mov_b32 m0, s91
	v_lshl_add_u64 v[238:239], s[22:23], 0, v[140:141]
	global_load_lds_dwordx4 v[238:239], off
	s_waitcnt vmcnt(10)
	s_barrier
	s_waitcnt lgkmcnt(0)
	v_mfma_f32_16x16x32_bf16 v[62:65], v[130:133], v[162:165], v[62:65]
	v_mfma_f32_16x16x32_bf16 v[58:61], v[150:153], v[162:165], v[58:61]
	v_mfma_f32_16x16x32_bf16 v[54:57], v[130:133], v[170:173], v[54:57]
	v_mfma_f32_16x16x32_bf16 v[46:49], v[150:153], v[170:173], v[46:49]
	v_mfma_f32_16x16x32_bf16 v[38:41], v[130:133], v[192:195], v[38:41]
	v_mfma_f32_16x16x32_bf16 v[30:33], v[150:153], v[192:195], v[30:33]
	v_mfma_f32_16x16x32_bf16 v[22:25], v[130:133], v[200:203], v[22:25]
	v_mfma_f32_16x16x32_bf16 v[14:17], v[150:153], v[200:203], v[14:17]
	v_mfma_f32_16x16x32_bf16 v[62:65], v[134:137], v[166:169], v[62:65]
	v_mfma_f32_16x16x32_bf16 v[58:61], v[158:161], v[166:169], v[58:61]
	v_mfma_f32_16x16x32_bf16 v[54:57], v[134:137], v[174:177], v[54:57]
	v_mfma_f32_16x16x32_bf16 v[46:49], v[158:161], v[174:177], v[46:49]
	v_mfma_f32_16x16x32_bf16 v[38:41], v[134:137], v[196:199], v[38:41]
	v_mfma_f32_16x16x32_bf16 v[30:33], v[158:161], v[196:199], v[30:33]
	v_mfma_f32_16x16x32_bf16 v[22:25], v[134:137], v[204:207], v[22:25]
	v_mfma_f32_16x16x32_bf16 v[14:17], v[158:161], v[204:207], v[14:17]
	s_barrier
	s_add_u32 s50, s20, 0x20000
	s_addc_u32 s51, s21, 0
	s_add_i32 s52, s52, s36
	s_mov_b32 m0, s52
	v_lshl_add_u64 v[130:131], s[50:51], 0, v[142:143]
	global_load_lds_dwordx4 v[130:131], off
	s_add_i32 m0, s52, 0x2000
	v_lshl_add_u64 v[130:131], s[50:51], 0, v[138:139]
	global_load_lds_dwordx4 v[130:131], off
	v_add_u32_e32 v157, 0x18000, v154
	ds_read_b128 v[130:133], v157
	ds_read_b128 v[134:137], v157 offset:1024
	ds_read_b128 v[150:153], v157 offset:2048
	ds_read_b128 v[158:161], v157 offset:3072
	s_add_i32 s50, 0, 0x18000
	s_waitcnt vmcnt(6)
	s_barrier
	v_mfma_f32_16x16x32_bf16 v[50:53], v[208:211], v[162:165], v[50:53]
	v_mfma_f32_16x16x32_bf16 v[42:45], v[228:231], v[162:165], v[42:45]
	v_mfma_f32_16x16x32_bf16 v[34:37], v[208:211], v[170:173], v[34:37]
	v_mfma_f32_16x16x32_bf16 v[26:29], v[228:231], v[170:173], v[26:29]
	v_mfma_f32_16x16x32_bf16 v[18:21], v[208:211], v[192:195], v[18:21]
	v_mfma_f32_16x16x32_bf16 v[10:13], v[228:231], v[192:195], v[10:13]
	v_mfma_f32_16x16x32_bf16 v[6:9], v[208:211], v[200:203], v[6:9]
	v_mfma_f32_16x16x32_bf16 v[2:5], v[228:231], v[200:203], v[2:5]
	v_mfma_f32_16x16x32_bf16 v[50:53], v[224:227], v[166:169], v[50:53]
	v_mfma_f32_16x16x32_bf16 v[42:45], v[232:235], v[166:169], v[42:45]
	v_mfma_f32_16x16x32_bf16 v[34:37], v[224:227], v[174:177], v[34:37]
	v_mfma_f32_16x16x32_bf16 v[26:29], v[232:235], v[174:177], v[26:29]
	v_mfma_f32_16x16x32_bf16 v[18:21], v[224:227], v[196:199], v[18:21]
	v_mfma_f32_16x16x32_bf16 v[10:13], v[232:235], v[196:199], v[10:13]
	v_mfma_f32_16x16x32_bf16 v[6:9], v[224:227], v[204:207], v[6:9]
	v_mfma_f32_16x16x32_bf16 v[2:5], v[232:235], v[204:207], v[2:5]
	s_barrier
	s_add_u32 s22, s22, 0x20000
	s_addc_u32 s23, s23, 0
	s_mov_b32 m0, s42
	v_lshl_add_u64 v[208:209], s[22:23], 0, v[144:145]
	ds_read_b128 v[162:165], v156 offset:32768
	ds_read_b128 v[166:169], v156 offset:33792
	ds_read_b128 v[170:173], v156 offset:34816
	ds_read_b128 v[174:177], v156 offset:35840
	ds_read_b128 v[192:195], v156 offset:36864
	ds_read_b128 v[196:199], v156 offset:37888
	ds_read_b128 v[200:203], v156 offset:38912
	ds_read_b128 v[204:207], v156 offset:39936
	global_load_lds_dwordx4 v[208:209], off
	s_mov_b32 m0, s43
	v_lshl_add_u64 v[208:209], s[22:23], 0, v[140:141]
	global_load_lds_dwordx4 v[208:209], off
	s_barrier
	s_waitcnt lgkmcnt(0)
	v_mfma_f32_16x16x32_bf16 v[126:129], v[130:133], v[162:165], v[126:129]
	v_mfma_f32_16x16x32_bf16 v[122:125], v[150:153], v[162:165], v[122:125]
	v_mfma_f32_16x16x32_bf16 v[118:121], v[130:133], v[170:173], v[118:121]
	v_mfma_f32_16x16x32_bf16 v[110:113], v[150:153], v[170:173], v[110:113]
	v_mfma_f32_16x16x32_bf16 v[102:105], v[130:133], v[192:195], v[102:105]
	v_mfma_f32_16x16x32_bf16 v[94:97], v[150:153], v[192:195], v[94:97]
	v_mfma_f32_16x16x32_bf16 v[86:89], v[130:133], v[200:203], v[86:89]
	v_mfma_f32_16x16x32_bf16 v[78:81], v[150:153], v[200:203], v[78:81]
	v_mfma_f32_16x16x32_bf16 v[126:129], v[134:137], v[166:169], v[126:129]
	v_mfma_f32_16x16x32_bf16 v[122:125], v[158:161], v[166:169], v[122:125]
	v_mfma_f32_16x16x32_bf16 v[118:121], v[134:137], v[174:177], v[118:121]
	v_mfma_f32_16x16x32_bf16 v[110:113], v[158:161], v[174:177], v[110:113]
	v_mfma_f32_16x16x32_bf16 v[102:105], v[134:137], v[196:199], v[102:105]
	v_mfma_f32_16x16x32_bf16 v[94:97], v[158:161], v[196:199], v[94:97]
	v_mfma_f32_16x16x32_bf16 v[86:89], v[134:137], v[204:207], v[86:89]
	v_mfma_f32_16x16x32_bf16 v[78:81], v[158:161], v[204:207], v[78:81]
	s_barrier
	s_add_i32 s22, 0, 0x1c000
	s_add_i32 s23, s50, s36
	v_add_u32_e32 v157, s22, v154
	v_lshl_add_u64 v[178:179], v[178:179], 0, s[78:79]
	s_mov_b32 m0, s23
	ds_read_b128 v[208:211], v157
	ds_read_b128 v[224:227], v157 offset:1024
	ds_read_b128 v[228:231], v157 offset:2048
	ds_read_b128 v[232:235], v157 offset:3072
	global_load_lds_dwordx4 v[178:179], off
	s_add_i32 m0, s23, 0x2000
	v_lshl_add_u64 v[178:179], v[212:213], 0, s[78:79]
	global_load_lds_dwordx4 v[178:179], off
	s_mov_b32 m0, s25
	v_lshl_add_u64 v[178:179], v[236:237], 0, s[78:79]
	s_waitcnt lgkmcnt(0)
	s_barrier
	v_mfma_f32_16x16x32_bf16 v[114:117], v[208:211], v[162:165], v[114:117]
	v_mfma_f32_16x16x32_bf16 v[106:109], v[228:231], v[162:165], v[106:109]
	v_mfma_f32_16x16x32_bf16 v[98:101], v[208:211], v[170:173], v[98:101]
	v_mfma_f32_16x16x32_bf16 v[90:93], v[228:231], v[170:173], v[90:93]
	v_mfma_f32_16x16x32_bf16 v[82:85], v[208:211], v[192:195], v[82:85]
	v_mfma_f32_16x16x32_bf16 v[74:77], v[228:231], v[192:195], v[74:77]
	v_mfma_f32_16x16x32_bf16 v[70:73], v[208:211], v[200:203], v[70:73]
	v_mfma_f32_16x16x32_bf16 v[66:69], v[228:231], v[200:203], v[66:69]
	v_mfma_f32_16x16x32_bf16 v[114:117], v[224:227], v[166:169], v[114:117]
	v_mfma_f32_16x16x32_bf16 v[106:109], v[232:235], v[166:169], v[106:109]
	v_mfma_f32_16x16x32_bf16 v[98:101], v[224:227], v[174:177], v[98:101]
	v_mfma_f32_16x16x32_bf16 v[90:93], v[232:235], v[174:177], v[90:93]
	v_mfma_f32_16x16x32_bf16 v[82:85], v[224:227], v[196:199], v[82:85]
	v_mfma_f32_16x16x32_bf16 v[74:77], v[232:235], v[196:199], v[74:77]
	v_mfma_f32_16x16x32_bf16 v[70:73], v[224:227], v[204:207], v[70:73]
	v_mfma_f32_16x16x32_bf16 v[66:69], v[232:235], v[204:207], v[66:69]
	s_barrier
	ds_read_b128 v[162:165], v156 offset:49152
	ds_read_b128 v[166:169], v156 offset:50176
	ds_read_b128 v[170:173], v156 offset:51200
	ds_read_b128 v[174:177], v156 offset:52224
	ds_read_b128 v[192:195], v156 offset:53248
	ds_read_b128 v[196:199], v156 offset:54272
	ds_read_b128 v[200:203], v156 offset:55296
	ds_read_b128 v[204:207], v156 offset:56320
	global_load_lds_dwordx4 v[178:179], off
	s_mov_b32 m0, s26
	v_lshl_add_u64 v[178:179], v[238:239], 0, s[78:79]
	global_load_lds_dwordx4 v[178:179], off
	s_waitcnt vmcnt(10)
	s_barrier
	s_waitcnt lgkmcnt(0)
	v_mfma_f32_16x16x32_bf16 v[62:65], v[130:133], v[162:165], v[62:65]
	v_mfma_f32_16x16x32_bf16 v[58:61], v[150:153], v[162:165], v[58:61]
	v_mfma_f32_16x16x32_bf16 v[54:57], v[130:133], v[170:173], v[54:57]
	v_mfma_f32_16x16x32_bf16 v[46:49], v[150:153], v[170:173], v[46:49]
	v_mfma_f32_16x16x32_bf16 v[38:41], v[130:133], v[192:195], v[38:41]
	v_mfma_f32_16x16x32_bf16 v[30:33], v[150:153], v[192:195], v[30:33]
	v_mfma_f32_16x16x32_bf16 v[22:25], v[130:133], v[200:203], v[22:25]
	v_mfma_f32_16x16x32_bf16 v[14:17], v[150:153], v[200:203], v[14:17]
	v_mfma_f32_16x16x32_bf16 v[62:65], v[134:137], v[166:169], v[62:65]
	v_mfma_f32_16x16x32_bf16 v[58:61], v[158:161], v[166:169], v[58:61]
	v_mfma_f32_16x16x32_bf16 v[54:57], v[134:137], v[174:177], v[54:57]
	v_mfma_f32_16x16x32_bf16 v[46:49], v[158:161], v[174:177], v[46:49]
	v_mfma_f32_16x16x32_bf16 v[38:41], v[134:137], v[196:199], v[38:41]
	v_mfma_f32_16x16x32_bf16 v[30:33], v[158:161], v[196:199], v[30:33]
	v_mfma_f32_16x16x32_bf16 v[22:25], v[134:137], v[204:207], v[22:25]
	v_mfma_f32_16x16x32_bf16 v[14:17], v[158:161], v[204:207], v[14:17]
	s_barrier
	s_add_u32 s20, s20, 0x20080
	s_addc_u32 s21, s21, 0
	s_add_i32 s22, s22, s36
	s_mov_b32 m0, s22
	v_lshl_add_u64 v[130:131], s[20:21], 0, v[142:143]
	global_load_lds_dwordx4 v[130:131], off
	s_add_i32 m0, s22, 0x2000
	v_lshl_add_u64 v[130:131], s[20:21], 0, v[138:139]
	global_load_lds_dwordx4 v[130:131], off
	v_add_u32_e32 v157, 0x10000, v154
	ds_read_b128 v[130:133], v157
	ds_read_b128 v[134:137], v157 offset:1024
	ds_read_b128 v[150:153], v157 offset:2048
	ds_read_b128 v[158:161], v157 offset:3072
	s_add_i32 s49, s49, 2
	s_add_u32 s18, s18, 0x100
	s_addc_u32 s19, s19, 0
	s_add_u32 s47, s47, 0x100
	s_addc_u32 s48, s48, 0
	s_cmp_gt_u32 s49, 5
	s_waitcnt vmcnt(6)
	s_barrier
	v_mfma_f32_16x16x32_bf16 v[50:53], v[208:211], v[162:165], v[50:53]
	v_mfma_f32_16x16x32_bf16 v[42:45], v[228:231], v[162:165], v[42:45]
	v_mfma_f32_16x16x32_bf16 v[34:37], v[208:211], v[170:173], v[34:37]
	v_mfma_f32_16x16x32_bf16 v[26:29], v[228:231], v[170:173], v[26:29]
	v_mfma_f32_16x16x32_bf16 v[18:21], v[208:211], v[192:195], v[18:21]
	v_mfma_f32_16x16x32_bf16 v[10:13], v[228:231], v[192:195], v[10:13]
	v_mfma_f32_16x16x32_bf16 v[6:9], v[208:211], v[200:203], v[6:9]
	v_mfma_f32_16x16x32_bf16 v[2:5], v[228:231], v[200:203], v[2:5]
	v_mfma_f32_16x16x32_bf16 v[50:53], v[224:227], v[166:169], v[50:53]
	v_mfma_f32_16x16x32_bf16 v[42:45], v[232:235], v[166:169], v[42:45]
	v_mfma_f32_16x16x32_bf16 v[34:37], v[224:227], v[174:177], v[34:37]
	v_mfma_f32_16x16x32_bf16 v[26:29], v[232:235], v[174:177], v[26:29]
	v_mfma_f32_16x16x32_bf16 v[18:21], v[224:227], v[196:199], v[18:21]
	v_mfma_f32_16x16x32_bf16 v[10:13], v[232:235], v[196:199], v[10:13]
	v_mfma_f32_16x16x32_bf16 v[6:9], v[224:227], v[204:207], v[6:9]
	v_mfma_f32_16x16x32_bf16 v[2:5], v[232:235], v[204:207], v[2:5]
	s_barrier
	s_cbranch_scc0 .LBB0_386
	s_waitcnt lgkmcnt(0)
	v_lshl_add_u32 v164, s29, 8, v1
	v_lshl_or_b32 v150, s28, 8, v155
	s_mov_b64 s[18:19], -1
	s_cmp_lt_i32 s28, 8
	v_or_b32_e32 v163, 16, v164
	v_or_b32_e32 v162, 32, v164
	v_or_b32_e32 v161, 48, v164
	v_add_u32_e32 v160, 0x80, v164
	v_add_u32_e32 v159, 0x90, v164
	v_add_u32_e32 v158, 0xa0, v164
	v_add_u32_e32 v157, 0xb0, v164
	s_cbranch_scc1 .LBB0_389
	v_lshlrev_b32_e32 v130, 7, v164
	v_readlane_b32 s4, v255, 4
	v_and_b32_e32 v132, 0x3e780, v130
	v_mov_b32_e32 v133, v0
	v_readlane_b32 s5, v255, 5
	v_readlane_b32 s6, v255, 6
	v_readlane_b32 s7, v255, 7
	v_lshlrev_b32_e32 v130, 1, v150
	v_lshl_add_u64 v[134:135], s[4:5], 0, v[132:133]
	v_and_b32_e32 v130, 0x70, v130
	v_mov_b32_e32 v131, v0
	v_lshl_add_u64 v[132:133], s[6:7], 0, v[132:133]
	v_lshl_add_u64 v[152:153], v[132:133], 0, v[130:131]
	v_lshl_add_u64 v[136:137], v[134:135], 0, v[130:131]
	global_load_dwordx4 v[170:173], v[152:153], off
	global_load_dwordx4 v[166:169], v[136:137], off
	v_readlane_b32 s8, v255, 8
	v_readlane_b32 s9, v255, 9
	v_mov_b32_e32 v151, v0
	v_lshlrev_b64 v[134:135], 1, v[150:151]
	v_mov_b64_e32 v[132:133], s[8:9]
	v_mad_i64_i32 v[174:175], s[18:19], v164, s24, v[132:133]
	v_lshl_add_u64 v[174:175], v[174:175], 0, v[134:135]
	v_readlane_b32 s10, v255, 10
	v_readlane_b32 s11, v255, 11
	s_waitcnt vmcnt(0)
	v_pk_mul_f32 v[172:173], v[172:173], s[86:87] op_sel_hi:[1,0]
	v_pk_mul_f32 v[170:171], v[170:171], s[86:87] op_sel_hi:[1,0]
	v_pk_mul_f32 v[168:169], v[168:169], s[86:87] op_sel_hi:[1,0]
	v_pk_mul_f32 v[166:167], v[166:167], s[86:87] op_sel_hi:[1,0]
	v_pk_mul_f32 v[176:177], v[124:125], v[172:173]
	v_pk_mul_f32 v[178:179], v[122:123], v[170:171]
	v_pk_mul_f32 v[172:173], v[128:129], v[172:173]
	v_pk_mul_f32 v[170:171], v[126:127], v[170:171]
	v_pk_fma_f32 v[176:177], v[128:129], v[168:169], v[176:177] neg_lo:[0,0,1] neg_hi:[0,0,1]
	v_pk_fma_f32 v[178:179], v[126:127], v[166:167], v[178:179] neg_lo:[0,0,1] neg_hi:[0,0,1]
	v_pk_fma_f32 v[172:173], v[124:125], v[168:169], v[172:173]
	v_pk_fma_f32 v[168:169], v[122:123], v[166:167], v[170:171]
	v_cvt_pk_bf16_f32 v166, v178, v179
	v_cvt_pk_bf16_f32 v167, v176, v177
	v_cvt_pk_bf16_f32 v168, v168, v169
	v_cvt_pk_bf16_f32 v169, v172, v173
	global_store_dwordx4 v[174:175], v[166:169], off
	global_load_dwordx4 v[166:169], v[136:137], off
	s_nop 0
	global_load_dwordx4 v[170:173], v[152:153], off
	v_lshlrev_b32_e32 v136, 7, v163
	v_mov_b32_e32 v137, v0
	v_and_b32_e32 v136, 0x3ef80, v136
	v_lshl_add_u64 v[152:153], s[4:5], 0, v[136:137]
	v_lshl_add_u64 v[136:137], s[6:7], 0, v[136:137]
	v_lshl_add_u64 v[136:137], v[136:137], 0, v[130:131]
	v_lshl_add_u64 v[152:153], v[152:153], 0, v[130:131]
	s_waitcnt vmcnt(0)
	v_pk_mul_f32 v[168:169], v[168:169], s[86:87] op_sel_hi:[1,0]
	v_pk_mul_f32 v[172:173], v[172:173], s[86:87] op_sel_hi:[1,0]
	v_pk_mul_f32 v[170:171], v[170:171], s[86:87] op_sel_hi:[1,0]
	v_pk_mul_f32 v[166:167], v[166:167], s[86:87] op_sel_hi:[1,0]
	v_pk_mul_f32 v[176:177], v[108:109], v[172:173]
	v_pk_mul_f32 v[178:179], v[106:107], v[170:171]
	v_pk_mul_f32 v[172:173], v[116:117], v[172:173]
	v_pk_mul_f32 v[170:171], v[114:115], v[170:171]
	v_pk_fma_f32 v[176:177], v[116:117], v[168:169], v[176:177] neg_lo:[0,0,1] neg_hi:[0,0,1]
	v_pk_fma_f32 v[178:179], v[114:115], v[166:167], v[178:179] neg_lo:[0,0,1] neg_hi:[0,0,1]
	v_pk_fma_f32 v[172:173], v[108:109], v[168:169], v[172:173]
	v_pk_fma_f32 v[168:169], v[106:107], v[166:167], v[170:171]
	v_cvt_pk_bf16_f32 v166, v178, v179
	v_cvt_pk_bf16_f32 v167, v176, v177
	v_cvt_pk_bf16_f32 v168, v168, v169
	v_cvt_pk_bf16_f32 v169, v172, v173
	global_store_dwordx4 v[174:175], v[166:169], off offset:256
	global_load_dwordx4 v[170:173], v[136:137], off
	v_mad_i64_i32 v[174:175], s[18:19], v163, s24, v[132:133]
	global_load_dwordx4 v[166:169], v[152:153], off
	v_lshl_add_u64 v[174:175], v[174:175], 0, v[134:135]
	s_waitcnt vmcnt(0)
	v_pk_mul_f32 v[172:173], v[172:173], s[86:87] op_sel_hi:[1,0]
	v_pk_mul_f32 v[170:171], v[170:171], s[86:87] op_sel_hi:[1,0]
	v_pk_mul_f32 v[176:177], v[112:113], v[172:173]
	v_pk_mul_f32 v[168:169], v[168:169], s[86:87] op_sel_hi:[1,0]
	v_pk_mul_f32 v[166:167], v[166:167], s[86:87] op_sel_hi:[1,0]
	v_pk_mul_f32 v[178:179], v[110:111], v[170:171]
	v_pk_mul_f32 v[172:173], v[120:121], v[172:173]
	v_pk_mul_f32 v[170:171], v[118:119], v[170:171]
	v_pk_fma_f32 v[176:177], v[120:121], v[168:169], v[176:177] neg_lo:[0,0,1] neg_hi:[0,0,1]
	v_pk_fma_f32 v[178:179], v[118:119], v[166:167], v[178:179] neg_lo:[0,0,1] neg_hi:[0,0,1]
	v_pk_fma_f32 v[172:173], v[112:113], v[168:169], v[172:173]
	v_pk_fma_f32 v[168:169], v[110:111], v[166:167], v[170:171]
	v_cvt_pk_bf16_f32 v166, v178, v179
	v_cvt_pk_bf16_f32 v167, v176, v177
	v_cvt_pk_bf16_f32 v168, v168, v169
	v_cvt_pk_bf16_f32 v169, v172, v173
	global_store_dwordx4 v[174:175], v[166:169], off
	global_load_dwordx4 v[166:169], v[152:153], off
	s_nop 0
	global_load_dwordx4 v[170:173], v[136:137], off
	v_lshlrev_b32_e32 v136, 7, v162
	v_mov_b32_e32 v137, v0
	v_and_b32_e32 v136, 0x3f780, v136
	v_lshl_add_u64 v[152:153], s[4:5], 0, v[136:137]
	v_lshl_add_u64 v[136:137], s[6:7], 0, v[136:137]
	v_lshl_add_u64 v[136:137], v[136:137], 0, v[130:131]
	v_lshl_add_u64 v[152:153], v[152:153], 0, v[130:131]
	s_waitcnt vmcnt(0)
	v_pk_mul_f32 v[168:169], v[168:169], s[86:87] op_sel_hi:[1,0]
	v_pk_mul_f32 v[172:173], v[172:173], s[86:87] op_sel_hi:[1,0]
	v_pk_mul_f32 v[170:171], v[170:171], s[86:87] op_sel_hi:[1,0]
	v_pk_mul_f32 v[166:167], v[166:167], s[86:87] op_sel_hi:[1,0]
	v_pk_mul_f32 v[176:177], v[92:93], v[172:173]
	v_pk_mul_f32 v[178:179], v[90:91], v[170:171]
	v_pk_mul_f32 v[172:173], v[100:101], v[172:173]
	v_pk_mul_f32 v[170:171], v[98:99], v[170:171]
	v_pk_fma_f32 v[176:177], v[100:101], v[168:169], v[176:177] neg_lo:[0,0,1] neg_hi:[0,0,1]
	v_pk_fma_f32 v[178:179], v[98:99], v[166:167], v[178:179] neg_lo:[0,0,1] neg_hi:[0,0,1]
	v_pk_fma_f32 v[172:173], v[92:93], v[168:169], v[172:173]
	v_pk_fma_f32 v[168:169], v[90:91], v[166:167], v[170:171]
	v_cvt_pk_bf16_f32 v166, v178, v179
	v_cvt_pk_bf16_f32 v167, v176, v177
	v_cvt_pk_bf16_f32 v168, v168, v169
	v_cvt_pk_bf16_f32 v169, v172, v173
	global_store_dwordx4 v[174:175], v[166:169], off offset:256
	global_load_dwordx4 v[170:173], v[136:137], off
	v_mad_i64_i32 v[174:175], s[18:19], v162, s24, v[132:133]
	global_load_dwordx4 v[166:169], v[152:153], off
	v_lshl_add_u64 v[174:175], v[174:175], 0, v[134:135]
	s_waitcnt vmcnt(0)
	v_pk_mul_f32 v[172:173], v[172:173], s[86:87] op_sel_hi:[1,0]
	v_pk_mul_f32 v[170:171], v[170:171], s[86:87] op_sel_hi:[1,0]
	v_pk_mul_f32 v[176:177], v[96:97], v[172:173]
	v_pk_mul_f32 v[168:169], v[168:169], s[86:87] op_sel_hi:[1,0]
	v_pk_mul_f32 v[166:167], v[166:167], s[86:87] op_sel_hi:[1,0]
	v_pk_mul_f32 v[178:179], v[94:95], v[170:171]
	v_pk_mul_f32 v[172:173], v[104:105], v[172:173]
	v_pk_mul_f32 v[170:171], v[102:103], v[170:171]
	v_pk_fma_f32 v[176:177], v[104:105], v[168:169], v[176:177] neg_lo:[0,0,1] neg_hi:[0,0,1]
	v_pk_fma_f32 v[178:179], v[102:103], v[166:167], v[178:179] neg_lo:[0,0,1] neg_hi:[0,0,1]
	v_pk_fma_f32 v[172:173], v[96:97], v[168:169], v[172:173]
	v_pk_fma_f32 v[168:169], v[94:95], v[166:167], v[170:171]
	v_cvt_pk_bf16_f32 v166, v178, v179
	v_cvt_pk_bf16_f32 v167, v176, v177
	v_cvt_pk_bf16_f32 v168, v168, v169
	v_cvt_pk_bf16_f32 v169, v172, v173
	global_store_dwordx4 v[174:175], v[166:169], off
	global_load_dwordx4 v[166:169], v[152:153], off
	s_nop 0
	global_load_dwordx4 v[170:173], v[136:137], off
	v_lshlrev_b32_e32 v136, 7, v161
	v_mov_b32_e32 v137, v0
	v_and_b32_e32 v136, 0x3ff80, v136
	v_lshl_add_u64 v[152:153], s[4:5], 0, v[136:137]
	v_lshl_add_u64 v[136:137], s[6:7], 0, v[136:137]
	v_lshl_add_u64 v[136:137], v[136:137], 0, v[130:131]
	v_lshl_add_u64 v[152:153], v[152:153], 0, v[130:131]
	s_waitcnt vmcnt(0)
	v_pk_mul_f32 v[168:169], v[168:169], s[86:87] op_sel_hi:[1,0]
	v_pk_mul_f32 v[172:173], v[172:173], s[86:87] op_sel_hi:[1,0]
	v_pk_mul_f32 v[170:171], v[170:171], s[86:87] op_sel_hi:[1,0]
	v_pk_mul_f32 v[166:167], v[166:167], s[86:87] op_sel_hi:[1,0]
	v_pk_mul_f32 v[176:177], v[76:77], v[172:173]
	v_pk_mul_f32 v[178:179], v[74:75], v[170:171]
	v_pk_mul_f32 v[172:173], v[84:85], v[172:173]
	v_pk_mul_f32 v[170:171], v[82:83], v[170:171]
	v_pk_fma_f32 v[176:177], v[84:85], v[168:169], v[176:177] neg_lo:[0,0,1] neg_hi:[0,0,1]
	v_pk_fma_f32 v[178:179], v[82:83], v[166:167], v[178:179] neg_lo:[0,0,1] neg_hi:[0,0,1]
	v_pk_fma_f32 v[172:173], v[76:77], v[168:169], v[172:173]
	v_pk_fma_f32 v[168:169], v[74:75], v[166:167], v[170:171]
	v_cvt_pk_bf16_f32 v166, v178, v179
	v_cvt_pk_bf16_f32 v167, v176, v177
	v_cvt_pk_bf16_f32 v168, v168, v169
	v_cvt_pk_bf16_f32 v169, v172, v173
	global_store_dwordx4 v[174:175], v[166:169], off offset:256
	global_load_dwordx4 v[170:173], v[136:137], off
	v_mad_i64_i32 v[174:175], s[18:19], v161, s24, v[132:133]
	global_load_dwordx4 v[166:169], v[152:153], off
	v_lshl_add_u64 v[174:175], v[174:175], 0, v[134:135]
	s_waitcnt vmcnt(0)
	v_pk_mul_f32 v[172:173], v[172:173], s[86:87] op_sel_hi:[1,0]
	v_pk_mul_f32 v[170:171], v[170:171], s[86:87] op_sel_hi:[1,0]
	v_pk_mul_f32 v[176:177], v[80:81], v[172:173]
	v_pk_mul_f32 v[168:169], v[168:169], s[86:87] op_sel_hi:[1,0]
	v_pk_mul_f32 v[166:167], v[166:167], s[86:87] op_sel_hi:[1,0]
	v_pk_mul_f32 v[178:179], v[78:79], v[170:171]
	v_pk_mul_f32 v[172:173], v[88:89], v[172:173]
	v_pk_mul_f32 v[170:171], v[86:87], v[170:171]
	v_pk_fma_f32 v[176:177], v[88:89], v[168:169], v[176:177] neg_lo:[0,0,1] neg_hi:[0,0,1]
	v_pk_fma_f32 v[178:179], v[86:87], v[166:167], v[178:179] neg_lo:[0,0,1] neg_hi:[0,0,1]
	v_pk_fma_f32 v[172:173], v[80:81], v[168:169], v[172:173]
	v_pk_fma_f32 v[168:169], v[78:79], v[166:167], v[170:171]
	v_cvt_pk_bf16_f32 v166, v178, v179
	v_cvt_pk_bf16_f32 v167, v176, v177
	v_cvt_pk_bf16_f32 v168, v168, v169
	v_cvt_pk_bf16_f32 v169, v172, v173
	global_store_dwordx4 v[174:175], v[166:169], off
	global_load_dwordx4 v[166:169], v[152:153], off
	s_nop 0
	global_load_dwordx4 v[170:173], v[136:137], off
	v_lshlrev_b32_e32 v136, 7, v160
	v_mov_b32_e32 v137, v0
	v_and_b32_e32 v136, 0x3e780, v136
	v_lshl_add_u64 v[152:153], s[4:5], 0, v[136:137]
	v_lshl_add_u64 v[136:137], s[6:7], 0, v[136:137]
	v_lshl_add_u64 v[136:137], v[136:137], 0, v[130:131]
	v_lshl_add_u64 v[152:153], v[152:153], 0, v[130:131]
	s_waitcnt vmcnt(0)
	v_pk_mul_f32 v[168:169], v[168:169], s[86:87] op_sel_hi:[1,0]
	v_pk_mul_f32 v[172:173], v[172:173], s[86:87] op_sel_hi:[1,0]
	v_pk_mul_f32 v[170:171], v[170:171], s[86:87] op_sel_hi:[1,0]
	v_pk_mul_f32 v[166:167], v[166:167], s[86:87] op_sel_hi:[1,0]
	v_pk_mul_f32 v[176:177], v[68:69], v[172:173]
	v_pk_mul_f32 v[178:179], v[66:67], v[170:171]
	v_pk_mul_f32 v[172:173], v[72:73], v[172:173]
	v_pk_mul_f32 v[170:171], v[70:71], v[170:171]
	v_pk_fma_f32 v[176:177], v[72:73], v[168:169], v[176:177] neg_lo:[0,0,1] neg_hi:[0,0,1]
	v_pk_fma_f32 v[178:179], v[70:71], v[166:167], v[178:179] neg_lo:[0,0,1] neg_hi:[0,0,1]
	v_pk_fma_f32 v[172:173], v[68:69], v[168:169], v[172:173]
	v_pk_fma_f32 v[168:169], v[66:67], v[166:167], v[170:171]
	v_cvt_pk_bf16_f32 v166, v178, v179
	v_cvt_pk_bf16_f32 v167, v176, v177
	v_cvt_pk_bf16_f32 v168, v168, v169
	v_cvt_pk_bf16_f32 v169, v172, v173
	global_store_dwordx4 v[174:175], v[166:169], off offset:256
	global_load_dwordx4 v[170:173], v[136:137], off
	v_mad_i64_i32 v[174:175], s[18:19], v160, s24, v[132:133]
	global_load_dwordx4 v[166:169], v[152:153], off
	v_lshl_add_u64 v[174:175], v[174:175], 0, v[134:135]
	s_waitcnt vmcnt(0)
	v_pk_mul_f32 v[172:173], v[172:173], s[86:87] op_sel_hi:[1,0]
	v_pk_mul_f32 v[170:171], v[170:171], s[86:87] op_sel_hi:[1,0]
	v_pk_mul_f32 v[176:177], v[60:61], v[172:173]
	v_pk_mul_f32 v[168:169], v[168:169], s[86:87] op_sel_hi:[1,0]
	v_pk_mul_f32 v[166:167], v[166:167], s[86:87] op_sel_hi:[1,0]
	v_pk_mul_f32 v[178:179], v[58:59], v[170:171]
	v_pk_mul_f32 v[172:173], v[64:65], v[172:173]
	v_pk_mul_f32 v[170:171], v[62:63], v[170:171]
	v_pk_fma_f32 v[176:177], v[64:65], v[168:169], v[176:177] neg_lo:[0,0,1] neg_hi:[0,0,1]
	v_pk_fma_f32 v[178:179], v[62:63], v[166:167], v[178:179] neg_lo:[0,0,1] neg_hi:[0,0,1]
	v_pk_fma_f32 v[172:173], v[60:61], v[168:169], v[172:173]
	v_pk_fma_f32 v[168:169], v[58:59], v[166:167], v[170:171]
	v_cvt_pk_bf16_f32 v166, v178, v179
	v_cvt_pk_bf16_f32 v167, v176, v177
	v_cvt_pk_bf16_f32 v168, v168, v169
	v_cvt_pk_bf16_f32 v169, v172, v173
	global_store_dwordx4 v[174:175], v[166:169], off
	global_load_dwordx4 v[166:169], v[152:153], off
	s_nop 0
	global_load_dwordx4 v[170:173], v[136:137], off
	v_lshlrev_b32_e32 v136, 7, v159
	v_mov_b32_e32 v137, v0
	v_and_b32_e32 v136, 0x3ef80, v136
	v_lshl_add_u64 v[152:153], s[4:5], 0, v[136:137]
	v_lshl_add_u64 v[136:137], s[6:7], 0, v[136:137]
	v_lshl_add_u64 v[136:137], v[136:137], 0, v[130:131]
	v_lshl_add_u64 v[152:153], v[152:153], 0, v[130:131]
	s_waitcnt vmcnt(0)
	v_pk_mul_f32 v[168:169], v[168:169], s[86:87] op_sel_hi:[1,0]
	v_pk_mul_f32 v[172:173], v[172:173], s[86:87] op_sel_hi:[1,0]
	v_pk_mul_f32 v[170:171], v[170:171], s[86:87] op_sel_hi:[1,0]
	v_pk_mul_f32 v[166:167], v[166:167], s[86:87] op_sel_hi:[1,0]
	v_pk_mul_f32 v[176:177], v[44:45], v[172:173]
	v_pk_mul_f32 v[178:179], v[42:43], v[170:171]
	v_pk_mul_f32 v[172:173], v[52:53], v[172:173]
	v_pk_mul_f32 v[170:171], v[50:51], v[170:171]
	v_pk_fma_f32 v[176:177], v[52:53], v[168:169], v[176:177] neg_lo:[0,0,1] neg_hi:[0,0,1]
	v_pk_fma_f32 v[178:179], v[50:51], v[166:167], v[178:179] neg_lo:[0,0,1] neg_hi:[0,0,1]
	v_pk_fma_f32 v[172:173], v[44:45], v[168:169], v[172:173]
	v_pk_fma_f32 v[168:169], v[42:43], v[166:167], v[170:171]
	v_cvt_pk_bf16_f32 v166, v178, v179
	v_cvt_pk_bf16_f32 v167, v176, v177
	v_cvt_pk_bf16_f32 v168, v168, v169
	v_cvt_pk_bf16_f32 v169, v172, v173
	global_store_dwordx4 v[174:175], v[166:169], off offset:256
	global_load_dwordx4 v[170:173], v[136:137], off
	v_mad_i64_i32 v[174:175], s[18:19], v159, s24, v[132:133]
	global_load_dwordx4 v[166:169], v[152:153], off
	v_lshl_add_u64 v[174:175], v[174:175], 0, v[134:135]
	s_waitcnt vmcnt(0)
	v_pk_mul_f32 v[172:173], v[172:173], s[86:87] op_sel_hi:[1,0]
	v_pk_mul_f32 v[170:171], v[170:171], s[86:87] op_sel_hi:[1,0]
	v_pk_mul_f32 v[176:177], v[48:49], v[172:173]
	v_pk_mul_f32 v[168:169], v[168:169], s[86:87] op_sel_hi:[1,0]
	v_pk_mul_f32 v[166:167], v[166:167], s[86:87] op_sel_hi:[1,0]
	v_pk_mul_f32 v[178:179], v[46:47], v[170:171]
	v_pk_mul_f32 v[172:173], v[56:57], v[172:173]
	v_pk_mul_f32 v[170:171], v[54:55], v[170:171]
	v_pk_fma_f32 v[176:177], v[56:57], v[168:169], v[176:177] neg_lo:[0,0,1] neg_hi:[0,0,1]
	v_pk_fma_f32 v[178:179], v[54:55], v[166:167], v[178:179] neg_lo:[0,0,1] neg_hi:[0,0,1]
	v_pk_fma_f32 v[172:173], v[48:49], v[168:169], v[172:173]
	v_pk_fma_f32 v[168:169], v[46:47], v[166:167], v[170:171]
	v_cvt_pk_bf16_f32 v166, v178, v179
	v_cvt_pk_bf16_f32 v167, v176, v177
	v_cvt_pk_bf16_f32 v168, v168, v169
	v_cvt_pk_bf16_f32 v169, v172, v173
	global_store_dwordx4 v[174:175], v[166:169], off
	global_load_dwordx4 v[166:169], v[152:153], off
	s_nop 0
	global_load_dwordx4 v[170:173], v[136:137], off
	v_lshlrev_b32_e32 v136, 7, v158
	v_mov_b32_e32 v137, v0
	v_and_b32_e32 v136, 0x3f780, v136
	v_lshl_add_u64 v[152:153], s[4:5], 0, v[136:137]
	v_lshl_add_u64 v[136:137], s[6:7], 0, v[136:137]
	v_lshl_add_u64 v[136:137], v[136:137], 0, v[130:131]
	v_lshl_add_u64 v[152:153], v[152:153], 0, v[130:131]
	s_waitcnt vmcnt(0)
	v_pk_mul_f32 v[168:169], v[168:169], s[86:87] op_sel_hi:[1,0]
	v_pk_mul_f32 v[172:173], v[172:173], s[86:87] op_sel_hi:[1,0]
	v_pk_mul_f32 v[170:171], v[170:171], s[86:87] op_sel_hi:[1,0]
	v_pk_mul_f32 v[166:167], v[166:167], s[86:87] op_sel_hi:[1,0]
	v_pk_mul_f32 v[176:177], v[28:29], v[172:173]
	v_pk_mul_f32 v[178:179], v[26:27], v[170:171]
	v_pk_mul_f32 v[172:173], v[36:37], v[172:173]
	v_pk_mul_f32 v[170:171], v[34:35], v[170:171]
	v_pk_fma_f32 v[176:177], v[36:37], v[168:169], v[176:177] neg_lo:[0,0,1] neg_hi:[0,0,1]
	v_pk_fma_f32 v[178:179], v[34:35], v[166:167], v[178:179] neg_lo:[0,0,1] neg_hi:[0,0,1]
	v_pk_fma_f32 v[172:173], v[28:29], v[168:169], v[172:173]
	v_pk_fma_f32 v[168:169], v[26:27], v[166:167], v[170:171]
	v_cvt_pk_bf16_f32 v166, v178, v179
	v_cvt_pk_bf16_f32 v167, v176, v177
	v_cvt_pk_bf16_f32 v168, v168, v169
	v_cvt_pk_bf16_f32 v169, v172, v173
	global_store_dwordx4 v[174:175], v[166:169], off offset:256
	global_load_dwordx4 v[170:173], v[136:137], off
	v_mad_i64_i32 v[174:175], s[18:19], v158, s24, v[132:133]
	global_load_dwordx4 v[166:169], v[152:153], off
	v_lshl_add_u64 v[174:175], v[174:175], 0, v[134:135]
	s_waitcnt vmcnt(0)
	v_pk_mul_f32 v[172:173], v[172:173], s[86:87] op_sel_hi:[1,0]
	v_pk_mul_f32 v[170:171], v[170:171], s[86:87] op_sel_hi:[1,0]
	v_pk_mul_f32 v[176:177], v[32:33], v[172:173]
	v_pk_mul_f32 v[168:169], v[168:169], s[86:87] op_sel_hi:[1,0]
	v_pk_mul_f32 v[166:167], v[166:167], s[86:87] op_sel_hi:[1,0]
	v_pk_mul_f32 v[178:179], v[30:31], v[170:171]
	v_pk_mul_f32 v[172:173], v[40:41], v[172:173]
	v_pk_mul_f32 v[170:171], v[38:39], v[170:171]
	v_pk_fma_f32 v[176:177], v[40:41], v[168:169], v[176:177] neg_lo:[0,0,1] neg_hi:[0,0,1]
	v_pk_fma_f32 v[178:179], v[38:39], v[166:167], v[178:179] neg_lo:[0,0,1] neg_hi:[0,0,1]
	v_pk_fma_f32 v[172:173], v[32:33], v[168:169], v[172:173]
	v_pk_fma_f32 v[168:169], v[30:31], v[166:167], v[170:171]
	v_cvt_pk_bf16_f32 v166, v178, v179
	v_cvt_pk_bf16_f32 v167, v176, v177
	v_cvt_pk_bf16_f32 v168, v168, v169
	v_cvt_pk_bf16_f32 v169, v172, v173
	global_store_dwordx4 v[174:175], v[166:169], off
	global_load_dwordx4 v[166:169], v[152:153], off
	s_nop 0
	global_load_dwordx4 v[170:173], v[136:137], off
	v_lshlrev_b32_e32 v136, 7, v157
	v_mov_b32_e32 v137, v0
	v_and_b32_e32 v136, 0x3ff80, v136
	v_lshl_add_u64 v[152:153], s[4:5], 0, v[136:137]
	v_lshl_add_u64 v[176:177], v[152:153], 0, v[130:131]
	v_lshl_add_u64 v[136:137], s[6:7], 0, v[136:137]
	v_lshl_add_u64 v[136:137], v[136:137], 0, v[130:131]
	v_mad_i64_i32 v[130:131], s[18:19], v157, s24, v[132:133]
	s_mov_b64 s[18:19], 0
	s_waitcnt vmcnt(0)
	v_pk_mul_f32 v[152:153], v[168:169], s[86:87] op_sel_hi:[1,0]
	v_pk_mul_f32 v[168:169], v[172:173], s[86:87] op_sel_hi:[1,0]
	v_pk_mul_f32 v[170:171], v[170:171], s[86:87] op_sel_hi:[1,0]
	v_pk_mul_f32 v[166:167], v[166:167], s[86:87] op_sel_hi:[1,0]
	v_pk_mul_f32 v[172:173], v[12:13], v[168:169]
	v_pk_mul_f32 v[178:179], v[10:11], v[170:171]
	v_pk_mul_f32 v[168:169], v[20:21], v[168:169]
	v_pk_mul_f32 v[170:171], v[18:19], v[170:171]
	v_pk_fma_f32 v[172:173], v[20:21], v[152:153], v[172:173] neg_lo:[0,0,1] neg_hi:[0,0,1]
	v_pk_fma_f32 v[178:179], v[18:19], v[166:167], v[178:179] neg_lo:[0,0,1] neg_hi:[0,0,1]
	v_pk_fma_f32 v[152:153], v[12:13], v[152:153], v[168:169]
	v_pk_fma_f32 v[168:169], v[10:11], v[166:167], v[170:171]
	v_cvt_pk_bf16_f32 v166, v178, v179
	v_cvt_pk_bf16_f32 v167, v172, v173
	v_cvt_pk_bf16_f32 v168, v168, v169
	v_cvt_pk_bf16_f32 v169, v152, v153
	global_store_dwordx4 v[174:175], v[166:169], off offset:256
	global_load_dwordx4 v[166:169], v[176:177], off
	v_lshl_add_u64 v[152:153], v[130:131], 0, v[134:135]
	global_load_dwordx4 v[170:173], v[136:137], off
	s_waitcnt vmcnt(0)
	v_pk_mul_f32 v[132:133], v[166:167], s[86:87] op_sel_hi:[1,0]
	v_pk_mul_f32 v[130:131], v[168:169], s[86:87] op_sel_hi:[1,0]
	v_pk_mul_f32 v[134:135], v[172:173], s[86:87] op_sel_hi:[1,0]
	v_pk_mul_f32 v[166:167], v[170:171], s[86:87] op_sel_hi:[1,0]
	v_pk_mul_f32 v[168:169], v[16:17], v[134:135]
	v_pk_mul_f32 v[170:171], v[14:15], v[166:167]
	v_pk_mul_f32 v[134:135], v[24:25], v[134:135]
	v_pk_mul_f32 v[166:167], v[22:23], v[166:167]
	v_pk_fma_f32 v[168:169], v[24:25], v[130:131], v[168:169] neg_lo:[0,0,1] neg_hi:[0,0,1]
	v_pk_fma_f32 v[170:171], v[22:23], v[132:133], v[170:171] neg_lo:[0,0,1] neg_hi:[0,0,1]
	v_pk_fma_f32 v[134:135], v[16:17], v[130:131], v[134:135]
	v_pk_fma_f32 v[132:133], v[14:15], v[132:133], v[166:167]
	v_cvt_pk_bf16_f32 v130, v170, v171
	v_cvt_pk_bf16_f32 v131, v168, v169
	v_cvt_pk_bf16_f32 v132, v132, v133
	v_cvt_pk_bf16_f32 v133, v134, v135
	global_store_dwordx4 v[152:153], v[130:133], off
	global_load_dwordx4 v[130:133], v[176:177], off
	s_nop 0
	global_load_dwordx4 v[134:137], v[136:137], off
	s_waitcnt vmcnt(0)
	v_pk_mul_f32 v[166:167], v[132:133], s[86:87] op_sel_hi:[1,0]
	v_pk_mul_f32 v[168:169], v[130:131], s[86:87] op_sel_hi:[1,0]
	v_pk_mul_f32 v[130:131], v[136:137], s[86:87] op_sel_hi:[1,0]
	v_pk_mul_f32 v[132:133], v[134:135], s[86:87] op_sel_hi:[1,0]
	v_pk_mul_f32 v[134:135], v[4:5], v[130:131]
	v_pk_mul_f32 v[136:137], v[2:3], v[132:133]
	v_pk_mul_f32 v[170:171], v[8:9], v[130:131]
	v_pk_mul_f32 v[172:173], v[6:7], v[132:133]
	v_pk_fma_f32 v[132:133], v[8:9], v[166:167], v[134:135] neg_lo:[0,0,1] neg_hi:[0,0,1]
	v_pk_fma_f32 v[130:131], v[6:7], v[168:169], v[136:137] neg_lo:[0,0,1] neg_hi:[0,0,1]
	v_pk_fma_f32 v[136:137], v[4:5], v[166:167], v[170:171]
	v_pk_fma_f32 v[134:135], v[2:3], v[168:169], v[172:173]

.LBB0_526:
	s_add_u32 s20, s18, 0xfff80080
	s_addc_u32 s21, s19, -1
	s_add_i32 s56, 0, 0x10000
	s_cmp_eq_u32 s55, 28
	s_cselect_b32 s23, s39, s21
	s_cselect_b32 s22, s51, s20
	s_cselect_b32 s21, s31, s54
	s_cselect_b32 s20, s52, s53
	v_lshl_add_u64 v[152:153], s[18:19], 0, v[140:141]
	s_add_i32 m0, s29, 0xc000
	ds_read_b128 v[164:167], v154
	ds_read_b128 v[168:171], v154 offset:1024
	ds_read_b128 v[172:175], v154 offset:2048
	ds_read_b128 v[176:179], v154 offset:3072
	ds_read_b128 v[192:195], v154 offset:4096
	ds_read_b128 v[196:199], v154 offset:5120
	ds_read_b128 v[200:203], v154 offset:6144
	ds_read_b128 v[204:207], v154 offset:7168
	global_load_lds_dwordx4 v[152:153], off
	s_add_i32 m0, s29, 0xe000
	v_lshl_add_u64 v[152:153], s[18:19], 0, v[142:143]
	global_load_lds_dwordx4 v[152:153], off
	s_barrier
	s_waitcnt lgkmcnt(0)
	v_mfma_f32_16x16x32_bf16 v[126:129], v[144:147], v[164:167], v[126:129]
	v_mfma_f32_16x16x32_bf16 v[122:125], v[156:159], v[164:167], v[122:125]
	v_mfma_f32_16x16x32_bf16 v[118:121], v[144:147], v[172:175], v[118:121]
	v_mfma_f32_16x16x32_bf16 v[114:117], v[156:159], v[172:175], v[114:117]
	v_mfma_f32_16x16x32_bf16 v[102:105], v[144:147], v[192:195], v[102:105]
	v_mfma_f32_16x16x32_bf16 v[98:101], v[156:159], v[192:195], v[98:101]
	v_mfma_f32_16x16x32_bf16 v[86:89], v[144:147], v[200:203], v[86:89]
	v_mfma_f32_16x16x32_bf16 v[82:85], v[156:159], v[200:203], v[82:85]
	v_mfma_f32_16x16x32_bf16 v[126:129], v[148:151], v[168:171], v[126:129]
	v_mfma_f32_16x16x32_bf16 v[122:125], v[160:163], v[168:171], v[122:125]
	v_mfma_f32_16x16x32_bf16 v[118:121], v[148:151], v[176:179], v[118:121]
	v_mfma_f32_16x16x32_bf16 v[114:117], v[160:163], v[176:179], v[114:117]
	v_mfma_f32_16x16x32_bf16 v[102:105], v[148:151], v[196:199], v[102:105]
	v_mfma_f32_16x16x32_bf16 v[98:101], v[160:163], v[196:199], v[98:101]
	v_mfma_f32_16x16x32_bf16 v[86:89], v[148:151], v[204:207], v[86:89]
	v_mfma_f32_16x16x32_bf16 v[82:85], v[160:163], v[204:207], v[82:85]
	s_barrier
	s_add_i32 s58, 0, 0x14000
	v_add_u32_e32 v152, s58, v139
	s_add_i32 s56, s56, s28
	ds_read_b128 v[208:211], v152
	ds_read_b128 v[224:227], v152 offset:1024
	ds_read_b128 v[228:231], v152 offset:2048
	ds_read_b128 v[232:235], v152 offset:3072
	v_lshl_add_u64 v[152:153], s[20:21], 0, v[134:135]
	s_mov_b32 m0, s56
	v_lshl_add_u64 v[212:213], s[20:21], 0, v[130:131]
	global_load_lds_dwordx4 v[152:153], off
	s_add_i32 m0, s56, 0x2000
	s_nop 0
	global_load_lds_dwordx4 v[212:213], off
	s_mov_b32 m0, s29
	v_lshl_add_u64 v[236:237], s[22:23], 0, v[136:137]
	s_waitcnt lgkmcnt(0)
	s_barrier
	v_mfma_f32_16x16x32_bf16 v[110:113], v[208:211], v[164:167], v[110:113]
	v_mfma_f32_16x16x32_bf16 v[106:109], v[228:231], v[164:167], v[106:109]
	v_mfma_f32_16x16x32_bf16 v[94:97], v[208:211], v[172:175], v[94:97]
	v_mfma_f32_16x16x32_bf16 v[90:93], v[228:231], v[172:175], v[90:93]
	v_mfma_f32_16x16x32_bf16 v[78:81], v[208:211], v[192:195], v[78:81]
	v_mfma_f32_16x16x32_bf16 v[74:77], v[228:231], v[192:195], v[74:77]
	v_mfma_f32_16x16x32_bf16 v[70:73], v[208:211], v[200:203], v[70:73]
	v_mfma_f32_16x16x32_bf16 v[66:69], v[228:231], v[200:203], v[66:69]
	v_mfma_f32_16x16x32_bf16 v[110:113], v[224:227], v[168:171], v[110:113]
	v_mfma_f32_16x16x32_bf16 v[106:109], v[232:235], v[168:171], v[106:109]
	v_mfma_f32_16x16x32_bf16 v[94:97], v[224:227], v[176:179], v[94:97]
	v_mfma_f32_16x16x32_bf16 v[90:93], v[232:235], v[176:179], v[90:93]
	v_mfma_f32_16x16x32_bf16 v[78:81], v[224:227], v[196:199], v[78:81]
	v_mfma_f32_16x16x32_bf16 v[74:77], v[232:235], v[196:199], v[74:77]
	v_mfma_f32_16x16x32_bf16 v[70:73], v[224:227], v[204:207], v[70:73]
	v_mfma_f32_16x16x32_bf16 v[66:69], v[232:235], v[204:207], v[66:69]
	s_barrier
	ds_read_b128 v[164:167], v154 offset:16384
	ds_read_b128 v[168:171], v154 offset:17408
	ds_read_b128 v[172:175], v154 offset:18432
	ds_read_b128 v[176:179], v154 offset:19456
	ds_read_b128 v[192:195], v154 offset:20480
	ds_read_b128 v[196:199], v154 offset:21504
	ds_read_b128 v[200:203], v154 offset:22528
	ds_read_b128 v[204:207], v154 offset:23552
	global_load_lds_dwordx4 v[236:237], off
	s_mov_b32 m0, s44
	v_lshl_add_u64 v[238:239], s[22:23], 0, v[132:133]
	global_load_lds_dwordx4 v[238:239], off
	s_waitcnt vmcnt(10)
	s_barrier
	s_waitcnt lgkmcnt(0)
	v_mfma_f32_16x16x32_bf16 v[62:65], v[144:147], v[164:167], v[62:65]
	v_mfma_f32_16x16x32_bf16 v[58:61], v[156:159], v[164:167], v[58:61]
	v_mfma_f32_16x16x32_bf16 v[54:57], v[144:147], v[172:175], v[54:57]
	v_mfma_f32_16x16x32_bf16 v[50:53], v[156:159], v[172:175], v[50:53]
	v_mfma_f32_16x16x32_bf16 v[38:41], v[144:147], v[192:195], v[38:41]
	v_mfma_f32_16x16x32_bf16 v[34:37], v[156:159], v[192:195], v[34:37]
	v_mfma_f32_16x16x32_bf16 v[22:25], v[144:147], v[200:203], v[22:25]
	v_mfma_f32_16x16x32_bf16 v[18:21], v[156:159], v[200:203], v[18:21]
	v_mfma_f32_16x16x32_bf16 v[62:65], v[148:151], v[168:171], v[62:65]
	v_mfma_f32_16x16x32_bf16 v[58:61], v[160:163], v[168:171], v[58:61]
	v_mfma_f32_16x16x32_bf16 v[54:57], v[148:151], v[176:179], v[54:57]
	v_mfma_f32_16x16x32_bf16 v[50:53], v[160:163], v[176:179], v[50:53]
	v_mfma_f32_16x16x32_bf16 v[38:41], v[148:151], v[196:199], v[38:41]
	v_mfma_f32_16x16x32_bf16 v[34:37], v[160:163], v[196:199], v[34:37]
	v_mfma_f32_16x16x32_bf16 v[22:25], v[148:151], v[204:207], v[22:25]
	v_mfma_f32_16x16x32_bf16 v[18:21], v[160:163], v[204:207], v[18:21]
	s_barrier
	s_add_u32 s56, s20, 0x80000
	s_addc_u32 s57, s21, 0
	s_add_i32 s58, s58, s28
	s_mov_b32 m0, s58
	v_lshl_add_u64 v[144:145], s[56:57], 0, v[134:135]
	global_load_lds_dwordx4 v[144:145], off
	s_add_i32 m0, s58, 0x2000
	v_lshl_add_u64 v[144:145], s[56:57], 0, v[130:131]
	global_load_lds_dwordx4 v[144:145], off
	v_add_u32_e32 v155, 0x18000, v139
	ds_read_b128 v[144:147], v155
	ds_read_b128 v[148:151], v155 offset:1024
	ds_read_b128 v[156:159], v155 offset:2048
	ds_read_b128 v[160:163], v155 offset:3072
	s_add_i32 s56, 0, 0x18000
	s_waitcnt vmcnt(6)
	s_barrier
	v_mfma_f32_16x16x32_bf16 v[46:49], v[208:211], v[164:167], v[46:49]
	v_mfma_f32_16x16x32_bf16 v[42:45], v[228:231], v[164:167], v[42:45]
	v_mfma_f32_16x16x32_bf16 v[30:33], v[208:211], v[172:175], v[30:33]
	v_mfma_f32_16x16x32_bf16 v[26:29], v[228:231], v[172:175], v[26:29]
	v_mfma_f32_16x16x32_bf16 v[14:17], v[208:211], v[192:195], v[14:17]
	v_mfma_f32_16x16x32_bf16 v[10:13], v[228:231], v[192:195], v[10:13]
	v_mfma_f32_16x16x32_bf16 v[6:9], v[208:211], v[200:203], v[6:9]
	v_mfma_f32_16x16x32_bf16 v[2:5], v[228:231], v[200:203], v[2:5]
	v_mfma_f32_16x16x32_bf16 v[46:49], v[224:227], v[168:171], v[46:49]
	v_mfma_f32_16x16x32_bf16 v[42:45], v[232:235], v[168:171], v[42:45]
	v_mfma_f32_16x16x32_bf16 v[30:33], v[224:227], v[176:179], v[30:33]
	v_mfma_f32_16x16x32_bf16 v[26:29], v[232:235], v[176:179], v[26:29]
	v_mfma_f32_16x16x32_bf16 v[14:17], v[224:227], v[196:199], v[14:17]
	v_mfma_f32_16x16x32_bf16 v[10:13], v[232:235], v[196:199], v[10:13]
	v_mfma_f32_16x16x32_bf16 v[6:9], v[224:227], v[204:207], v[6:9]
	v_mfma_f32_16x16x32_bf16 v[2:5], v[232:235], v[204:207], v[2:5]
	s_barrier
	s_add_u32 s22, s22, 0x80000
	s_addc_u32 s23, s23, 0
	s_mov_b32 m0, s45
	v_lshl_add_u64 v[208:209], s[22:23], 0, v[136:137]
	ds_read_b128 v[164:167], v154 offset:32768
	ds_read_b128 v[168:171], v154 offset:33792
	ds_read_b128 v[172:175], v154 offset:34816
	ds_read_b128 v[176:179], v154 offset:35840
	ds_read_b128 v[192:195], v154 offset:36864
	ds_read_b128 v[196:199], v154 offset:37888
	ds_read_b128 v[200:203], v154 offset:38912
	ds_read_b128 v[204:207], v154 offset:39936
	global_load_lds_dwordx4 v[208:209], off
	s_mov_b32 m0, s46
	v_lshl_add_u64 v[208:209], s[22:23], 0, v[132:133]
	global_load_lds_dwordx4 v[208:209], off
	s_barrier
	s_waitcnt lgkmcnt(0)
	v_mfma_f32_16x16x32_bf16 v[126:129], v[144:147], v[164:167], v[126:129]
	v_mfma_f32_16x16x32_bf16 v[122:125], v[156:159], v[164:167], v[122:125]
	v_mfma_f32_16x16x32_bf16 v[118:121], v[144:147], v[172:175], v[118:121]
	v_mfma_f32_16x16x32_bf16 v[114:117], v[156:159], v[172:175], v[114:117]
	v_mfma_f32_16x16x32_bf16 v[102:105], v[144:147], v[192:195], v[102:105]
	v_mfma_f32_16x16x32_bf16 v[98:101], v[156:159], v[192:195], v[98:101]
	v_mfma_f32_16x16x32_bf16 v[86:89], v[144:147], v[200:203], v[86:89]
	v_mfma_f32_16x16x32_bf16 v[82:85], v[156:159], v[200:203], v[82:85]
	v_mfma_f32_16x16x32_bf16 v[126:129], v[148:151], v[168:171], v[126:129]
	v_mfma_f32_16x16x32_bf16 v[122:125], v[160:163], v[168:171], v[122:125]
	v_mfma_f32_16x16x32_bf16 v[118:121], v[148:151], v[176:179], v[118:121]
	v_mfma_f32_16x16x32_bf16 v[114:117], v[160:163], v[176:179], v[114:117]
	v_mfma_f32_16x16x32_bf16 v[102:105], v[148:151], v[196:199], v[102:105]
	v_mfma_f32_16x16x32_bf16 v[98:101], v[160:163], v[196:199], v[98:101]
	v_mfma_f32_16x16x32_bf16 v[86:89], v[148:151], v[204:207], v[86:89]
	v_mfma_f32_16x16x32_bf16 v[82:85], v[160:163], v[204:207], v[82:85]
	s_barrier
	s_add_i32 s22, 0, 0x1c000
	s_add_i32 s23, s56, s28
	v_add_u32_e32 v155, s22, v139
	v_lshl_add_u64 v[152:153], v[152:153], 0, s[78:79]
	s_mov_b32 m0, s23
	ds_read_b128 v[208:211], v155
	ds_read_b128 v[224:227], v155 offset:1024
	ds_read_b128 v[228:231], v155 offset:2048
	ds_read_b128 v[232:235], v155 offset:3072
	global_load_lds_dwordx4 v[152:153], off
	s_add_i32 m0, s23, 0x2000
	v_lshl_add_u64 v[152:153], v[212:213], 0, s[78:79]
	global_load_lds_dwordx4 v[152:153], off
	s_mov_b32 m0, s47
	v_lshl_add_u64 v[152:153], v[236:237], 0, s[78:79]
	s_waitcnt lgkmcnt(0)
	s_barrier
	v_mfma_f32_16x16x32_bf16 v[110:113], v[208:211], v[164:167], v[110:113]
	v_mfma_f32_16x16x32_bf16 v[106:109], v[228:231], v[164:167], v[106:109]
	v_mfma_f32_16x16x32_bf16 v[94:97], v[208:211], v[172:175], v[94:97]
	v_mfma_f32_16x16x32_bf16 v[90:93], v[228:231], v[172:175], v[90:93]
	v_mfma_f32_16x16x32_bf16 v[78:81], v[208:211], v[192:195], v[78:81]
	v_mfma_f32_16x16x32_bf16 v[74:77], v[228:231], v[192:195], v[74:77]
	v_mfma_f32_16x16x32_bf16 v[70:73], v[208:211], v[200:203], v[70:73]
	v_mfma_f32_16x16x32_bf16 v[66:69], v[228:231], v[200:203], v[66:69]
	v_mfma_f32_16x16x32_bf16 v[110:113], v[224:227], v[168:171], v[110:113]
	v_mfma_f32_16x16x32_bf16 v[106:109], v[232:235], v[168:171], v[106:109]
	v_mfma_f32_16x16x32_bf16 v[94:97], v[224:227], v[176:179], v[94:97]
	v_mfma_f32_16x16x32_bf16 v[90:93], v[232:235], v[176:179], v[90:93]
	v_mfma_f32_16x16x32_bf16 v[78:81], v[224:227], v[196:199], v[78:81]
	v_mfma_f32_16x16x32_bf16 v[74:77], v[232:235], v[196:199], v[74:77]
	v_mfma_f32_16x16x32_bf16 v[70:73], v[224:227], v[204:207], v[70:73]
	v_mfma_f32_16x16x32_bf16 v[66:69], v[232:235], v[204:207], v[66:69]
	s_barrier
	ds_read_b128 v[164:167], v154 offset:49152
	ds_read_b128 v[168:171], v154 offset:50176
	ds_read_b128 v[172:175], v154 offset:51200
	ds_read_b128 v[176:179], v154 offset:52224
	ds_read_b128 v[192:195], v154 offset:53248
	ds_read_b128 v[196:199], v154 offset:54272
	ds_read_b128 v[200:203], v154 offset:55296
	ds_read_b128 v[204:207], v154 offset:56320
	global_load_lds_dwordx4 v[152:153], off
	s_mov_b32 m0, s48
	v_lshl_add_u64 v[152:153], v[238:239], 0, s[78:79]
	global_load_lds_dwordx4 v[152:153], off
	s_waitcnt vmcnt(10)
	s_barrier
	s_waitcnt lgkmcnt(0)
	v_mfma_f32_16x16x32_bf16 v[62:65], v[144:147], v[164:167], v[62:65]
	v_mfma_f32_16x16x32_bf16 v[58:61], v[156:159], v[164:167], v[58:61]
	v_mfma_f32_16x16x32_bf16 v[54:57], v[144:147], v[172:175], v[54:57]
	v_mfma_f32_16x16x32_bf16 v[50:53], v[156:159], v[172:175], v[50:53]
	v_mfma_f32_16x16x32_bf16 v[38:41], v[144:147], v[192:195], v[38:41]
	v_mfma_f32_16x16x32_bf16 v[34:37], v[156:159], v[192:195], v[34:37]
	v_mfma_f32_16x16x32_bf16 v[22:25], v[144:147], v[200:203], v[22:25]
	v_mfma_f32_16x16x32_bf16 v[18:21], v[156:159], v[200:203], v[18:21]
	v_mfma_f32_16x16x32_bf16 v[62:65], v[148:151], v[168:171], v[62:65]
	v_mfma_f32_16x16x32_bf16 v[58:61], v[160:163], v[168:171], v[58:61]
	v_mfma_f32_16x16x32_bf16 v[54:57], v[148:151], v[176:179], v[54:57]
	v_mfma_f32_16x16x32_bf16 v[50:53], v[160:163], v[176:179], v[50:53]
	v_mfma_f32_16x16x32_bf16 v[38:41], v[148:151], v[196:199], v[38:41]
	v_mfma_f32_16x16x32_bf16 v[34:37], v[160:163], v[196:199], v[34:37]
	v_mfma_f32_16x16x32_bf16 v[22:25], v[148:151], v[204:207], v[22:25]
	v_mfma_f32_16x16x32_bf16 v[18:21], v[160:163], v[204:207], v[18:21]
	s_barrier
	s_add_u32 s20, s20, 0x80080
	s_addc_u32 s21, s21, 0
	s_add_i32 s22, s22, s28
	s_mov_b32 m0, s22
	v_lshl_add_u64 v[144:145], s[20:21], 0, v[134:135]
	global_load_lds_dwordx4 v[144:145], off
	s_add_i32 m0, s22, 0x2000
	v_lshl_add_u64 v[144:145], s[20:21], 0, v[130:131]
	global_load_lds_dwordx4 v[144:145], off
	v_add_u32_e32 v152, 0x10000, v139
	ds_read_b128 v[144:147], v152
	ds_read_b128 v[148:151], v152 offset:1024
	ds_read_b128 v[156:159], v152 offset:2048
	ds_read_b128 v[160:163], v152 offset:3072
	s_add_i32 s55, s55, 2
	s_add_u32 s18, s18, 0x100
	s_addc_u32 s19, s19, 0
	s_add_u32 s53, s53, 0x100
	s_addc_u32 s54, s54, 0
	s_cmp_gt_u32 s55, 29
	s_waitcnt vmcnt(6)
	s_barrier
	v_mfma_f32_16x16x32_bf16 v[46:49], v[208:211], v[164:167], v[46:49]
	v_mfma_f32_16x16x32_bf16 v[42:45], v[228:231], v[164:167], v[42:45]
	v_mfma_f32_16x16x32_bf16 v[30:33], v[208:211], v[172:175], v[30:33]
	v_mfma_f32_16x16x32_bf16 v[26:29], v[228:231], v[172:175], v[26:29]
	v_mfma_f32_16x16x32_bf16 v[14:17], v[208:211], v[192:195], v[14:17]
	v_mfma_f32_16x16x32_bf16 v[10:13], v[228:231], v[192:195], v[10:13]
	v_mfma_f32_16x16x32_bf16 v[6:9], v[208:211], v[200:203], v[6:9]
	v_mfma_f32_16x16x32_bf16 v[2:5], v[228:231], v[200:203], v[2:5]
	v_mfma_f32_16x16x32_bf16 v[46:49], v[224:227], v[168:171], v[46:49]
	v_mfma_f32_16x16x32_bf16 v[42:45], v[232:235], v[168:171], v[42:45]
	v_mfma_f32_16x16x32_bf16 v[30:33], v[224:227], v[176:179], v[30:33]
	v_mfma_f32_16x16x32_bf16 v[26:29], v[232:235], v[176:179], v[26:29]
	v_mfma_f32_16x16x32_bf16 v[14:17], v[224:227], v[196:199], v[14:17]
	v_mfma_f32_16x16x32_bf16 v[10:13], v[232:235], v[196:199], v[10:13]
	v_mfma_f32_16x16x32_bf16 v[6:9], v[224:227], v[204:207], v[6:9]
	v_mfma_f32_16x16x32_bf16 v[2:5], v[232:235], v[204:207], v[2:5]
	s_barrier
	s_cbranch_scc0 .LBB0_526
	s_waitcnt lgkmcnt(0)
	v_lshl_add_u32 v152, s36, 8, v1
	v_or_b32_e32 v150, 16, v152
	v_or_b32_e32 v148, 32, v152
	v_or_b32_e32 v146, 48, v152
	s_mov_b64 s[18:19], -1
	s_cmp_lt_i32 s50, 8
	v_ashrrev_i32_e32 v153, 31, v152
	v_lshlrev_b32_e32 v144, 1, v138
	v_ashrrev_i32_e32 v151, 31, v150
	v_ashrrev_i32_e32 v149, 31, v148
	v_ashrrev_i32_e32 v147, 31, v146
	s_cbranch_scc1 .LBB0_529
	s_lshl_b32 s18, s50, 7
	s_add_i32 s36, s18, 0xfffffc00
	v_lshlrev_b64 v[156:157], 12, v[152:153]
	v_lshl_add_u64 v[156:157], s[72:73], 0, v[156:157]
	s_lshl_b64 s[18:19], s[36:37], 1
	v_lshl_add_u64 v[156:157], v[156:157], 0, s[18:19]
	v_mov_b32_e32 v145, v0
	v_lshl_add_u64 v[160:161], v[156:157], 0, v[144:145]
	v_pk_mul_f32 v[158:159], v[128:129], v[112:113]
	v_pk_mul_f32 v[156:157], v[126:127], v[110:111]
	v_pk_mul_f32 v[162:163], v[124:125], v[108:109]
	v_pk_mul_f32 v[164:165], v[122:123], v[106:107]
	v_cvt_pk_bf16_f32 v156, v156, v157
	v_cvt_pk_bf16_f32 v157, v158, v159
	v_cvt_pk_bf16_f32 v158, v164, v165
	v_cvt_pk_bf16_f32 v159, v162, v163
	global_store_dwordx4 v[160:161], v[156:159], off
	v_pk_mul_f32 v[164:165], v[116:117], v[92:93]
	v_pk_mul_f32 v[166:167], v[114:115], v[90:91]
	v_lshlrev_b64 v[156:157], 12, v[150:151]
	v_lshl_add_u64 v[156:157], s[72:73], 0, v[156:157]
	v_lshl_add_u64 v[156:157], v[156:157], 0, s[18:19]
	v_lshl_add_u64 v[162:163], v[156:157], 0, v[144:145]
	v_pk_mul_f32 v[158:159], v[120:121], v[96:97]
	v_pk_mul_f32 v[156:157], v[118:119], v[94:95]
	s_nop 0
	v_cvt_pk_bf16_f32 v156, v156, v157
	v_cvt_pk_bf16_f32 v157, v158, v159
	v_cvt_pk_bf16_f32 v158, v166, v167
	v_cvt_pk_bf16_f32 v159, v164, v165
	global_store_dwordx4 v[162:163], v[156:159], off
	v_pk_mul_f32 v[164:165], v[100:101], v[76:77]
	v_pk_mul_f32 v[166:167], v[98:99], v[74:75]
	v_lshlrev_b64 v[156:157], 12, v[148:149]
	v_lshl_add_u64 v[156:157], s[72:73], 0, v[156:157]
	v_lshl_add_u64 v[156:157], v[156:157], 0, s[18:19]
	v_lshl_add_u64 v[162:163], v[156:157], 0, v[144:145]
	v_pk_mul_f32 v[158:159], v[104:105], v[80:81]
	v_pk_mul_f32 v[156:157], v[102:103], v[78:79]
	s_nop 0
	v_cvt_pk_bf16_f32 v156, v156, v157
	v_cvt_pk_bf16_f32 v157, v158, v159
	v_cvt_pk_bf16_f32 v158, v166, v167
	v_cvt_pk_bf16_f32 v159, v164, v165
	global_store_dwordx4 v[162:163], v[156:159], off
	v_pk_mul_f32 v[164:165], v[84:85], v[68:69]
	v_pk_mul_f32 v[166:167], v[82:83], v[66:67]
	v_lshlrev_b64 v[156:157], 12, v[146:147]
	v_lshl_add_u64 v[156:157], s[72:73], 0, v[156:157]
	v_lshl_add_u64 v[156:157], v[156:157], 0, s[18:19]
	v_lshl_add_u64 v[162:163], v[156:157], 0, v[144:145]
	v_pk_mul_f32 v[158:159], v[88:89], v[72:73]
	v_pk_mul_f32 v[156:157], v[86:87], v[70:71]
	s_mov_b32 s18, 0x80000
	v_cvt_pk_bf16_f32 v156, v156, v157
	v_cvt_pk_bf16_f32 v157, v158, v159
	v_cvt_pk_bf16_f32 v158, v166, v167
	v_cvt_pk_bf16_f32 v159, v164, v165
	global_store_dwordx4 v[162:163], v[156:159], off
	v_pk_mul_f32 v[162:163], v[60:61], v[44:45]
	v_pk_mul_f32 v[164:165], v[58:59], v[42:43]
	v_pk_mul_f32 v[158:159], v[64:65], v[48:49]
	v_pk_mul_f32 v[156:157], v[62:63], v[46:47]
	s_nop 0
	v_cvt_pk_bf16_f32 v156, v156, v157
	v_cvt_pk_bf16_f32 v157, v158, v159
	v_cvt_pk_bf16_f32 v159, v162, v163
	v_add_co_u32_e32 v162, vcc, s18, v160
	v_cvt_pk_bf16_f32 v158, v164, v165
	s_nop 0
	v_addc_co_u32_e32 v163, vcc, 0, v161, vcc
	global_store_dwordx4 v[162:163], v[156:159], off
	v_pk_mul_f32 v[162:163], v[52:53], v[28:29]
	s_mov_b32 s18, 0x90000
	v_pk_mul_f32 v[158:159], v[56:57], v[32:33]
	v_pk_mul_f32 v[156:157], v[54:55], v[30:31]
	v_pk_mul_f32 v[164:165], v[50:51], v[26:27]
	v_cvt_pk_bf16_f32 v156, v156, v157
	v_cvt_pk_bf16_f32 v157, v158, v159
	v_cvt_pk_bf16_f32 v159, v162, v163
	v_add_co_u32_e32 v162, vcc, s18, v160
	v_cvt_pk_bf16_f32 v158, v164, v165
	s_nop 0
	v_addc_co_u32_e32 v163, vcc, 0, v161, vcc
	global_store_dwordx4 v[162:163], v[156:159], off
	v_pk_mul_f32 v[162:163], v[36:37], v[12:13]
	s_mov_b32 s18, 0xa0000
	v_pk_mul_f32 v[158:159], v[40:41], v[16:17]
	v_pk_mul_f32 v[156:157], v[38:39], v[14:15]
	v_pk_mul_f32 v[164:165], v[34:35], v[10:11]
	v_cvt_pk_bf16_f32 v156, v156, v157
	v_cvt_pk_bf16_f32 v157, v158, v159
	v_cvt_pk_bf16_f32 v159, v162, v163
	v_add_co_u32_e32 v162, vcc, s18, v160
	v_cvt_pk_bf16_f32 v158, v164, v165
	s_nop 0
	v_addc_co_u32_e32 v163, vcc, 0, v161, vcc
	global_store_dwordx4 v[162:163], v[156:159], off
	v_pk_mul_f32 v[162:163], v[20:21], v[4:5]
	v_pk_mul_f32 v[164:165], v[18:19], v[2:3]
	v_pk_mul_f32 v[158:159], v[24:25], v[8:9]
	v_pk_mul_f32 v[156:157], v[22:23], v[6:7]
	v_add_co_u32_e32 v160, vcc, 0xb0000, v160
	v_cvt_pk_bf16_f32 v156, v156, v157
	v_cvt_pk_bf16_f32 v157, v158, v159
	v_cvt_pk_bf16_f32 v158, v164, v165
	v_cvt_pk_bf16_f32 v159, v162, v163
	v_addc_co_u32_e32 v161, vcc, 0, v161, vcc
	s_mov_b64 s[18:19], 0
	global_store_dwordx4 v[160:161], v[156:159], off

.LBB0_649:
	s_add_u32 s18, s38, vcc_lo
	s_addc_u32 s19, s39, vcc_hi
	s_add_u32 s18, s18, 0x100
	s_addc_u32 s19, s19, 0
	s_add_u32 s57, s50, vcc_lo
	s_addc_u32 s58, s51, vcc_hi
	s_add_i32 s59, 0, 0x10000
	s_cmpk_eq_i32 vcc_lo, 0xf00
	s_cselect_b32 s23, s52, s19
	s_cselect_b32 s22, s53, s18
	s_cselect_b32 s19, s54, s58
	s_cselect_b32 s18, s55, s57
	v_lshl_add_u64 v[162:163], v[142:143], 0, vcc
	s_add_i32 m0, s28, 0xc000
	ds_read_b128 v[170:173], v148
	ds_read_b128 v[174:177], v148 offset:1024
	ds_read_b128 v[192:195], v148 offset:2048
	ds_read_b128 v[196:199], v148 offset:3072
	ds_read_b128 v[200:203], v148 offset:4096
	ds_read_b128 v[204:207], v148 offset:5120
	ds_read_b128 v[208:211], v148 offset:6144
	ds_read_b128 v[224:227], v148 offset:7168
	global_load_lds_dwordx4 v[162:163], off
	s_add_i32 m0, s28, 0xe000
	v_lshl_add_u64 v[162:163], v[144:145], 0, vcc
	global_load_lds_dwordx4 v[162:163], off
	s_barrier
	s_waitcnt lgkmcnt(0)
	v_mfma_f32_16x16x32_bf16 v[90:93], v[150:153], v[170:173], v[90:93]
	v_mfma_f32_16x16x32_bf16 v[94:97], v[158:161], v[170:173], v[94:97]
	v_mfma_f32_16x16x32_bf16 v[102:105], v[150:153], v[192:195], v[102:105]
	v_mfma_f32_16x16x32_bf16 v[106:109], v[158:161], v[192:195], v[106:109]
	v_mfma_f32_16x16x32_bf16 v[114:117], v[150:153], v[200:203], v[114:117]
	v_mfma_f32_16x16x32_bf16 v[118:121], v[158:161], v[200:203], v[118:121]
	v_mfma_f32_16x16x32_bf16 v[122:125], v[150:153], v[208:211], v[122:125]
	v_mfma_f32_16x16x32_bf16 v[126:129], v[158:161], v[208:211], v[126:129]
	v_mfma_f32_16x16x32_bf16 v[90:93], v[154:157], v[174:177], v[90:93]
	v_mfma_f32_16x16x32_bf16 v[94:97], v[166:169], v[174:177], v[94:97]
	v_mfma_f32_16x16x32_bf16 v[102:105], v[154:157], v[196:199], v[102:105]
	v_mfma_f32_16x16x32_bf16 v[106:109], v[166:169], v[196:199], v[106:109]
	v_mfma_f32_16x16x32_bf16 v[114:117], v[154:157], v[204:207], v[114:117]
	v_mfma_f32_16x16x32_bf16 v[118:121], v[166:169], v[204:207], v[118:121]
	v_mfma_f32_16x16x32_bf16 v[122:125], v[154:157], v[224:227], v[122:125]
	v_mfma_f32_16x16x32_bf16 v[126:129], v[166:169], v[224:227], v[126:129]
	s_barrier
	s_add_i32 s57, 0, 0x14000
	s_add_i32 s58, s59, s85
	v_add_u32_e32 v149, s57, v147
	v_lshl_add_u64 v[162:163], s[18:19], 0, v[134:135]
	s_mov_b32 m0, s58
	ds_read_b128 v[228:231], v149
	ds_read_b128 v[232:235], v149 offset:1024
	ds_read_b128 v[236:239], v149 offset:2048
	ds_read_b128 v[240:243], v149 offset:3072
	global_load_lds_dwordx4 v[162:163], off
	s_add_i32 m0, s58, 0x2000
	v_lshl_add_u64 v[178:179], s[18:19], 0, v[130:131]
	global_load_lds_dwordx4 v[178:179], off
	s_mov_b32 m0, s28
	v_lshl_add_u64 v[212:213], s[22:23], 0, v[136:137]
	s_waitcnt lgkmcnt(0)
	s_barrier
	v_mfma_f32_16x16x32_bf16 v[10:13], v[228:231], v[170:173], v[10:13]
	v_mfma_f32_16x16x32_bf16 v[14:17], v[236:239], v[170:173], v[14:17]
	v_mfma_f32_16x16x32_bf16 v[26:29], v[228:231], v[192:195], v[26:29]
	v_mfma_f32_16x16x32_bf16 v[38:41], v[236:239], v[192:195], v[38:41]
	v_mfma_f32_16x16x32_bf16 v[58:61], v[228:231], v[200:203], v[58:61]
	v_mfma_f32_16x16x32_bf16 v[62:65], v[236:239], v[200:203], v[62:65]
	v_mfma_f32_16x16x32_bf16 v[74:77], v[228:231], v[208:211], v[74:77]
	v_mfma_f32_16x16x32_bf16 v[78:81], v[236:239], v[208:211], v[78:81]
	v_mfma_f32_16x16x32_bf16 v[10:13], v[232:235], v[174:177], v[10:13]
	v_mfma_f32_16x16x32_bf16 v[14:17], v[240:243], v[174:177], v[14:17]
	v_mfma_f32_16x16x32_bf16 v[26:29], v[232:235], v[196:199], v[26:29]
	v_mfma_f32_16x16x32_bf16 v[38:41], v[240:243], v[196:199], v[38:41]
	v_mfma_f32_16x16x32_bf16 v[58:61], v[232:235], v[204:207], v[58:61]
	v_mfma_f32_16x16x32_bf16 v[62:65], v[240:243], v[204:207], v[62:65]
	v_mfma_f32_16x16x32_bf16 v[74:77], v[232:235], v[224:227], v[74:77]
	v_mfma_f32_16x16x32_bf16 v[78:81], v[240:243], v[224:227], v[78:81]
	s_barrier
	ds_read_b128 v[170:173], v148 offset:16384
	ds_read_b128 v[174:177], v148 offset:17408
	ds_read_b128 v[192:195], v148 offset:18432
	ds_read_b128 v[196:199], v148 offset:19456
	ds_read_b128 v[200:203], v148 offset:20480
	ds_read_b128 v[204:207], v148 offset:21504
	ds_read_b128 v[208:211], v148 offset:22528
	ds_read_b128 v[224:227], v148 offset:23552
	global_load_lds_dwordx4 v[212:213], off
	s_mov_b32 m0, s29
	v_lshl_add_u64 v[244:245], s[22:23], 0, v[132:133]
	global_load_lds_dwordx4 v[244:245], off
	s_waitcnt vmcnt(10)
	s_barrier
	s_waitcnt lgkmcnt(0)
	v_mfma_f32_16x16x32_bf16 v[110:113], v[150:153], v[170:173], v[110:113]
	v_mfma_f32_16x16x32_bf16 v[98:101], v[158:161], v[170:173], v[98:101]
	v_mfma_f32_16x16x32_bf16 v[82:85], v[150:153], v[192:195], v[82:85]
	v_mfma_f32_16x16x32_bf16 v[66:69], v[158:161], v[192:195], v[66:69]
	v_mfma_f32_16x16x32_bf16 v[50:53], v[150:153], v[200:203], v[50:53]
	v_mfma_f32_16x16x32_bf16 v[42:45], v[158:161], v[200:203], v[42:45]
	v_mfma_f32_16x16x32_bf16 v[30:33], v[150:153], v[208:211], v[30:33]
	v_mfma_f32_16x16x32_bf16 v[18:21], v[158:161], v[208:211], v[18:21]
	v_mfma_f32_16x16x32_bf16 v[110:113], v[154:157], v[174:177], v[110:113]
	v_mfma_f32_16x16x32_bf16 v[98:101], v[166:169], v[174:177], v[98:101]
	v_mfma_f32_16x16x32_bf16 v[82:85], v[154:157], v[196:199], v[82:85]
	v_mfma_f32_16x16x32_bf16 v[66:69], v[166:169], v[196:199], v[66:69]
	v_mfma_f32_16x16x32_bf16 v[50:53], v[154:157], v[204:207], v[50:53]
	v_mfma_f32_16x16x32_bf16 v[42:45], v[166:169], v[204:207], v[42:45]
	v_mfma_f32_16x16x32_bf16 v[30:33], v[154:157], v[224:227], v[30:33]
	v_mfma_f32_16x16x32_bf16 v[18:21], v[166:169], v[224:227], v[18:21]
	s_barrier
	s_add_u32 s58, s18, 0x80000
	s_addc_u32 s59, s19, 0
	s_add_i32 s57, s57, s85
	s_mov_b32 m0, s57
	v_lshl_add_u64 v[150:151], s[58:59], 0, v[134:135]
	global_load_lds_dwordx4 v[150:151], off
	s_add_i32 m0, s57, 0x2000
	v_lshl_add_u64 v[150:151], s[58:59], 0, v[130:131]
	global_load_lds_dwordx4 v[150:151], off
	v_add_u32_e32 v149, 0x18000, v147
	ds_read_b128 v[150:153], v149
	ds_read_b128 v[154:157], v149 offset:1024
	ds_read_b128 v[158:161], v149 offset:2048
	ds_read_b128 v[166:169], v149 offset:3072
	s_add_i32 s57, 0, 0x18000
	s_waitcnt vmcnt(6)
	s_barrier
	v_mfma_f32_16x16x32_bf16 v[86:89], v[228:231], v[170:173], v[86:89]
	v_mfma_f32_16x16x32_bf16 v[70:73], v[236:239], v[170:173], v[70:73]
	v_mfma_f32_16x16x32_bf16 v[54:57], v[228:231], v[192:195], v[54:57]
	v_mfma_f32_16x16x32_bf16 v[46:49], v[236:239], v[192:195], v[46:49]
	v_mfma_f32_16x16x32_bf16 v[34:37], v[228:231], v[200:203], v[34:37]
	v_mfma_f32_16x16x32_bf16 v[22:25], v[236:239], v[200:203], v[22:25]
	v_mfma_f32_16x16x32_bf16 v[6:9], v[228:231], v[208:211], v[6:9]
	v_mfma_f32_16x16x32_bf16 v[2:5], v[236:239], v[208:211], v[2:5]
	v_mfma_f32_16x16x32_bf16 v[86:89], v[232:235], v[174:177], v[86:89]
	v_mfma_f32_16x16x32_bf16 v[70:73], v[240:243], v[174:177], v[70:73]
	v_mfma_f32_16x16x32_bf16 v[54:57], v[232:235], v[196:199], v[54:57]
	v_mfma_f32_16x16x32_bf16 v[46:49], v[240:243], v[196:199], v[46:49]
	v_mfma_f32_16x16x32_bf16 v[34:37], v[232:235], v[204:207], v[34:37]
	v_mfma_f32_16x16x32_bf16 v[22:25], v[240:243], v[204:207], v[22:25]
	v_mfma_f32_16x16x32_bf16 v[6:9], v[232:235], v[224:227], v[6:9]
	v_mfma_f32_16x16x32_bf16 v[2:5], v[240:243], v[224:227], v[2:5]
	s_barrier
	s_add_u32 s22, s22, 0x80000
	s_addc_u32 s23, s23, 0
	s_mov_b32 m0, s97
	v_lshl_add_u64 v[228:229], s[22:23], 0, v[136:137]
	ds_read_b128 v[170:173], v148 offset:32768
	ds_read_b128 v[174:177], v148 offset:33792
	ds_read_b128 v[192:195], v148 offset:34816
	ds_read_b128 v[196:199], v148 offset:35840
	ds_read_b128 v[200:203], v148 offset:36864
	ds_read_b128 v[204:207], v148 offset:37888
	ds_read_b128 v[208:211], v148 offset:38912
	ds_read_b128 v[224:227], v148 offset:39936
	global_load_lds_dwordx4 v[228:229], off
	s_mov_b32 m0, s44
	v_lshl_add_u64 v[228:229], s[22:23], 0, v[132:133]
	global_load_lds_dwordx4 v[228:229], off
	s_barrier
	s_waitcnt lgkmcnt(0)
	v_mfma_f32_16x16x32_bf16 v[90:93], v[150:153], v[170:173], v[90:93]
	v_mfma_f32_16x16x32_bf16 v[94:97], v[158:161], v[170:173], v[94:97]
	v_mfma_f32_16x16x32_bf16 v[102:105], v[150:153], v[192:195], v[102:105]
	v_mfma_f32_16x16x32_bf16 v[106:109], v[158:161], v[192:195], v[106:109]
	v_mfma_f32_16x16x32_bf16 v[114:117], v[150:153], v[200:203], v[114:117]
	v_mfma_f32_16x16x32_bf16 v[118:121], v[158:161], v[200:203], v[118:121]
	v_mfma_f32_16x16x32_bf16 v[122:125], v[150:153], v[208:211], v[122:125]
	v_mfma_f32_16x16x32_bf16 v[126:129], v[158:161], v[208:211], v[126:129]
	v_mfma_f32_16x16x32_bf16 v[90:93], v[154:157], v[174:177], v[90:93]
	v_mfma_f32_16x16x32_bf16 v[94:97], v[166:169], v[174:177], v[94:97]
	v_mfma_f32_16x16x32_bf16 v[102:105], v[154:157], v[196:199], v[102:105]
	v_mfma_f32_16x16x32_bf16 v[106:109], v[166:169], v[196:199], v[106:109]
	v_mfma_f32_16x16x32_bf16 v[114:117], v[154:157], v[204:207], v[114:117]
	v_mfma_f32_16x16x32_bf16 v[118:121], v[166:169], v[204:207], v[118:121]
	v_mfma_f32_16x16x32_bf16 v[122:125], v[154:157], v[224:227], v[122:125]
	v_mfma_f32_16x16x32_bf16 v[126:129], v[166:169], v[224:227], v[126:129]
	s_barrier
	s_add_i32 s22, 0, 0x1c000
	s_add_i32 s23, s57, s85
	v_add_u32_e32 v149, s22, v147
	v_lshl_add_u64 v[162:163], v[162:163], 0, s[78:79]
	s_mov_b32 m0, s23
	ds_read_b128 v[228:231], v149
	ds_read_b128 v[232:235], v149 offset:1024
	ds_read_b128 v[236:239], v149 offset:2048
	ds_read_b128 v[240:243], v149 offset:3072
	global_load_lds_dwordx4 v[162:163], off
	s_add_i32 m0, s23, 0x2000
	v_lshl_add_u64 v[162:163], v[178:179], 0, s[78:79]
	global_load_lds_dwordx4 v[162:163], off
	s_mov_b32 m0, s46
	v_lshl_add_u64 v[162:163], v[212:213], 0, s[78:79]
	s_waitcnt lgkmcnt(0)
	s_barrier
	v_mfma_f32_16x16x32_bf16 v[10:13], v[228:231], v[170:173], v[10:13]
	v_mfma_f32_16x16x32_bf16 v[14:17], v[236:239], v[170:173], v[14:17]
	v_mfma_f32_16x16x32_bf16 v[26:29], v[228:231], v[192:195], v[26:29]
	v_mfma_f32_16x16x32_bf16 v[38:41], v[236:239], v[192:195], v[38:41]
	v_mfma_f32_16x16x32_bf16 v[58:61], v[228:231], v[200:203], v[58:61]
	v_mfma_f32_16x16x32_bf16 v[62:65], v[236:239], v[200:203], v[62:65]
	v_mfma_f32_16x16x32_bf16 v[74:77], v[228:231], v[208:211], v[74:77]
	v_mfma_f32_16x16x32_bf16 v[78:81], v[236:239], v[208:211], v[78:81]
	v_mfma_f32_16x16x32_bf16 v[10:13], v[232:235], v[174:177], v[10:13]
	v_mfma_f32_16x16x32_bf16 v[14:17], v[240:243], v[174:177], v[14:17]
	v_mfma_f32_16x16x32_bf16 v[26:29], v[232:235], v[196:199], v[26:29]
	v_mfma_f32_16x16x32_bf16 v[38:41], v[240:243], v[196:199], v[38:41]
	v_mfma_f32_16x16x32_bf16 v[58:61], v[232:235], v[204:207], v[58:61]
	v_mfma_f32_16x16x32_bf16 v[62:65], v[240:243], v[204:207], v[62:65]
	v_mfma_f32_16x16x32_bf16 v[74:77], v[232:235], v[224:227], v[74:77]
	v_mfma_f32_16x16x32_bf16 v[78:81], v[240:243], v[224:227], v[78:81]
	s_barrier
	ds_read_b128 v[170:173], v148 offset:49152
	ds_read_b128 v[174:177], v148 offset:50176
	ds_read_b128 v[192:195], v148 offset:51200
	ds_read_b128 v[196:199], v148 offset:52224
	ds_read_b128 v[200:203], v148 offset:53248
	ds_read_b128 v[204:207], v148 offset:54272
	ds_read_b128 v[208:211], v148 offset:55296
	ds_read_b128 v[224:227], v148 offset:56320
	global_load_lds_dwordx4 v[162:163], off
	s_mov_b32 m0, s47
	v_lshl_add_u64 v[162:163], v[244:245], 0, s[78:79]
	global_load_lds_dwordx4 v[162:163], off
	s_waitcnt vmcnt(10)
	s_barrier
	s_waitcnt lgkmcnt(0)
	v_mfma_f32_16x16x32_bf16 v[110:113], v[150:153], v[170:173], v[110:113]
	v_mfma_f32_16x16x32_bf16 v[98:101], v[158:161], v[170:173], v[98:101]
	v_mfma_f32_16x16x32_bf16 v[82:85], v[150:153], v[192:195], v[82:85]
	v_mfma_f32_16x16x32_bf16 v[66:69], v[158:161], v[192:195], v[66:69]
	v_mfma_f32_16x16x32_bf16 v[50:53], v[150:153], v[200:203], v[50:53]
	v_mfma_f32_16x16x32_bf16 v[42:45], v[158:161], v[200:203], v[42:45]
	v_mfma_f32_16x16x32_bf16 v[30:33], v[150:153], v[208:211], v[30:33]
	v_mfma_f32_16x16x32_bf16 v[18:21], v[158:161], v[208:211], v[18:21]
	v_mfma_f32_16x16x32_bf16 v[110:113], v[154:157], v[174:177], v[110:113]
	v_mfma_f32_16x16x32_bf16 v[98:101], v[166:169], v[174:177], v[98:101]
	v_mfma_f32_16x16x32_bf16 v[82:85], v[154:157], v[196:199], v[82:85]
	v_mfma_f32_16x16x32_bf16 v[66:69], v[166:169], v[196:199], v[66:69]
	v_mfma_f32_16x16x32_bf16 v[50:53], v[154:157], v[204:207], v[50:53]
	v_mfma_f32_16x16x32_bf16 v[42:45], v[166:169], v[204:207], v[42:45]
	v_mfma_f32_16x16x32_bf16 v[30:33], v[154:157], v[224:227], v[30:33]
	v_mfma_f32_16x16x32_bf16 v[18:21], v[166:169], v[224:227], v[18:21]
	s_barrier
	s_add_u32 s18, s18, 0x80080
	s_addc_u32 s19, s19, 0
	s_add_i32 s22, s22, s85
	s_mov_b32 m0, s22
	v_lshl_add_u64 v[150:151], s[18:19], 0, v[134:135]
	global_load_lds_dwordx4 v[150:151], off
	s_add_i32 m0, s22, 0x2000
	v_lshl_add_u64 v[150:151], s[18:19], 0, v[130:131]
	global_load_lds_dwordx4 v[150:151], off
	v_add_u32_e32 v149, 0x10000, v147
	ds_read_b128 v[150:153], v149
	ds_read_b128 v[154:157], v149 offset:1024
	ds_read_b128 v[158:161], v149 offset:2048
	ds_read_b128 v[166:169], v149 offset:3072
	s_add_i32 s56, s56, 2
	s_add_u32 vcc_lo, vcc_lo, 0x100
	s_addc_u32 vcc_hi, vcc_hi, 0
	s_cmp_gt_u32 s56, 29
	s_waitcnt vmcnt(6)
	s_barrier
	v_mfma_f32_16x16x32_bf16 v[86:89], v[228:231], v[170:173], v[86:89]
	v_mfma_f32_16x16x32_bf16 v[70:73], v[236:239], v[170:173], v[70:73]
	v_mfma_f32_16x16x32_bf16 v[54:57], v[228:231], v[192:195], v[54:57]
	v_mfma_f32_16x16x32_bf16 v[46:49], v[236:239], v[192:195], v[46:49]
	v_mfma_f32_16x16x32_bf16 v[34:37], v[228:231], v[200:203], v[34:37]
	v_mfma_f32_16x16x32_bf16 v[22:25], v[236:239], v[200:203], v[22:25]
	v_mfma_f32_16x16x32_bf16 v[6:9], v[228:231], v[208:211], v[6:9]
	v_mfma_f32_16x16x32_bf16 v[2:5], v[236:239], v[208:211], v[2:5]
	v_mfma_f32_16x16x32_bf16 v[86:89], v[232:235], v[174:177], v[86:89]
	v_mfma_f32_16x16x32_bf16 v[70:73], v[240:243], v[174:177], v[70:73]
	v_mfma_f32_16x16x32_bf16 v[54:57], v[232:235], v[196:199], v[54:57]
	v_mfma_f32_16x16x32_bf16 v[46:49], v[240:243], v[196:199], v[46:49]
	v_mfma_f32_16x16x32_bf16 v[34:37], v[232:235], v[204:207], v[34:37]
	v_mfma_f32_16x16x32_bf16 v[22:25], v[240:243], v[204:207], v[22:25]
	v_mfma_f32_16x16x32_bf16 v[6:9], v[232:235], v[224:227], v[6:9]
	v_mfma_f32_16x16x32_bf16 v[2:5], v[240:243], v[224:227], v[2:5]
	s_barrier
	s_cbranch_scc0 .LBB0_649
	s_waitcnt lgkmcnt(0)
	s_add_u32 s18, s50, 0xffffff00
	s_addc_u32 s19, s51, -1
	s_andn2_b64 vcc, exec, s[42:43]
	s_cbranch_vccnz .LBB0_652
	v_mov_b32_e32 v2, 0
	s_mov_b32 s84, s80
	s_mov_b32 s25, s82
	s_mov_b64 s[38:39], s[20:21]
	s_mov_b32 s48, s49
	v_mov_b32_e32 v3, v2
	v_mov_b32_e32 v4, v2
	v_mov_b32_e32 v5, v2
	v_mov_b32_e32 v6, v2
	v_mov_b32_e32 v7, v2
	v_mov_b32_e32 v8, v2
	v_mov_b32_e32 v9, v2
	v_mov_b32_e32 v22, v2
	v_mov_b32_e32 v23, v2
	v_mov_b32_e32 v24, v2
	v_mov_b32_e32 v25, v2
	v_mov_b32_e32 v34, v2
	v_mov_b32_e32 v35, v2
	v_mov_b32_e32 v36, v2
	v_mov_b32_e32 v37, v2
	v_mov_b32_e32 v46, v2
	v_mov_b32_e32 v47, v2
	v_mov_b32_e32 v48, v2
	v_mov_b32_e32 v49, v2
	v_mov_b32_e32 v54, v2
	v_mov_b32_e32 v55, v2
	v_mov_b32_e32 v56, v2
	v_mov_b32_e32 v57, v2
	v_mov_b32_e32 v70, v2
	v_mov_b32_e32 v71, v2
	v_mov_b32_e32 v72, v2
	v_mov_b32_e32 v73, v2
	v_mov_b32_e32 v86, v2
	v_mov_b32_e32 v87, v2
	v_mov_b32_e32 v88, v2
	v_mov_b32_e32 v89, v2
	v_mov_b32_e32 v18, v2
	v_mov_b32_e32 v19, v2
	v_mov_b32_e32 v20, v2
	v_mov_b32_e32 v21, v2
	v_mov_b32_e32 v30, v2
	v_mov_b32_e32 v31, v2
	v_mov_b32_e32 v32, v2
	v_mov_b32_e32 v33, v2
	v_mov_b32_e32 v42, v2
	v_mov_b32_e32 v43, v2
	v_mov_b32_e32 v44, v2
	v_mov_b32_e32 v45, v2
	v_mov_b32_e32 v50, v2
	v_mov_b32_e32 v51, v2
	v_mov_b32_e32 v52, v2
	v_mov_b32_e32 v53, v2
	v_mov_b32_e32 v66, v2
	v_mov_b32_e32 v67, v2
	v_mov_b32_e32 v68, v2
	v_mov_b32_e32 v69, v2
	v_mov_b32_e32 v82, v2
	v_mov_b32_e32 v83, v2
	v_mov_b32_e32 v84, v2
	v_mov_b32_e32 v85, v2
	v_mov_b32_e32 v98, v2
	v_mov_b32_e32 v99, v2
	v_mov_b32_e32 v100, v2
	v_mov_b32_e32 v101, v2
	v_mov_b32_e32 v110, v2
	v_mov_b32_e32 v111, v2
	v_mov_b32_e32 v112, v2
	v_mov_b32_e32 v113, v2
	v_mov_b32_e32 v78, v2
	v_mov_b32_e32 v79, v2
	v_mov_b32_e32 v80, v2
	v_mov_b32_e32 v81, v2
	v_mov_b32_e32 v74, v2
	v_mov_b32_e32 v75, v2
	v_mov_b32_e32 v76, v2
	v_mov_b32_e32 v77, v2
	v_mov_b32_e32 v62, v2
	v_mov_b32_e32 v63, v2
	v_mov_b32_e32 v64, v2
	v_mov_b32_e32 v65, v2
	v_mov_b32_e32 v58, v2
	v_mov_b32_e32 v59, v2
	v_mov_b32_e32 v60, v2
	v_mov_b32_e32 v61, v2
	v_mov_b32_e32 v38, v2
	v_mov_b32_e32 v39, v2
	v_mov_b32_e32 v40, v2
	v_mov_b32_e32 v41, v2
	v_mov_b32_e32 v26, v2
	v_mov_b32_e32 v27, v2
	v_mov_b32_e32 v28, v2
	v_mov_b32_e32 v29, v2
	v_mov_b32_e32 v14, v2
	v_mov_b32_e32 v15, v2
	v_mov_b32_e32 v16, v2
	v_mov_b32_e32 v17, v2
	v_mov_b32_e32 v10, v2
	v_mov_b32_e32 v11, v2
	v_mov_b32_e32 v12, v2
	v_mov_b32_e32 v13, v2
	v_mov_b32_e32 v126, v2
	v_mov_b32_e32 v127, v2
	v_mov_b32_e32 v128, v2
	v_mov_b32_e32 v129, v2
	v_mov_b32_e32 v122, v2
	v_mov_b32_e32 v123, v2
	v_mov_b32_e32 v124, v2
	v_mov_b32_e32 v125, v2
	v_mov_b32_e32 v118, v2
	v_mov_b32_e32 v119, v2
	v_mov_b32_e32 v120, v2
	v_mov_b32_e32 v121, v2
	v_mov_b32_e32 v114, v2
	v_mov_b32_e32 v115, v2
	v_mov_b32_e32 v116, v2
	v_mov_b32_e32 v117, v2
	v_mov_b32_e32 v106, v2
	v_mov_b32_e32 v107, v2
	v_mov_b32_e32 v108, v2
	v_mov_b32_e32 v109, v2
	v_mov_b32_e32 v102, v2
	v_mov_b32_e32 v103, v2
	v_mov_b32_e32 v104, v2
	v_mov_b32_e32 v105, v2
	v_mov_b32_e32 v94, v2
	v_mov_b32_e32 v95, v2
	v_mov_b32_e32 v96, v2
	v_mov_b32_e32 v97, v2
	v_mov_b32_e32 v90, v2
	v_mov_b32_e32 v91, v2
	v_mov_b32_e32 v92, v2
	v_mov_b32_e32 v93, v2
	s_andn2_b64 vcc, exec, s[0:1]
	s_cbranch_vccnz .LBB0_653
	s_branch .LBB0_654

.LBB0_749:
	s_add_u32 s20, s18, 0xfff80080
	s_addc_u32 s21, s19, -1
	s_add_i32 s58, 0, 0x10000
	s_cmp_eq_u32 s57, 28
	s_cselect_b32 s23, s39, s21
	s_cselect_b32 s22, s53, s20
	s_cselect_b32 s21, s31, s56
	s_cselect_b32 s20, s54, s55
	v_lshl_add_u64 v[212:213], s[18:19], 0, v[154:155]
	s_add_i32 m0, s44, 0xc000
	ds_read_b128 v[176:179], v158
	ds_read_b128 v[192:195], v158 offset:1024
	ds_read_b128 v[196:199], v158 offset:2048
	ds_read_b128 v[200:203], v158 offset:3072
	ds_read_b128 v[204:207], v158 offset:4096
	ds_read_b128 v[208:211], v158 offset:5120
	ds_read_b128 v[224:227], v158 offset:6144
	ds_read_b128 v[228:231], v158 offset:7168
	global_load_lds_dwordx4 v[212:213], off
	s_add_i32 m0, s44, 0xe000
	v_lshl_add_u64 v[212:213], s[18:19], 0, v[156:157]
	global_load_lds_dwordx4 v[212:213], off
	s_barrier
	s_waitcnt lgkmcnt(0)
	v_mfma_f32_16x16x32_bf16 v[126:129], v[160:163], v[176:179], v[126:129]
	v_mfma_f32_16x16x32_bf16 v[122:125], v[168:171], v[176:179], v[122:125]
	v_mfma_f32_16x16x32_bf16 v[110:113], v[160:163], v[196:199], v[110:113]
	v_mfma_f32_16x16x32_bf16 v[106:109], v[168:171], v[196:199], v[106:109]
	v_mfma_f32_16x16x32_bf16 v[94:97], v[160:163], v[204:207], v[94:97]
	v_mfma_f32_16x16x32_bf16 v[90:93], v[168:171], v[204:207], v[90:93]
	v_mfma_f32_16x16x32_bf16 v[78:81], v[160:163], v[224:227], v[78:81]
	v_mfma_f32_16x16x32_bf16 v[74:77], v[168:171], v[224:227], v[74:77]
	v_mfma_f32_16x16x32_bf16 v[126:129], v[164:167], v[192:195], v[126:129]
	v_mfma_f32_16x16x32_bf16 v[122:125], v[172:175], v[192:195], v[122:125]
	v_mfma_f32_16x16x32_bf16 v[110:113], v[164:167], v[200:203], v[110:113]
	v_mfma_f32_16x16x32_bf16 v[106:109], v[172:175], v[200:203], v[106:109]
	v_mfma_f32_16x16x32_bf16 v[94:97], v[164:167], v[208:211], v[94:97]
	v_mfma_f32_16x16x32_bf16 v[90:93], v[172:175], v[208:211], v[90:93]
	v_mfma_f32_16x16x32_bf16 v[78:81], v[164:167], v[228:231], v[78:81]
	v_mfma_f32_16x16x32_bf16 v[74:77], v[172:175], v[228:231], v[74:77]
	s_barrier
	s_add_i32 s82, 0, 0x14000
	s_add_i32 s58, s58, s29
	v_add_u32_e32 v159, s82, v1
	v_lshl_add_u64 v[212:213], s[20:21], 0, v[134:135]
	s_mov_b32 m0, s58
	ds_read_b128 v[232:235], v159
	ds_read_b128 v[236:239], v159 offset:1024
	ds_read_b128 v[240:243], v159 offset:2048
	ds_read_b128 v[244:247], v159 offset:3072
	global_load_lds_dwordx4 v[212:213], off
	s_add_i32 m0, s58, 0x2000
	v_lshl_add_u64 v[248:249], s[20:21], 0, v[130:131]
	global_load_lds_dwordx4 v[248:249], off
	s_mov_b32 m0, s44
	v_lshl_add_u64 v[250:251], s[22:23], 0, v[136:137]
	s_waitcnt lgkmcnt(0)
	s_barrier
	v_mfma_f32_16x16x32_bf16 v[118:121], v[232:235], v[176:179], v[118:121]
	v_mfma_f32_16x16x32_bf16 v[114:117], v[240:243], v[176:179], v[114:117]
	v_mfma_f32_16x16x32_bf16 v[102:105], v[232:235], v[196:199], v[102:105]
	v_mfma_f32_16x16x32_bf16 v[98:101], v[240:243], v[196:199], v[98:101]
	v_mfma_f32_16x16x32_bf16 v[86:89], v[232:235], v[204:207], v[86:89]
	v_mfma_f32_16x16x32_bf16 v[82:85], v[240:243], v[204:207], v[82:85]
	v_mfma_f32_16x16x32_bf16 v[70:73], v[232:235], v[224:227], v[70:73]
	v_mfma_f32_16x16x32_bf16 v[66:69], v[240:243], v[224:227], v[66:69]
	v_mfma_f32_16x16x32_bf16 v[118:121], v[236:239], v[192:195], v[118:121]
	v_mfma_f32_16x16x32_bf16 v[114:117], v[244:247], v[192:195], v[114:117]
	v_mfma_f32_16x16x32_bf16 v[102:105], v[236:239], v[200:203], v[102:105]
	v_mfma_f32_16x16x32_bf16 v[98:101], v[244:247], v[200:203], v[98:101]
	v_mfma_f32_16x16x32_bf16 v[86:89], v[236:239], v[208:211], v[86:89]
	v_mfma_f32_16x16x32_bf16 v[82:85], v[244:247], v[208:211], v[82:85]
	v_mfma_f32_16x16x32_bf16 v[70:73], v[236:239], v[228:231], v[70:73]
	v_mfma_f32_16x16x32_bf16 v[66:69], v[244:247], v[228:231], v[66:69]
	s_barrier
	ds_read_b128 v[176:179], v158 offset:16384
	ds_read_b128 v[192:195], v158 offset:17408
	ds_read_b128 v[196:199], v158 offset:18432
	ds_read_b128 v[200:203], v158 offset:19456
	ds_read_b128 v[204:207], v158 offset:20480
	ds_read_b128 v[208:211], v158 offset:21504
	ds_read_b128 v[224:227], v158 offset:22528
	ds_read_b128 v[228:231], v158 offset:23552
	global_load_lds_dwordx4 v[250:251], off
	s_mov_b32 m0, s45
	v_lshl_add_u64 v[222:223], s[22:23], 0, v[132:133]
	global_load_lds_dwordx4 v[222:223], off
	s_waitcnt vmcnt(10)
	s_barrier
	s_waitcnt lgkmcnt(0)
	v_mfma_f32_16x16x32_bf16 v[62:65], v[160:163], v[176:179], v[62:65]
	v_mfma_f32_16x16x32_bf16 v[58:61], v[168:171], v[176:179], v[58:61]
	v_mfma_f32_16x16x32_bf16 v[46:49], v[160:163], v[196:199], v[46:49]
	v_mfma_f32_16x16x32_bf16 v[42:45], v[168:171], v[196:199], v[42:45]
	v_mfma_f32_16x16x32_bf16 v[30:33], v[160:163], v[204:207], v[30:33]
	v_mfma_f32_16x16x32_bf16 v[26:29], v[168:171], v[204:207], v[26:29]
	v_mfma_f32_16x16x32_bf16 v[14:17], v[160:163], v[224:227], v[14:17]
	v_mfma_f32_16x16x32_bf16 v[10:13], v[168:171], v[224:227], v[10:13]
	v_mfma_f32_16x16x32_bf16 v[62:65], v[164:167], v[192:195], v[62:65]
	v_mfma_f32_16x16x32_bf16 v[58:61], v[172:175], v[192:195], v[58:61]
	v_mfma_f32_16x16x32_bf16 v[46:49], v[164:167], v[200:203], v[46:49]
	v_mfma_f32_16x16x32_bf16 v[42:45], v[172:175], v[200:203], v[42:45]
	v_mfma_f32_16x16x32_bf16 v[30:33], v[164:167], v[208:211], v[30:33]
	v_mfma_f32_16x16x32_bf16 v[26:29], v[172:175], v[208:211], v[26:29]
	v_mfma_f32_16x16x32_bf16 v[14:17], v[164:167], v[228:231], v[14:17]
	v_mfma_f32_16x16x32_bf16 v[10:13], v[172:175], v[228:231], v[10:13]
	s_barrier
	s_add_u32 s58, s20, 0x80000
	s_addc_u32 s59, s21, 0
	s_add_i32 s82, s82, s29
	s_mov_b32 m0, s82
	v_lshl_add_u64 v[160:161], s[58:59], 0, v[134:135]
	global_load_lds_dwordx4 v[160:161], off
	s_add_i32 m0, s82, 0x2000
	v_lshl_add_u64 v[160:161], s[58:59], 0, v[130:131]
	global_load_lds_dwordx4 v[160:161], off
	v_add_u32_e32 v159, 0x18000, v1
	ds_read_b128 v[160:163], v159
	ds_read_b128 v[164:167], v159 offset:1024
	ds_read_b128 v[168:171], v159 offset:2048
	ds_read_b128 v[172:175], v159 offset:3072
	s_add_i32 s58, 0, 0x18000
	s_waitcnt vmcnt(6)
	s_barrier
	v_mfma_f32_16x16x32_bf16 v[54:57], v[232:235], v[176:179], v[54:57]
	v_mfma_f32_16x16x32_bf16 v[50:53], v[240:243], v[176:179], v[50:53]
	v_mfma_f32_16x16x32_bf16 v[38:41], v[232:235], v[196:199], v[38:41]
	v_mfma_f32_16x16x32_bf16 v[34:37], v[240:243], v[196:199], v[34:37]
	v_mfma_f32_16x16x32_bf16 v[22:25], v[232:235], v[204:207], v[22:25]
	v_mfma_f32_16x16x32_bf16 v[18:21], v[240:243], v[204:207], v[18:21]
	v_mfma_f32_16x16x32_bf16 v[6:9], v[232:235], v[224:227], v[6:9]
	v_mfma_f32_16x16x32_bf16 v[2:5], v[240:243], v[224:227], v[2:5]
	v_mfma_f32_16x16x32_bf16 v[54:57], v[236:239], v[192:195], v[54:57]
	v_mfma_f32_16x16x32_bf16 v[50:53], v[244:247], v[192:195], v[50:53]
	v_mfma_f32_16x16x32_bf16 v[38:41], v[236:239], v[200:203], v[38:41]
	v_mfma_f32_16x16x32_bf16 v[34:37], v[244:247], v[200:203], v[34:37]
	v_mfma_f32_16x16x32_bf16 v[22:25], v[236:239], v[208:211], v[22:25]
	v_mfma_f32_16x16x32_bf16 v[18:21], v[244:247], v[208:211], v[18:21]
	v_mfma_f32_16x16x32_bf16 v[6:9], v[236:239], v[228:231], v[6:9]
	v_mfma_f32_16x16x32_bf16 v[2:5], v[244:247], v[228:231], v[2:5]
	s_barrier
	s_add_u32 s22, s22, 0x80000
	s_addc_u32 s23, s23, 0
	s_mov_b32 m0, s46
	v_lshl_add_u64 v[232:233], s[22:23], 0, v[136:137]
	ds_read_b128 v[176:179], v158 offset:32768
	ds_read_b128 v[192:195], v158 offset:33792
	ds_read_b128 v[196:199], v158 offset:34816
	ds_read_b128 v[200:203], v158 offset:35840
	ds_read_b128 v[204:207], v158 offset:36864
	ds_read_b128 v[208:211], v158 offset:37888
	ds_read_b128 v[224:227], v158 offset:38912
	ds_read_b128 v[228:231], v158 offset:39936
	global_load_lds_dwordx4 v[232:233], off
	s_mov_b32 m0, s47
	v_lshl_add_u64 v[232:233], s[22:23], 0, v[132:133]
	global_load_lds_dwordx4 v[232:233], off
	s_barrier
	s_waitcnt lgkmcnt(0)
	v_mfma_f32_16x16x32_bf16 v[126:129], v[160:163], v[176:179], v[126:129]
	v_mfma_f32_16x16x32_bf16 v[122:125], v[168:171], v[176:179], v[122:125]
	v_mfma_f32_16x16x32_bf16 v[110:113], v[160:163], v[196:199], v[110:113]
	v_mfma_f32_16x16x32_bf16 v[106:109], v[168:171], v[196:199], v[106:109]
	v_mfma_f32_16x16x32_bf16 v[94:97], v[160:163], v[204:207], v[94:97]
	v_mfma_f32_16x16x32_bf16 v[90:93], v[168:171], v[204:207], v[90:93]
	v_mfma_f32_16x16x32_bf16 v[78:81], v[160:163], v[224:227], v[78:81]
	v_mfma_f32_16x16x32_bf16 v[74:77], v[168:171], v[224:227], v[74:77]
	v_mfma_f32_16x16x32_bf16 v[126:129], v[164:167], v[192:195], v[126:129]
	v_mfma_f32_16x16x32_bf16 v[122:125], v[172:175], v[192:195], v[122:125]
	v_mfma_f32_16x16x32_bf16 v[110:113], v[164:167], v[200:203], v[110:113]
	v_mfma_f32_16x16x32_bf16 v[106:109], v[172:175], v[200:203], v[106:109]
	v_mfma_f32_16x16x32_bf16 v[94:97], v[164:167], v[208:211], v[94:97]
	v_mfma_f32_16x16x32_bf16 v[90:93], v[172:175], v[208:211], v[90:93]
	v_mfma_f32_16x16x32_bf16 v[78:81], v[164:167], v[228:231], v[78:81]
	v_mfma_f32_16x16x32_bf16 v[74:77], v[172:175], v[228:231], v[74:77]
	s_barrier
	s_add_i32 s22, 0, 0x1c000
	s_add_i32 s23, s58, s29
	v_add_u32_e32 v159, s22, v1
	v_lshl_add_u64 v[212:213], v[212:213], 0, s[78:79]
	s_mov_b32 m0, s23
	ds_read_b128 v[232:235], v159
	ds_read_b128 v[236:239], v159 offset:1024
	ds_read_b128 v[240:243], v159 offset:2048
	ds_read_b128 v[244:247], v159 offset:3072
	global_load_lds_dwordx4 v[212:213], off
	s_add_i32 m0, s23, 0x2000
	v_lshl_add_u64 v[212:213], v[248:249], 0, s[78:79]
	global_load_lds_dwordx4 v[212:213], off
	s_mov_b32 m0, s48
	v_lshl_add_u64 v[212:213], v[250:251], 0, s[78:79]
	s_waitcnt lgkmcnt(0)
	s_barrier
	v_mfma_f32_16x16x32_bf16 v[118:121], v[232:235], v[176:179], v[118:121]
	v_mfma_f32_16x16x32_bf16 v[114:117], v[240:243], v[176:179], v[114:117]
	v_mfma_f32_16x16x32_bf16 v[102:105], v[232:235], v[196:199], v[102:105]
	v_mfma_f32_16x16x32_bf16 v[98:101], v[240:243], v[196:199], v[98:101]
	v_mfma_f32_16x16x32_bf16 v[86:89], v[232:235], v[204:207], v[86:89]
	v_mfma_f32_16x16x32_bf16 v[82:85], v[240:243], v[204:207], v[82:85]
	v_mfma_f32_16x16x32_bf16 v[70:73], v[232:235], v[224:227], v[70:73]
	v_mfma_f32_16x16x32_bf16 v[66:69], v[240:243], v[224:227], v[66:69]
	v_mfma_f32_16x16x32_bf16 v[118:121], v[236:239], v[192:195], v[118:121]
	v_mfma_f32_16x16x32_bf16 v[114:117], v[244:247], v[192:195], v[114:117]
	v_mfma_f32_16x16x32_bf16 v[102:105], v[236:239], v[200:203], v[102:105]
	v_mfma_f32_16x16x32_bf16 v[98:101], v[244:247], v[200:203], v[98:101]
	v_mfma_f32_16x16x32_bf16 v[86:89], v[236:239], v[208:211], v[86:89]
	v_mfma_f32_16x16x32_bf16 v[82:85], v[244:247], v[208:211], v[82:85]
	v_mfma_f32_16x16x32_bf16 v[70:73], v[236:239], v[228:231], v[70:73]
	v_mfma_f32_16x16x32_bf16 v[66:69], v[244:247], v[228:231], v[66:69]
	s_barrier
	ds_read_b128 v[176:179], v158 offset:49152
	ds_read_b128 v[192:195], v158 offset:50176
	ds_read_b128 v[196:199], v158 offset:51200
	ds_read_b128 v[200:203], v158 offset:52224
	ds_read_b128 v[204:207], v158 offset:53248
	ds_read_b128 v[208:211], v158 offset:54272
	ds_read_b128 v[224:227], v158 offset:55296
	ds_read_b128 v[228:231], v158 offset:56320
	global_load_lds_dwordx4 v[212:213], off
	s_mov_b32 m0, s49
	v_lshl_add_u64 v[212:213], v[222:223], 0, s[78:79]
	global_load_lds_dwordx4 v[212:213], off
	s_waitcnt vmcnt(10)
	s_barrier
	s_waitcnt lgkmcnt(0)
	v_mfma_f32_16x16x32_bf16 v[62:65], v[160:163], v[176:179], v[62:65]
	v_mfma_f32_16x16x32_bf16 v[58:61], v[168:171], v[176:179], v[58:61]
	v_mfma_f32_16x16x32_bf16 v[46:49], v[160:163], v[196:199], v[46:49]
	v_mfma_f32_16x16x32_bf16 v[42:45], v[168:171], v[196:199], v[42:45]
	v_mfma_f32_16x16x32_bf16 v[30:33], v[160:163], v[204:207], v[30:33]
	v_mfma_f32_16x16x32_bf16 v[26:29], v[168:171], v[204:207], v[26:29]
	v_mfma_f32_16x16x32_bf16 v[14:17], v[160:163], v[224:227], v[14:17]
	v_mfma_f32_16x16x32_bf16 v[10:13], v[168:171], v[224:227], v[10:13]
	v_mfma_f32_16x16x32_bf16 v[62:65], v[164:167], v[192:195], v[62:65]
	v_mfma_f32_16x16x32_bf16 v[58:61], v[172:175], v[192:195], v[58:61]
	v_mfma_f32_16x16x32_bf16 v[46:49], v[164:167], v[200:203], v[46:49]
	v_mfma_f32_16x16x32_bf16 v[42:45], v[172:175], v[200:203], v[42:45]
	v_mfma_f32_16x16x32_bf16 v[30:33], v[164:167], v[208:211], v[30:33]
	v_mfma_f32_16x16x32_bf16 v[26:29], v[172:175], v[208:211], v[26:29]
	v_mfma_f32_16x16x32_bf16 v[14:17], v[164:167], v[228:231], v[14:17]
	v_mfma_f32_16x16x32_bf16 v[10:13], v[172:175], v[228:231], v[10:13]
	s_barrier
	s_add_u32 s20, s20, 0x80080
	s_addc_u32 s21, s21, 0
	s_add_i32 s22, s22, s29
	s_mov_b32 m0, s22
	v_lshl_add_u64 v[160:161], s[20:21], 0, v[134:135]
	global_load_lds_dwordx4 v[160:161], off
	s_add_i32 m0, s22, 0x2000
	v_lshl_add_u64 v[160:161], s[20:21], 0, v[130:131]
	global_load_lds_dwordx4 v[160:161], off
	v_add_u32_e32 v159, 0x10000, v1
	ds_read_b128 v[160:163], v159
	ds_read_b128 v[164:167], v159 offset:1024
	ds_read_b128 v[168:171], v159 offset:2048
	ds_read_b128 v[172:175], v159 offset:3072
	s_add_i32 s57, s57, 2
	s_add_u32 s18, s18, 0x100
	s_addc_u32 s19, s19, 0
	s_add_u32 s55, s55, 0x100
	s_addc_u32 s56, s56, 0
	s_cmp_gt_u32 s57, 29
	s_waitcnt vmcnt(6)
	s_barrier
	v_mfma_f32_16x16x32_bf16 v[54:57], v[232:235], v[176:179], v[54:57]
	v_mfma_f32_16x16x32_bf16 v[50:53], v[240:243], v[176:179], v[50:53]
	v_mfma_f32_16x16x32_bf16 v[38:41], v[232:235], v[196:199], v[38:41]
	v_mfma_f32_16x16x32_bf16 v[34:37], v[240:243], v[196:199], v[34:37]
	v_mfma_f32_16x16x32_bf16 v[22:25], v[232:235], v[204:207], v[22:25]
	v_mfma_f32_16x16x32_bf16 v[18:21], v[240:243], v[204:207], v[18:21]
	v_mfma_f32_16x16x32_bf16 v[6:9], v[232:235], v[224:227], v[6:9]
	v_mfma_f32_16x16x32_bf16 v[2:5], v[240:243], v[224:227], v[2:5]
	v_mfma_f32_16x16x32_bf16 v[54:57], v[236:239], v[192:195], v[54:57]
	v_mfma_f32_16x16x32_bf16 v[50:53], v[244:247], v[192:195], v[50:53]
	v_mfma_f32_16x16x32_bf16 v[38:41], v[236:239], v[200:203], v[38:41]
	v_mfma_f32_16x16x32_bf16 v[34:37], v[244:247], v[200:203], v[34:37]
	v_mfma_f32_16x16x32_bf16 v[22:25], v[236:239], v[208:211], v[22:25]
	v_mfma_f32_16x16x32_bf16 v[18:21], v[244:247], v[208:211], v[18:21]
	v_mfma_f32_16x16x32_bf16 v[6:9], v[236:239], v[228:231], v[6:9]
	v_mfma_f32_16x16x32_bf16 v[2:5], v[244:247], v[228:231], v[2:5]
	s_barrier
	s_cbranch_scc0 .LBB0_749
	s_waitcnt lgkmcnt(0)
	s_lshl_b32 s18, s52, 5
	s_add_i32 s18, s18, s51
	v_max_f32_e32 v122, 0, v122
	v_max_f32_e32 v123, 0, v123
	s_ashr_i32 s19, s18, 31
	v_pk_mul_f32 v[162:163], v[122:123], v[122:123]
	v_max_f32_e32 v123, v124, v124
	s_lshl_b64 s[18:19], s[18:19], 17
	v_max_f32_e32 v122, v128, v128
	v_max_f32_e32 v124, 0, v123
	v_max_f32_e32 v123, v129, v129
	s_add_u32 s18, s68, s18
	v_max_f32_e32 v126, 0, v126
	v_max_f32_e32 v127, 0, v127
	v_max_f32_e32 v122, 0, v122
	v_max_f32_e32 v123, 0, v123
	v_max_f32_e32 v125, 0, v125
	s_addc_u32 s19, s69, s19
	v_pk_mul_f32 v[126:127], v[126:127], v[126:127]
	v_pk_mul_f32 v[128:129], v[122:123], v[122:123]
	v_pk_mul_f32 v[164:165], v[124:125], v[124:125]
	v_lshl_add_u64 v[160:161], v[138:139], 1, s[18:19]
	v_cvt_pk_bf16_f32 v122, v126, v127
	v_cvt_pk_bf16_f32 v123, v128, v129
	v_cvt_pk_bf16_f32 v124, v162, v163
	v_cvt_pk_bf16_f32 v125, v164, v165
	v_max_f32_e32 v114, 0, v114
	v_max_f32_e32 v115, 0, v115
	global_store_dwordx4 v[160:161], v[122:125], off
	v_max_f32_e32 v118, v118, v118
	v_max_f32_e32 v119, v119, v119
	v_pk_mul_f32 v[122:123], v[114:115], v[114:115]
	v_max_f32_e32 v115, v116, v116
	v_max_f32_e32 v114, v120, v120
	v_max_f32_e32 v116, 0, v115
	v_max_f32_e32 v115, v121, v121
	v_max_f32_e32 v118, 0, v118
	v_max_f32_e32 v119, 0, v119
	v_max_f32_e32 v114, 0, v114
	v_max_f32_e32 v115, 0, v115
	v_max_f32_e32 v117, 0, v117
	v_pk_mul_f32 v[118:119], v[118:119], v[118:119]
	v_pk_mul_f32 v[120:121], v[114:115], v[114:115]
	v_pk_mul_f32 v[124:125], v[116:117], v[116:117]
	v_cvt_pk_bf16_f32 v114, v118, v119
	v_cvt_pk_bf16_f32 v115, v120, v121
	v_cvt_pk_bf16_f32 v116, v122, v123
	v_cvt_pk_bf16_f32 v117, v124, v125
	v_max_f32_e32 v106, 0, v106
	v_max_f32_e32 v107, 0, v107
	global_store_dwordx4 v[160:161], v[114:117], off offset:256
	v_max_f32_e32 v110, v110, v110
	v_max_f32_e32 v111, v111, v111
	v_pk_mul_f32 v[116:117], v[106:107], v[106:107]
	v_max_f32_e32 v107, v108, v108
	v_max_f32_e32 v106, v112, v112
	v_max_f32_e32 v108, 0, v107
	v_max_f32_e32 v107, v113, v113
	v_max_f32_e32 v110, 0, v110
	v_max_f32_e32 v111, 0, v111
	v_max_f32_e32 v106, 0, v106
	v_max_f32_e32 v107, 0, v107
	v_max_f32_e32 v109, 0, v109
	v_pk_mul_f32 v[110:111], v[110:111], v[110:111]
	v_pk_mul_f32 v[112:113], v[106:107], v[106:107]
	v_pk_mul_f32 v[118:119], v[108:109], v[108:109]
	v_lshl_add_u64 v[114:115], v[140:141], 1, s[18:19]
	v_cvt_pk_bf16_f32 v106, v110, v111
	v_cvt_pk_bf16_f32 v107, v112, v113
	v_cvt_pk_bf16_f32 v108, v116, v117
	v_cvt_pk_bf16_f32 v109, v118, v119
	v_max_f32_e32 v98, 0, v98
	v_max_f32_e32 v99, 0, v99
	global_store_dwordx4 v[114:115], v[106:109], off
	v_max_f32_e32 v102, v102, v102
	v_max_f32_e32 v103, v103, v103
	v_pk_mul_f32 v[106:107], v[98:99], v[98:99]
	v_max_f32_e32 v99, v100, v100
	v_max_f32_e32 v98, v104, v104
	v_max_f32_e32 v100, 0, v99
	v_max_f32_e32 v99, v105, v105
	v_max_f32_e32 v102, 0, v102
	v_max_f32_e32 v103, 0, v103
	v_max_f32_e32 v98, 0, v98
	v_max_f32_e32 v99, 0, v99
	v_max_f32_e32 v101, 0, v101
	v_pk_mul_f32 v[102:103], v[102:103], v[102:103]
	v_pk_mul_f32 v[104:105], v[98:99], v[98:99]
	v_pk_mul_f32 v[108:109], v[100:101], v[100:101]
	v_cvt_pk_bf16_f32 v98, v102, v103
	v_cvt_pk_bf16_f32 v99, v104, v105
	v_cvt_pk_bf16_f32 v100, v106, v107
	v_cvt_pk_bf16_f32 v101, v108, v109
	v_max_f32_e32 v90, 0, v90
	v_max_f32_e32 v91, 0, v91
	global_store_dwordx4 v[114:115], v[98:101], off offset:256
	v_max_f32_e32 v94, v94, v94
	v_max_f32_e32 v95, v95, v95
	v_pk_mul_f32 v[100:101], v[90:91], v[90:91]
	v_max_f32_e32 v91, v92, v92
	v_max_f32_e32 v90, v96, v96
	v_max_f32_e32 v92, 0, v91
	v_max_f32_e32 v91, v97, v97
	v_max_f32_e32 v94, 0, v94
	v_max_f32_e32 v95, 0, v95
	v_max_f32_e32 v90, 0, v90
	v_max_f32_e32 v91, 0, v91
	v_max_f32_e32 v93, 0, v93
	v_pk_mul_f32 v[94:95], v[94:95], v[94:95]
	v_pk_mul_f32 v[96:97], v[90:91], v[90:91]
	v_pk_mul_f32 v[102:103], v[92:93], v[92:93]
	v_lshl_add_u64 v[98:99], v[142:143], 1, s[18:19]
	v_cvt_pk_bf16_f32 v90, v94, v95
	v_cvt_pk_bf16_f32 v91, v96, v97
	v_cvt_pk_bf16_f32 v92, v100, v101
	v_cvt_pk_bf16_f32 v93, v102, v103
	v_max_f32_e32 v82, 0, v82
	v_max_f32_e32 v83, 0, v83
	global_store_dwordx4 v[98:99], v[90:93], off
	v_max_f32_e32 v86, v86, v86
	v_max_f32_e32 v87, v87, v87
	v_pk_mul_f32 v[90:91], v[82:83], v[82:83]
	v_max_f32_e32 v83, v84, v84
	v_max_f32_e32 v82, v88, v88
	v_max_f32_e32 v84, 0, v83
	v_max_f32_e32 v83, v89, v89
	v_max_f32_e32 v86, 0, v86
	v_max_f32_e32 v87, 0, v87
	v_max_f32_e32 v82, 0, v82
	v_max_f32_e32 v83, 0, v83
	v_max_f32_e32 v85, 0, v85
	v_pk_mul_f32 v[86:87], v[86:87], v[86:87]
	v_pk_mul_f32 v[88:89], v[82:83], v[82:83]
	v_pk_mul_f32 v[92:93], v[84:85], v[84:85]
	v_cvt_pk_bf16_f32 v82, v86, v87
	v_cvt_pk_bf16_f32 v83, v88, v89
	v_cvt_pk_bf16_f32 v84, v90, v91
	v_cvt_pk_bf16_f32 v85, v92, v93
	v_max_f32_e32 v74, 0, v74
	v_max_f32_e32 v75, 0, v75
	global_store_dwordx4 v[98:99], v[82:85], off offset:256
	v_max_f32_e32 v78, v78, v78
	v_max_f32_e32 v79, v79, v79
	v_pk_mul_f32 v[84:85], v[74:75], v[74:75]
	v_max_f32_e32 v75, v76, v76
	v_max_f32_e32 v74, v80, v80
	v_max_f32_e32 v76, 0, v75
	v_max_f32_e32 v75, v81, v81
	v_max_f32_e32 v78, 0, v78
	v_max_f32_e32 v79, 0, v79
	v_max_f32_e32 v74, 0, v74
	v_max_f32_e32 v75, 0, v75
	v_max_f32_e32 v77, 0, v77
	v_pk_mul_f32 v[78:79], v[78:79], v[78:79]
	v_pk_mul_f32 v[80:81], v[74:75], v[74:75]
	v_pk_mul_f32 v[86:87], v[76:77], v[76:77]
	v_lshl_add_u64 v[82:83], v[144:145], 1, s[18:19]
	v_cvt_pk_bf16_f32 v74, v78, v79
	v_cvt_pk_bf16_f32 v75, v80, v81
	v_cvt_pk_bf16_f32 v76, v84, v85
	v_cvt_pk_bf16_f32 v77, v86, v87
	v_max_f32_e32 v66, 0, v66
	v_max_f32_e32 v67, 0, v67
	global_store_dwordx4 v[82:83], v[74:77], off
	v_max_f32_e32 v70, v70, v70
	v_max_f32_e32 v71, v71, v71
	v_pk_mul_f32 v[74:75], v[66:67], v[66:67]
	v_max_f32_e32 v67, v68, v68
	v_max_f32_e32 v66, v72, v72
	v_max_f32_e32 v68, 0, v67
	v_max_f32_e32 v67, v73, v73
	v_max_f32_e32 v70, 0, v70
	v_max_f32_e32 v71, 0, v71
	v_max_f32_e32 v66, 0, v66
	v_max_f32_e32 v67, 0, v67
	v_max_f32_e32 v69, 0, v69
	v_pk_mul_f32 v[70:71], v[70:71], v[70:71]
	v_pk_mul_f32 v[72:73], v[66:67], v[66:67]
	v_pk_mul_f32 v[76:77], v[68:69], v[68:69]
	v_cvt_pk_bf16_f32 v66, v70, v71
	v_cvt_pk_bf16_f32 v67, v72, v73
	v_cvt_pk_bf16_f32 v68, v74, v75
	v_cvt_pk_bf16_f32 v69, v76, v77
	v_max_f32_e32 v58, 0, v58
	v_max_f32_e32 v59, 0, v59
	global_store_dwordx4 v[82:83], v[66:69], off offset:256
	v_max_f32_e32 v62, v62, v62
	v_max_f32_e32 v63, v63, v63
	v_pk_mul_f32 v[68:69], v[58:59], v[58:59]
	v_max_f32_e32 v59, v60, v60
	v_max_f32_e32 v58, v64, v64
	v_max_f32_e32 v60, 0, v59
	v_max_f32_e32 v59, v65, v65
	v_max_f32_e32 v62, 0, v62
	v_max_f32_e32 v63, 0, v63
	v_max_f32_e32 v58, 0, v58
	v_max_f32_e32 v59, 0, v59
	v_max_f32_e32 v61, 0, v61
	v_pk_mul_f32 v[62:63], v[62:63], v[62:63]
	v_pk_mul_f32 v[64:65], v[58:59], v[58:59]
	v_pk_mul_f32 v[70:71], v[60:61], v[60:61]
	v_lshl_add_u64 v[66:67], v[146:147], 1, s[18:19]
	v_cvt_pk_bf16_f32 v58, v62, v63
	v_cvt_pk_bf16_f32 v59, v64, v65
	v_cvt_pk_bf16_f32 v60, v68, v69
	v_cvt_pk_bf16_f32 v61, v70, v71
	v_max_f32_e32 v50, 0, v50
	v_max_f32_e32 v51, 0, v51
	global_store_dwordx4 v[66:67], v[58:61], off
	v_max_f32_e32 v54, v54, v54
	v_max_f32_e32 v55, v55, v55
	v_pk_mul_f32 v[58:59], v[50:51], v[50:51]
	v_max_f32_e32 v51, v52, v52
	v_max_f32_e32 v50, v56, v56
	v_max_f32_e32 v52, 0, v51
	v_max_f32_e32 v51, v57, v57
	v_max_f32_e32 v54, 0, v54
	v_max_f32_e32 v55, 0, v55
	v_max_f32_e32 v50, 0, v50
	v_max_f32_e32 v51, 0, v51
	v_max_f32_e32 v53, 0, v53
	v_pk_mul_f32 v[54:55], v[54:55], v[54:55]
	v_pk_mul_f32 v[56:57], v[50:51], v[50:51]
	v_pk_mul_f32 v[60:61], v[52:53], v[52:53]
	v_cvt_pk_bf16_f32 v50, v54, v55
	v_cvt_pk_bf16_f32 v51, v56, v57
	v_cvt_pk_bf16_f32 v52, v58, v59
	v_cvt_pk_bf16_f32 v53, v60, v61
	v_max_f32_e32 v42, 0, v42
	v_max_f32_e32 v43, 0, v43
	global_store_dwordx4 v[66:67], v[50:53], off offset:256
	v_max_f32_e32 v46, v46, v46
	v_max_f32_e32 v47, v47, v47
	v_pk_mul_f32 v[52:53], v[42:43], v[42:43]
	v_max_f32_e32 v43, v44, v44
	v_max_f32_e32 v42, v48, v48
	v_max_f32_e32 v44, 0, v43
	v_max_f32_e32 v43, v49, v49
	v_max_f32_e32 v46, 0, v46
	v_max_f32_e32 v47, 0, v47
	v_max_f32_e32 v42, 0, v42
	v_max_f32_e32 v43, 0, v43
	v_max_f32_e32 v45, 0, v45
	v_pk_mul_f32 v[46:47], v[46:47], v[46:47]
	v_pk_mul_f32 v[48:49], v[42:43], v[42:43]
	v_pk_mul_f32 v[54:55], v[44:45], v[44:45]
	v_lshl_add_u64 v[50:51], v[148:149], 1, s[18:19]
	v_cvt_pk_bf16_f32 v42, v46, v47
	v_cvt_pk_bf16_f32 v43, v48, v49
	v_cvt_pk_bf16_f32 v44, v52, v53
	v_cvt_pk_bf16_f32 v45, v54, v55
	v_max_f32_e32 v34, 0, v34
	v_max_f32_e32 v35, 0, v35
	global_store_dwordx4 v[50:51], v[42:45], off
	v_max_f32_e32 v38, v38, v38
	v_max_f32_e32 v39, v39, v39
	v_pk_mul_f32 v[42:43], v[34:35], v[34:35]
	v_max_f32_e32 v35, v36, v36
	v_max_f32_e32 v34, v40, v40
	v_max_f32_e32 v36, 0, v35
	v_max_f32_e32 v35, v41, v41
	v_max_f32_e32 v38, 0, v38
	v_max_f32_e32 v39, 0, v39
	v_max_f32_e32 v34, 0, v34
	v_max_f32_e32 v35, 0, v35
	v_max_f32_e32 v37, 0, v37
	v_pk_mul_f32 v[38:39], v[38:39], v[38:39]
	v_pk_mul_f32 v[40:41], v[34:35], v[34:35]
	v_pk_mul_f32 v[44:45], v[36:37], v[36:37]
	v_cvt_pk_bf16_f32 v34, v38, v39
	v_cvt_pk_bf16_f32 v35, v40, v41
	v_cvt_pk_bf16_f32 v36, v42, v43
	v_cvt_pk_bf16_f32 v37, v44, v45
	v_max_f32_e32 v26, 0, v26
	v_max_f32_e32 v27, 0, v27
	global_store_dwordx4 v[50:51], v[34:37], off offset:256
	v_max_f32_e32 v30, v30, v30
	v_max_f32_e32 v31, v31, v31
	v_pk_mul_f32 v[36:37], v[26:27], v[26:27]
	v_max_f32_e32 v27, v28, v28
	v_max_f32_e32 v26, v32, v32
	v_max_f32_e32 v28, 0, v27
	v_max_f32_e32 v27, v33, v33
	v_max_f32_e32 v30, 0, v30
	v_max_f32_e32 v31, 0, v31
	v_max_f32_e32 v26, 0, v26
	v_max_f32_e32 v27, 0, v27
	v_max_f32_e32 v29, 0, v29
	v_pk_mul_f32 v[30:31], v[30:31], v[30:31]
	v_pk_mul_f32 v[32:33], v[26:27], v[26:27]
	v_pk_mul_f32 v[38:39], v[28:29], v[28:29]
	v_lshl_add_u64 v[34:35], v[150:151], 1, s[18:19]
	v_cvt_pk_bf16_f32 v26, v30, v31
	v_cvt_pk_bf16_f32 v27, v32, v33
	v_cvt_pk_bf16_f32 v28, v36, v37
	v_cvt_pk_bf16_f32 v29, v38, v39
	v_max_f32_e32 v18, 0, v18
	v_max_f32_e32 v19, 0, v19
	global_store_dwordx4 v[34:35], v[26:29], off
	v_max_f32_e32 v22, v22, v22
	v_max_f32_e32 v23, v23, v23
	v_pk_mul_f32 v[26:27], v[18:19], v[18:19]
	v_max_f32_e32 v19, v20, v20
	v_max_f32_e32 v18, v24, v24
	v_max_f32_e32 v20, 0, v19
	v_max_f32_e32 v19, v25, v25
	v_max_f32_e32 v22, 0, v22
	v_max_f32_e32 v23, 0, v23
	v_max_f32_e32 v18, 0, v18
	v_max_f32_e32 v19, 0, v19
	v_max_f32_e32 v21, 0, v21
	v_pk_mul_f32 v[22:23], v[22:23], v[22:23]
	v_pk_mul_f32 v[24:25], v[18:19], v[18:19]
	v_pk_mul_f32 v[28:29], v[20:21], v[20:21]
	v_cvt_pk_bf16_f32 v18, v22, v23
	v_cvt_pk_bf16_f32 v19, v24, v25
	v_cvt_pk_bf16_f32 v20, v26, v27
	v_cvt_pk_bf16_f32 v21, v28, v29
	v_max_f32_e32 v10, 0, v10
	v_max_f32_e32 v11, 0, v11
	global_store_dwordx4 v[34:35], v[18:21], off offset:256
	v_max_f32_e32 v14, v14, v14
	v_max_f32_e32 v15, v15, v15
	v_pk_mul_f32 v[20:21], v[10:11], v[10:11]
	v_max_f32_e32 v11, v12, v12
	v_max_f32_e32 v10, v16, v16
	v_max_f32_e32 v12, 0, v11
	v_max_f32_e32 v11, v17, v17
	v_max_f32_e32 v14, 0, v14
	v_max_f32_e32 v15, 0, v15
	v_max_f32_e32 v10, 0, v10
	v_max_f32_e32 v11, 0, v11
	v_max_f32_e32 v13, 0, v13
	v_pk_mul_f32 v[14:15], v[14:15], v[14:15]
	v_pk_mul_f32 v[16:17], v[10:11], v[10:11]
	v_pk_mul_f32 v[22:23], v[12:13], v[12:13]
	v_lshl_add_u64 v[18:19], v[152:153], 1, s[18:19]
	v_cvt_pk_bf16_f32 v10, v14, v15
	v_cvt_pk_bf16_f32 v11, v16, v17
	v_cvt_pk_bf16_f32 v12, v20, v21
	v_cvt_pk_bf16_f32 v13, v22, v23
	v_max_f32_e32 v2, 0, v2
	v_max_f32_e32 v3, 0, v3
	global_store_dwordx4 v[18:19], v[10:13], off
	v_max_f32_e32 v6, v6, v6
	v_max_f32_e32 v7, v7, v7
	v_pk_mul_f32 v[10:11], v[2:3], v[2:3]
	v_max_f32_e32 v3, v4, v4
	v_max_f32_e32 v2, v8, v8
	v_max_f32_e32 v4, 0, v3
	v_max_f32_e32 v3, v9, v9
	v_max_f32_e32 v6, 0, v6
	v_max_f32_e32 v7, 0, v7
	v_max_f32_e32 v2, 0, v2
	v_max_f32_e32 v3, 0, v3
	v_max_f32_e32 v5, 0, v5
	v_pk_mul_f32 v[6:7], v[6:7], v[6:7]
	v_pk_mul_f32 v[8:9], v[2:3], v[2:3]
	v_pk_mul_f32 v[12:13], v[4:5], v[4:5]
	v_cvt_pk_bf16_f32 v2, v6, v7
	v_cvt_pk_bf16_f32 v3, v8, v9
	v_cvt_pk_bf16_f32 v4, v10, v11
	v_cvt_pk_bf16_f32 v5, v12, v13
	s_and_b64 vcc, exec, s[0:1]
	s_mov_b32 s51, s30
	s_mov_b32 s52, s38
	s_mov_b64 s[20:21], s[80:81]
	s_mov_b64 s[18:19], s[42:43]
	global_store_dwordx4 v[18:19], v[2:5], off offset:256
	s_cbranch_vccz .LBB0_742
	s_waitcnt vmcnt(0)
	v_readlane_b32 s38, v255, 28
	s_cmpk_gt_u32 s26, 0xff
	v_readlane_b32 s39, v255, 29
	v_readlane_b32 s42, v255, 32
	s_cbranch_scc1 .LBB0_753
	s_barrier

.LBB0_814:
	s_add_i32 s22, s55, 0xffff0000
	s_and_b32 s22, s22, 0x3e0000
	s_and_b32 s23, s90, 0x100
	s_or_b32 s56, s23, s22
	s_and_b32 s22, s55, 0x7e0000
	s_add_u32 vcc_lo, s90, 0x100
	s_addc_u32 vcc_hi, s91, 0
	s_and_b32 s23, vcc_lo, 0x100
	s_or_b32 s22, s22, s23
	s_add_u32 s22, s84, s22
	s_addc_u32 s23, s85, 0
	s_add_u32 s57, s30, s90
	s_addc_u32 s58, s31, s91
	s_add_u32 s57, s57, 0x100
	s_addc_u32 s58, s58, 0
	s_add_i32 s59, 0, 0x10000
	s_cmpk_eq_i32 s54, 0x7c
	s_cselect_b32 s91, s43, s58
	s_cselect_b32 s90, s53, s57
	s_cselect_b32 s23, s51, s23
	s_cselect_b32 s22, s52, s22
	s_add_u32 s56, s84, s56
	s_addc_u32 s57, s85, 0
	s_add_u32 s56, s56, 0x10080
	s_addc_u32 s57, s57, 0
	v_lshl_add_u64 v[204:205], s[56:57], 0, v[136:137]
	s_add_i32 m0, s28, 0xc000
	ds_read_b128 v[158:161], v140
	ds_read_b128 v[162:165], v140 offset:1024
	ds_read_b128 v[168:171], v140 offset:2048
	ds_read_b128 v[172:175], v140 offset:3072
	ds_read_b128 v[176:179], v140 offset:4096
	ds_read_b128 v[192:195], v140 offset:5120
	ds_read_b128 v[196:199], v140 offset:6144
	ds_read_b128 v[200:203], v140 offset:7168
	global_load_lds_dwordx4 v[204:205], off
	s_add_i32 m0, s28, 0xe000
	v_lshl_add_u64 v[204:205], s[56:57], 0, v[132:133]
	global_load_lds_dwordx4 v[204:205], off
	s_barrier
	s_waitcnt lgkmcnt(0)
	v_mfma_f32_16x16x32_bf16 v[86:89], v[142:145], v[158:161], v[86:89]
	v_mfma_f32_16x16x32_bf16 v[94:97], v[150:153], v[158:161], v[94:97]
	v_mfma_f32_16x16x32_bf16 v[98:101], v[142:145], v[168:171], v[98:101]
	v_mfma_f32_16x16x32_bf16 v[102:105], v[150:153], v[168:171], v[102:105]
	v_mfma_f32_16x16x32_bf16 v[114:117], v[142:145], v[176:179], v[114:117]
	v_mfma_f32_16x16x32_bf16 v[122:125], v[150:153], v[176:179], v[122:125]
	v_mfma_f32_16x16x32_bf16 v[126:129], v[142:145], v[196:199], v[126:129]
	v_mfma_f32_16x16x32_bf16 v[118:121], v[150:153], v[196:199], v[118:121]
	v_mfma_f32_16x16x32_bf16 v[86:89], v[146:149], v[162:165], v[86:89]
	v_mfma_f32_16x16x32_bf16 v[94:97], v[154:157], v[162:165], v[94:97]
	v_mfma_f32_16x16x32_bf16 v[98:101], v[146:149], v[172:175], v[98:101]
	v_mfma_f32_16x16x32_bf16 v[102:105], v[154:157], v[172:175], v[102:105]
	v_mfma_f32_16x16x32_bf16 v[114:117], v[146:149], v[192:195], v[114:117]
	v_mfma_f32_16x16x32_bf16 v[122:125], v[154:157], v[192:195], v[122:125]
	v_mfma_f32_16x16x32_bf16 v[126:129], v[146:149], v[200:203], v[126:129]
	v_mfma_f32_16x16x32_bf16 v[118:121], v[154:157], v[200:203], v[118:121]
	s_barrier
	s_add_i32 s58, 0, 0x14000
	s_add_i32 s56, s59, s81
	v_add_u32_e32 v141, s58, v139
	v_lshl_add_u64 v[212:213], s[90:91], 0, v[134:135]
	s_mov_b32 m0, s56
	ds_read_b128 v[204:207], v141
	ds_read_b128 v[208:211], v141 offset:1024
	ds_read_b128 v[224:227], v141 offset:2048
	ds_read_b128 v[228:231], v141 offset:3072
	global_load_lds_dwordx4 v[212:213], off
	s_add_i32 m0, s56, 0x2000
	v_lshl_add_u64 v[222:223], s[90:91], 0, v[130:131]
	global_load_lds_dwordx4 v[222:223], off
	s_mov_b32 m0, s28
	v_lshl_add_u64 v[232:233], s[22:23], 0, v[136:137]
	s_waitcnt lgkmcnt(0)
	s_barrier
	v_mfma_f32_16x16x32_bf16 v[2:5], v[204:207], v[158:161], v[2:5]
	v_mfma_f32_16x16x32_bf16 v[6:9], v[224:227], v[158:161], v[6:9]
	v_mfma_f32_16x16x32_bf16 v[10:13], v[204:207], v[168:171], v[10:13]
	v_mfma_f32_16x16x32_bf16 v[14:17], v[224:227], v[168:171], v[14:17]
	v_mfma_f32_16x16x32_bf16 v[22:25], v[204:207], v[176:179], v[22:25]
	v_mfma_f32_16x16x32_bf16 v[18:21], v[224:227], v[176:179], v[18:21]
	v_mfma_f32_16x16x32_bf16 v[30:33], v[204:207], v[196:199], v[30:33]
	v_mfma_f32_16x16x32_bf16 v[26:29], v[224:227], v[196:199], v[26:29]
	v_mfma_f32_16x16x32_bf16 v[2:5], v[208:211], v[162:165], v[2:5]
	v_mfma_f32_16x16x32_bf16 v[6:9], v[228:231], v[162:165], v[6:9]
	v_mfma_f32_16x16x32_bf16 v[10:13], v[208:211], v[172:175], v[10:13]
	v_mfma_f32_16x16x32_bf16 v[14:17], v[228:231], v[172:175], v[14:17]
	v_mfma_f32_16x16x32_bf16 v[22:25], v[208:211], v[192:195], v[22:25]
	v_mfma_f32_16x16x32_bf16 v[18:21], v[228:231], v[192:195], v[18:21]
	v_mfma_f32_16x16x32_bf16 v[30:33], v[208:211], v[200:203], v[30:33]
	v_mfma_f32_16x16x32_bf16 v[26:29], v[228:231], v[200:203], v[26:29]
	s_barrier
	ds_read_b128 v[158:161], v140 offset:16384
	ds_read_b128 v[162:165], v140 offset:17408
	ds_read_b128 v[168:171], v140 offset:18432
	ds_read_b128 v[172:175], v140 offset:19456
	ds_read_b128 v[176:179], v140 offset:20480
	ds_read_b128 v[192:195], v140 offset:21504
	ds_read_b128 v[196:199], v140 offset:22528
	ds_read_b128 v[200:203], v140 offset:23552
	global_load_lds_dwordx4 v[232:233], off
	s_mov_b32 m0, s29
	v_lshl_add_u64 v[234:235], s[22:23], 0, v[132:133]
	global_load_lds_dwordx4 v[234:235], off
	s_waitcnt vmcnt(10)
	s_barrier
	s_waitcnt lgkmcnt(0)
	v_mfma_f32_16x16x32_bf16 v[110:113], v[142:145], v[158:161], v[110:113]
	v_mfma_f32_16x16x32_bf16 v[106:109], v[150:153], v[158:161], v[106:109]
	v_mfma_f32_16x16x32_bf16 v[90:93], v[142:145], v[168:171], v[90:93]
	v_mfma_f32_16x16x32_bf16 v[82:85], v[150:153], v[168:171], v[82:85]
	v_mfma_f32_16x16x32_bf16 v[78:81], v[142:145], v[176:179], v[78:81]
	v_mfma_f32_16x16x32_bf16 v[74:77], v[150:153], v[176:179], v[74:77]
	v_mfma_f32_16x16x32_bf16 v[70:73], v[142:145], v[196:199], v[70:73]
	v_mfma_f32_16x16x32_bf16 v[66:69], v[150:153], v[196:199], v[66:69]
	v_mfma_f32_16x16x32_bf16 v[110:113], v[146:149], v[162:165], v[110:113]
	v_mfma_f32_16x16x32_bf16 v[106:109], v[154:157], v[162:165], v[106:109]
	v_mfma_f32_16x16x32_bf16 v[90:93], v[146:149], v[172:175], v[90:93]
	v_mfma_f32_16x16x32_bf16 v[82:85], v[154:157], v[172:175], v[82:85]
	v_mfma_f32_16x16x32_bf16 v[78:81], v[146:149], v[192:195], v[78:81]
	v_mfma_f32_16x16x32_bf16 v[74:77], v[154:157], v[192:195], v[74:77]
	v_mfma_f32_16x16x32_bf16 v[70:73], v[146:149], v[200:203], v[70:73]
	v_mfma_f32_16x16x32_bf16 v[66:69], v[154:157], v[200:203], v[66:69]
	s_barrier
	s_add_u32 s56, s90, 0x200000
	s_addc_u32 s57, s91, 0
	s_add_i32 s58, s58, s81
	s_mov_b32 m0, s58
	v_lshl_add_u64 v[142:143], s[56:57], 0, v[134:135]
	global_load_lds_dwordx4 v[142:143], off
	s_add_i32 m0, s58, 0x2000
	v_lshl_add_u64 v[142:143], s[56:57], 0, v[130:131]
	global_load_lds_dwordx4 v[142:143], off
	v_add_u32_e32 v141, 0x18000, v139
	ds_read_b128 v[142:145], v141
	ds_read_b128 v[146:149], v141 offset:1024
	ds_read_b128 v[150:153], v141 offset:2048
	ds_read_b128 v[154:157], v141 offset:3072
	s_add_i32 s56, 0, 0x18000
	s_waitcnt vmcnt(6)
	s_barrier
	v_mfma_f32_16x16x32_bf16 v[38:41], v[204:207], v[158:161], v[38:41]
	v_mfma_f32_16x16x32_bf16 v[34:37], v[224:227], v[158:161], v[34:37]
	v_mfma_f32_16x16x32_bf16 v[46:49], v[204:207], v[168:171], v[46:49]
	v_mfma_f32_16x16x32_bf16 v[42:45], v[224:227], v[168:171], v[42:45]
	v_mfma_f32_16x16x32_bf16 v[54:57], v[204:207], v[176:179], v[54:57]
	v_mfma_f32_16x16x32_bf16 v[50:53], v[224:227], v[176:179], v[50:53]
	v_mfma_f32_16x16x32_bf16 v[62:65], v[204:207], v[196:199], v[62:65]
	v_mfma_f32_16x16x32_bf16 v[58:61], v[224:227], v[196:199], v[58:61]
	v_mfma_f32_16x16x32_bf16 v[38:41], v[208:211], v[162:165], v[38:41]
	v_mfma_f32_16x16x32_bf16 v[34:37], v[228:231], v[162:165], v[34:37]
	v_mfma_f32_16x16x32_bf16 v[46:49], v[208:211], v[172:175], v[46:49]
	v_mfma_f32_16x16x32_bf16 v[42:45], v[228:231], v[172:175], v[42:45]
	v_mfma_f32_16x16x32_bf16 v[54:57], v[208:211], v[192:195], v[54:57]
	v_mfma_f32_16x16x32_bf16 v[50:53], v[228:231], v[192:195], v[50:53]
	v_mfma_f32_16x16x32_bf16 v[62:65], v[208:211], v[200:203], v[62:65]
	v_mfma_f32_16x16x32_bf16 v[58:61], v[228:231], v[200:203], v[58:61]
	s_barrier
	s_add_u32 s22, s22, 0x10000
	s_addc_u32 s23, s23, 0
	s_mov_b32 m0, s44
	v_lshl_add_u64 v[204:205], s[22:23], 0, v[136:137]
	ds_read_b128 v[158:161], v140 offset:32768
	ds_read_b128 v[162:165], v140 offset:33792
	ds_read_b128 v[168:171], v140 offset:34816
	ds_read_b128 v[172:175], v140 offset:35840
	ds_read_b128 v[176:179], v140 offset:36864
	ds_read_b128 v[192:195], v140 offset:37888
	ds_read_b128 v[196:199], v140 offset:38912
	ds_read_b128 v[200:203], v140 offset:39936
	global_load_lds_dwordx4 v[204:205], off
	s_mov_b32 m0, s45
	v_lshl_add_u64 v[204:205], s[22:23], 0, v[132:133]
	global_load_lds_dwordx4 v[204:205], off
	s_barrier
	s_waitcnt lgkmcnt(0)
	v_mfma_f32_16x16x32_bf16 v[86:89], v[142:145], v[158:161], v[86:89]
	v_mfma_f32_16x16x32_bf16 v[94:97], v[150:153], v[158:161], v[94:97]
	v_mfma_f32_16x16x32_bf16 v[98:101], v[142:145], v[168:171], v[98:101]
	v_mfma_f32_16x16x32_bf16 v[102:105], v[150:153], v[168:171], v[102:105]
	v_mfma_f32_16x16x32_bf16 v[114:117], v[142:145], v[176:179], v[114:117]
	v_mfma_f32_16x16x32_bf16 v[122:125], v[150:153], v[176:179], v[122:125]
	v_mfma_f32_16x16x32_bf16 v[126:129], v[142:145], v[196:199], v[126:129]
	v_mfma_f32_16x16x32_bf16 v[118:121], v[150:153], v[196:199], v[118:121]
	v_mfma_f32_16x16x32_bf16 v[86:89], v[146:149], v[162:165], v[86:89]
	v_mfma_f32_16x16x32_bf16 v[94:97], v[154:157], v[162:165], v[94:97]
	v_mfma_f32_16x16x32_bf16 v[98:101], v[146:149], v[172:175], v[98:101]
	v_mfma_f32_16x16x32_bf16 v[102:105], v[154:157], v[172:175], v[102:105]
	v_mfma_f32_16x16x32_bf16 v[114:117], v[146:149], v[192:195], v[114:117]
	v_mfma_f32_16x16x32_bf16 v[122:125], v[154:157], v[192:195], v[122:125]
	v_mfma_f32_16x16x32_bf16 v[126:129], v[146:149], v[200:203], v[126:129]
	v_mfma_f32_16x16x32_bf16 v[118:121], v[154:157], v[200:203], v[118:121]
	s_barrier
	s_add_i32 s57, 0, 0x1c000
	s_add_i32 s22, s56, s81
	v_add_u32_e32 v141, s57, v139
	v_lshl_add_u64 v[212:213], v[212:213], 0, s[78:79]
	s_mov_b32 m0, s22
	ds_read_b128 v[204:207], v141
	ds_read_b128 v[208:211], v141 offset:1024
	ds_read_b128 v[224:227], v141 offset:2048
	ds_read_b128 v[228:231], v141 offset:3072
	global_load_lds_dwordx4 v[212:213], off
	s_add_i32 m0, s22, 0x2000
	v_lshl_add_u64 v[212:213], v[222:223], 0, s[78:79]
	global_load_lds_dwordx4 v[212:213], off
	s_mov_b32 m0, s47
	v_lshl_add_u64 v[212:213], v[232:233], 0, s[78:79]
	s_waitcnt lgkmcnt(0)
	s_barrier
	v_mfma_f32_16x16x32_bf16 v[2:5], v[204:207], v[158:161], v[2:5]
	v_mfma_f32_16x16x32_bf16 v[6:9], v[224:227], v[158:161], v[6:9]
	v_mfma_f32_16x16x32_bf16 v[10:13], v[204:207], v[168:171], v[10:13]
	v_mfma_f32_16x16x32_bf16 v[14:17], v[224:227], v[168:171], v[14:17]
	v_mfma_f32_16x16x32_bf16 v[22:25], v[204:207], v[176:179], v[22:25]
	v_mfma_f32_16x16x32_bf16 v[18:21], v[224:227], v[176:179], v[18:21]
	v_mfma_f32_16x16x32_bf16 v[30:33], v[204:207], v[196:199], v[30:33]
	v_mfma_f32_16x16x32_bf16 v[26:29], v[224:227], v[196:199], v[26:29]
	v_mfma_f32_16x16x32_bf16 v[2:5], v[208:211], v[162:165], v[2:5]
	v_mfma_f32_16x16x32_bf16 v[6:9], v[228:231], v[162:165], v[6:9]
	v_mfma_f32_16x16x32_bf16 v[10:13], v[208:211], v[172:175], v[10:13]
	v_mfma_f32_16x16x32_bf16 v[14:17], v[228:231], v[172:175], v[14:17]
	v_mfma_f32_16x16x32_bf16 v[22:25], v[208:211], v[192:195], v[22:25]
	v_mfma_f32_16x16x32_bf16 v[18:21], v[228:231], v[192:195], v[18:21]
	v_mfma_f32_16x16x32_bf16 v[30:33], v[208:211], v[200:203], v[30:33]
	v_mfma_f32_16x16x32_bf16 v[26:29], v[228:231], v[200:203], v[26:29]
	s_barrier
	ds_read_b128 v[158:161], v140 offset:49152
	ds_read_b128 v[162:165], v140 offset:50176
	ds_read_b128 v[168:171], v140 offset:51200
	ds_read_b128 v[172:175], v140 offset:52224
	ds_read_b128 v[176:179], v140 offset:53248
	ds_read_b128 v[192:195], v140 offset:54272
	ds_read_b128 v[196:199], v140 offset:55296
	ds_read_b128 v[200:203], v140 offset:56320
	global_load_lds_dwordx4 v[212:213], off
	s_mov_b32 m0, s48
	v_lshl_add_u64 v[212:213], v[234:235], 0, s[78:79]
	global_load_lds_dwordx4 v[212:213], off
	s_waitcnt vmcnt(10)
	s_barrier
	s_waitcnt lgkmcnt(0)
	v_mfma_f32_16x16x32_bf16 v[110:113], v[142:145], v[158:161], v[110:113]
	v_mfma_f32_16x16x32_bf16 v[106:109], v[150:153], v[158:161], v[106:109]
	v_mfma_f32_16x16x32_bf16 v[90:93], v[142:145], v[168:171], v[90:93]
	v_mfma_f32_16x16x32_bf16 v[82:85], v[150:153], v[168:171], v[82:85]
	v_mfma_f32_16x16x32_bf16 v[78:81], v[142:145], v[176:179], v[78:81]
	v_mfma_f32_16x16x32_bf16 v[74:77], v[150:153], v[176:179], v[74:77]
	v_mfma_f32_16x16x32_bf16 v[70:73], v[142:145], v[196:199], v[70:73]
	v_mfma_f32_16x16x32_bf16 v[66:69], v[150:153], v[196:199], v[66:69]
	v_mfma_f32_16x16x32_bf16 v[110:113], v[146:149], v[162:165], v[110:113]
	v_mfma_f32_16x16x32_bf16 v[106:109], v[154:157], v[162:165], v[106:109]
	v_mfma_f32_16x16x32_bf16 v[90:93], v[146:149], v[172:175], v[90:93]
	v_mfma_f32_16x16x32_bf16 v[82:85], v[154:157], v[172:175], v[82:85]
	v_mfma_f32_16x16x32_bf16 v[78:81], v[146:149], v[192:195], v[78:81]
	v_mfma_f32_16x16x32_bf16 v[74:77], v[154:157], v[192:195], v[74:77]
	v_mfma_f32_16x16x32_bf16 v[70:73], v[146:149], v[200:203], v[70:73]
	v_mfma_f32_16x16x32_bf16 v[66:69], v[154:157], v[200:203], v[66:69]
	s_barrier
	s_add_u32 s22, s90, 0x200080
	s_addc_u32 s23, s91, 0
	s_add_i32 s56, s57, s81
	s_mov_b32 m0, s56
	v_lshl_add_u64 v[142:143], s[22:23], 0, v[134:135]
	global_load_lds_dwordx4 v[142:143], off
	s_add_i32 m0, s56, 0x2000
	v_lshl_add_u64 v[142:143], s[22:23], 0, v[130:131]
	global_load_lds_dwordx4 v[142:143], off
	v_add_u32_e32 v141, 0x10000, v139
	ds_read_b128 v[142:145], v141
	ds_read_b128 v[146:149], v141 offset:1024
	ds_read_b128 v[150:153], v141 offset:2048
	ds_read_b128 v[154:157], v141 offset:3072
	s_add_i32 s54, s54, 2
	s_add_i32 s55, s55, 0x10000
	s_cmpk_gt_u32 s54, 0x7d
	s_mov_b64 s[90:91], vcc
	s_waitcnt vmcnt(6)
	s_barrier
	v_mfma_f32_16x16x32_bf16 v[38:41], v[204:207], v[158:161], v[38:41]
	v_mfma_f32_16x16x32_bf16 v[34:37], v[224:227], v[158:161], v[34:37]
	v_mfma_f32_16x16x32_bf16 v[46:49], v[204:207], v[168:171], v[46:49]
	v_mfma_f32_16x16x32_bf16 v[42:45], v[224:227], v[168:171], v[42:45]
	v_mfma_f32_16x16x32_bf16 v[54:57], v[204:207], v[176:179], v[54:57]
	v_mfma_f32_16x16x32_bf16 v[50:53], v[224:227], v[176:179], v[50:53]
	v_mfma_f32_16x16x32_bf16 v[62:65], v[204:207], v[196:199], v[62:65]
	v_mfma_f32_16x16x32_bf16 v[58:61], v[224:227], v[196:199], v[58:61]
	v_mfma_f32_16x16x32_bf16 v[38:41], v[208:211], v[162:165], v[38:41]
	v_mfma_f32_16x16x32_bf16 v[34:37], v[228:231], v[162:165], v[34:37]
	v_mfma_f32_16x16x32_bf16 v[46:49], v[208:211], v[172:175], v[46:49]
	v_mfma_f32_16x16x32_bf16 v[42:45], v[228:231], v[172:175], v[42:45]
	v_mfma_f32_16x16x32_bf16 v[54:57], v[208:211], v[192:195], v[54:57]
	v_mfma_f32_16x16x32_bf16 v[50:53], v[228:231], v[192:195], v[50:53]
	v_mfma_f32_16x16x32_bf16 v[62:65], v[208:211], v[200:203], v[62:65]
	v_mfma_f32_16x16x32_bf16 v[58:61], v[228:231], v[200:203], v[58:61]
	s_barrier
	s_cbranch_scc0 .LBB0_814
	s_waitcnt lgkmcnt(0)
	s_andn2_b64 vcc, exec, s[38:39]
	s_cbranch_vccnz .LBB0_806
	v_mov_b32_e32 v58, 0
	s_mov_b32 s80, s42
	s_mov_b32 s25, s82
	s_mov_b64 s[30:31], s[20:21]
	s_mov_b64 s[84:85], s[18:19]
	s_mov_b32 s49, s50
	v_mov_b32_e32 v59, v58
	v_mov_b32_e32 v60, v58
	v_mov_b32_e32 v61, v58
	v_mov_b32_e32 v62, v58
	v_mov_b32_e32 v63, v58
	v_mov_b32_e32 v64, v58
	v_mov_b32_e32 v65, v58
	v_mov_b32_e32 v50, v58
	v_mov_b32_e32 v51, v58
	v_mov_b32_e32 v52, v58
	v_mov_b32_e32 v53, v58
	v_mov_b32_e32 v54, v58
	v_mov_b32_e32 v55, v58
	v_mov_b32_e32 v56, v58
	v_mov_b32_e32 v57, v58
	v_mov_b32_e32 v42, v58
	v_mov_b32_e32 v43, v58
	v_mov_b32_e32 v44, v58
	v_mov_b32_e32 v45, v58
	v_mov_b32_e32 v46, v58
	v_mov_b32_e32 v47, v58
	v_mov_b32_e32 v48, v58
	v_mov_b32_e32 v49, v58
	v_mov_b32_e32 v34, v58
	v_mov_b32_e32 v35, v58
	v_mov_b32_e32 v36, v58
	v_mov_b32_e32 v37, v58
	v_mov_b32_e32 v38, v58
	v_mov_b32_e32 v39, v58
	v_mov_b32_e32 v40, v58
	v_mov_b32_e32 v41, v58
	v_mov_b32_e32 v66, v58
	v_mov_b32_e32 v67, v58
	v_mov_b32_e32 v68, v58
	v_mov_b32_e32 v69, v58
	v_mov_b32_e32 v70, v58
	v_mov_b32_e32 v71, v58
	v_mov_b32_e32 v72, v58
	v_mov_b32_e32 v73, v58
	v_mov_b32_e32 v74, v58
	v_mov_b32_e32 v75, v58
	v_mov_b32_e32 v76, v58
	v_mov_b32_e32 v77, v58
	v_mov_b32_e32 v78, v58
	v_mov_b32_e32 v79, v58
	v_mov_b32_e32 v80, v58
	v_mov_b32_e32 v81, v58
	v_mov_b32_e32 v82, v58
	v_mov_b32_e32 v83, v58
	v_mov_b32_e32 v84, v58
	v_mov_b32_e32 v85, v58
	v_mov_b32_e32 v90, v58
	v_mov_b32_e32 v91, v58
	v_mov_b32_e32 v92, v58
	v_mov_b32_e32 v93, v58
	v_mov_b32_e32 v106, v58
	v_mov_b32_e32 v107, v58
	v_mov_b32_e32 v108, v58
	v_mov_b32_e32 v109, v58
	v_mov_b32_e32 v110, v58
	v_mov_b32_e32 v111, v58
	v_mov_b32_e32 v112, v58
	v_mov_b32_e32 v113, v58
	v_mov_b32_e32 v26, v58
	v_mov_b32_e32 v27, v58
	v_mov_b32_e32 v28, v58
	v_mov_b32_e32 v29, v58
	v_mov_b32_e32 v30, v58
	v_mov_b32_e32 v31, v58
	v_mov_b32_e32 v32, v58
	v_mov_b32_e32 v33, v58
	v_mov_b32_e32 v18, v58
	v_mov_b32_e32 v19, v58
	v_mov_b32_e32 v20, v58
	v_mov_b32_e32 v21, v58
	v_mov_b32_e32 v22, v58
	v_mov_b32_e32 v23, v58
	v_mov_b32_e32 v24, v58
	v_mov_b32_e32 v25, v58
	v_mov_b32_e32 v14, v58
	v_mov_b32_e32 v15, v58
	v_mov_b32_e32 v16, v58
	v_mov_b32_e32 v17, v58
	v_mov_b32_e32 v10, v58
	v_mov_b32_e32 v11, v58
	v_mov_b32_e32 v12, v58
	v_mov_b32_e32 v13, v58
	v_mov_b32_e32 v6, v58
	v_mov_b32_e32 v7, v58
	v_mov_b32_e32 v8, v58
	v_mov_b32_e32 v9, v58
	v_mov_b32_e32 v2, v58
	v_mov_b32_e32 v3, v58
	v_mov_b32_e32 v4, v58
	v_mov_b32_e32 v5, v58
	v_mov_b32_e32 v118, v58
	v_mov_b32_e32 v119, v58
	v_mov_b32_e32 v120, v58
	v_mov_b32_e32 v121, v58
	v_mov_b32_e32 v126, v58
	v_mov_b32_e32 v127, v58
	v_mov_b32_e32 v128, v58
	v_mov_b32_e32 v129, v58
	v_mov_b32_e32 v122, v58
	v_mov_b32_e32 v123, v58
	v_mov_b32_e32 v124, v58
	v_mov_b32_e32 v125, v58
	v_mov_b32_e32 v114, v58
	v_mov_b32_e32 v115, v58
	v_mov_b32_e32 v116, v58
	v_mov_b32_e32 v117, v58
	v_mov_b32_e32 v102, v58
	v_mov_b32_e32 v103, v58
	v_mov_b32_e32 v104, v58
	v_mov_b32_e32 v105, v58
	v_mov_b32_e32 v98, v58
	v_mov_b32_e32 v99, v58
	v_mov_b32_e32 v100, v58
	v_mov_b32_e32 v101, v58
	v_mov_b32_e32 v94, v58
	v_mov_b32_e32 v95, v58
	v_mov_b32_e32 v96, v58
	v_mov_b32_e32 v97, v58
	v_mov_b32_e32 v86, v58
	v_mov_b32_e32 v87, v58
	v_mov_b32_e32 v88, v58
	v_mov_b32_e32 v89, v58
	s_branch .LBB0_806
